# hand-written row-pair-packed f32 compute loops for RWKV-7 and HGRN2 scans (waves 0-3), staging unchanged
# speedup vs baseline: 1.0251x; 1.0251x over previous
.LBB0_1027:
	s_bfe_u32 s22, s34, 0x20004
	s_bfe_u32 s23, s34, 0x30001
	s_cmp_lt_u32 s34, 64
	s_cselect_b64 s[12:13], -1, 0
	s_cmp_gt_u32 s34, 63
	s_cselect_b64 s[18:19], -1, 0
	s_and_saveexec_b64 s[0:1], s[10:11]
	s_xor_b64 s[0:1], exec, s[0:1]
	s_cbranch_execz .LBB0_1033
	s_setprio 3
	s_lshr_b32 s14, s34, 6
	s_bfe_u32 s15, s34, 0x20004
	s_bfe_u32 s17, s34, 0x30001
	s_and_b32 s18, s34, 1
	s_add_u32 s22, s28, 0xdc00000
	s_addc_u32 s23, s29, 0
	s_cmp_eq_u32 s14, 0
	s_cselect_b32 s22, s22, s26
	s_cselect_b32 s23, s23, s27
	s_mov_b32 s52, 0x8000
	s_mov_b32 s53, 0
	s_mov_b32 s55, 1
	s_lshl_b32 s56, s15, 12
	s_cmp_eq_u32 s14, 0
	s_cbranch_scc1 .Lrc_fwd
	s_mov_b32 s52, 0xffff8000
	s_mov_b32 s53, -1
	s_mov_b32 s55, -1
	s_add_u32 s56, s56, 0xfff
.Lrc_fwd:
	s_lshl_b32 s57, s17, 6
	s_lshl_b32 s58, s18, 5
	s_add_u32 s57, s57, s58
	s_add_u32 s57, s57, 0x200
	s_lshl_b32 s59, s18, 7
	v_and_b32_e32 v106, 15, v164
	v_lshrrev_b32_e32 v107, 4, v164
	v_lshlrev_b32_e32 v100, 4, v106
	v_lshl_add_u32 v101, v107, 3, s59
	v_lshlrev_b32_e32 v102, 3, v164
	v_add_u32_e32 v102, 49152, v102
	v_lshlrev_b32_e32 v103, 7, v164
	v_add_u32_e32 v103, 49152, v103
	v_bfe_u32 v93, v164, 1, 3
	v_lshl_or_b32 v103, v93, 4, v103
	v_mul_lo_u32 v108, v107, s55
	v_add_u32_e32 v108, s56, v108
	v_lshlrev_b32_e32 v108, 11, v108
	v_lshl_add_u32 v109, v106, 1, s57
	v_lshl_add_u32 v108, v109, 1, v108
	v_mov_b32_e32 v109, 0
	v_lshl_add_u64 v[104:105], v[108:109], 0, s[22:23]
	v_mov_b32_e32 v0, 0
	v_mov_b32_e32 v1, 0
	v_mov_b32_e32 v2, 0
	v_mov_b32_e32 v3, 0
	v_mov_b32_e32 v4, 0
	v_mov_b32_e32 v5, 0
	v_mov_b32_e32 v6, 0
	v_mov_b32_e32 v7, 0
	s_mov_b32 s16, 0
	s_barrier
.Lrc_loop:
	ds_read_b128 v[8:11], v100 offset:0
	ds_read_b128 v[12:15], v100 offset:256
	ds_read_b128 v[16:19], v100 offset:512
	ds_read_b128 v[20:23], v100 offset:768
	ds_read_b128 v[24:27], v100 offset:1024
	ds_read_b64 v[28:29], v101 offset:1280
	ds_read_b128 v[32:35], v100 offset:1536
	ds_read_b128 v[36:39], v100 offset:1792
	ds_read_b128 v[40:43], v100 offset:2048
	ds_read_b128 v[44:47], v100 offset:2304
	ds_read_b128 v[48:51], v100 offset:2560
	ds_read_b64 v[52:53], v101 offset:2816
	ds_read_b128 v[56:59], v103 offset:32768
	v_xor_b32_e32 v93, 16, v103
	ds_read_b128 v[60:63], v93 offset:32768
	v_xor_b32_e32 v93, 32, v103
	ds_read_b128 v[64:67], v93 offset:32768
	v_xor_b32_e32 v93, 48, v103
	ds_read_b128 v[68:71], v93 offset:32768
	v_xor_b32_e32 v93, 64, v103
	ds_read_b128 v[72:75], v93 offset:32768
	v_xor_b32_e32 v93, 80, v103
	ds_read_b128 v[76:79], v93 offset:32768
	v_xor_b32_e32 v93, 96, v103
	ds_read_b128 v[80:83], v93 offset:32768
	v_xor_b32_e32 v93, 112, v103
	ds_read_b128 v[84:87], v93 offset:32768
	s_waitcnt lgkmcnt(0)
	v_pk_add_f32 v[56:57], v[56:57], v[58:59]
	v_pk_add_f32 v[60:61], v[60:61], v[62:63]
	v_pk_add_f32 v[64:65], v[64:65], v[66:67]
	v_pk_add_f32 v[68:69], v[68:69], v[70:71]
	v_pk_add_f32 v[72:73], v[72:73], v[74:75]
	v_pk_add_f32 v[76:77], v[76:77], v[78:79]
	v_pk_add_f32 v[80:81], v[80:81], v[82:83]
	v_pk_add_f32 v[84:85], v[84:85], v[86:87]
	v_pk_add_f32 v[56:57], v[56:57], v[60:61]
	v_pk_add_f32 v[64:65], v[64:65], v[68:69]
	v_pk_add_f32 v[72:73], v[72:73], v[76:77]
	v_pk_add_f32 v[80:81], v[80:81], v[84:85]
	v_pk_add_f32 v[56:57], v[56:57], v[64:65]
	v_pk_add_f32 v[72:73], v[72:73], v[80:81]
	s_nop 0
	v_pk_add_f32 v[56:57], v[56:57], v[72:73]
	s_nop 0
	v_cvt_pk_bf16_f32 v92, v56, v57
	s_cmp_eq_u32 s16, 0
	s_cselect_b64 s[46:47], 0, -1
	s_cselect_b64 s[50:51], 0, s[52:53]
	s_mov_b64 exec, s[46:47]
	global_store_dword v[104:105], v92, off
	s_mov_b64 exec, -1
	v_lshl_add_u64 v[104:105], v[104:105], 0, s[50:51]
	ds_read_b128 v[56:59], v100 offset:3072
	ds_read_b128 v[60:63], v100 offset:3328
	ds_read_b128 v[64:67], v100 offset:3584
	ds_read_b128 v[68:71], v100 offset:3840
	ds_read_b128 v[72:75], v100 offset:4096
	ds_read_b64 v[76:77], v101 offset:4352
	v_pk_mul_f32 v[80:81], v[20:21], v[0:1] op_sel:[0,0] op_sel_hi:[0,1]
	v_pk_mul_f32 v[82:83], v[20:21], v[2:3] op_sel:[1,0] op_sel_hi:[1,1]
	v_pk_fma_f32 v[80:81], v[22:23], v[4:5], v[80:81] op_sel:[0,0,0] op_sel_hi:[0,1,1]
	v_pk_fma_f32 v[82:83], v[22:23], v[6:7], v[82:83] op_sel:[1,0,0] op_sel_hi:[1,1,1]
	s_nop 0
	v_pk_add_f32 v[80:81], v[80:81], v[82:83]
	v_pk_mul_f32 v[0:1], v[12:13], v[0:1] op_sel:[0,0] op_sel_hi:[0,1]
	v_pk_mul_f32 v[2:3], v[12:13], v[2:3] op_sel:[1,0] op_sel_hi:[1,1]
	v_add_f32_dpp v80, v80, v80 quad_perm:[1,0,3,2] row_mask:0xf bank_mask:0xf
	v_add_f32_dpp v81, v81, v81 quad_perm:[1,0,3,2] row_mask:0xf bank_mask:0xf
	v_pk_mul_f32 v[4:5], v[14:15], v[4:5] op_sel:[0,0] op_sel_hi:[0,1]
	v_add_f32_dpp v80, v80, v80 quad_perm:[2,3,0,1] row_mask:0xf bank_mask:0xf
	v_add_f32_dpp v81, v81, v81 quad_perm:[2,3,0,1] row_mask:0xf bank_mask:0xf
	v_pk_mul_f32 v[6:7], v[14:15], v[6:7] op_sel:[1,0] op_sel_hi:[1,1]
	v_add_f32_dpp v80, v80, v80 row_half_mirror row_mask:0xf bank_mask:0xf
	v_add_f32_dpp v81, v81, v81 row_half_mirror row_mask:0xf bank_mask:0xf
	s_nop 0
	v_add_f32_dpp v80, v80, v80 row_mirror row_mask:0xf bank_mask:0xf
	v_add_f32_dpp v81, v81, v81 row_mirror row_mask:0xf bank_mask:0xf
	v_pk_fma_f32 v[0:1], v[80:81], v[24:25], v[0:1] op_sel:[0,0,0] op_sel_hi:[1,0,1] neg_lo:[1,0,0] neg_hi:[1,0,0]
	v_pk_fma_f32 v[2:3], v[80:81], v[24:25], v[2:3] op_sel:[0,1,0] op_sel_hi:[1,1,1] neg_lo:[1,0,0] neg_hi:[1,0,0]
	v_pk_fma_f32 v[4:5], v[80:81], v[26:27], v[4:5] op_sel:[0,0,0] op_sel_hi:[1,0,1] neg_lo:[1,0,0] neg_hi:[1,0,0]
	v_pk_fma_f32 v[6:7], v[80:81], v[26:27], v[6:7] op_sel:[0,1,0] op_sel_hi:[1,1,1] neg_lo:[1,0,0] neg_hi:[1,0,0]
	v_pk_fma_f32 v[0:1], v[28:29], v[16:17], v[0:1] op_sel:[0,0,0] op_sel_hi:[1,0,1]
	v_pk_fma_f32 v[2:3], v[28:29], v[16:17], v[2:3] op_sel:[0,1,0] op_sel_hi:[1,1,1]
	v_pk_fma_f32 v[4:5], v[28:29], v[18:19], v[4:5] op_sel:[0,0,0] op_sel_hi:[1,0,1]
	v_pk_fma_f32 v[6:7], v[28:29], v[18:19], v[6:7] op_sel:[0,1,0] op_sel_hi:[1,1,1]
	v_pk_mul_f32 v[84:85], v[8:9], v[0:1] op_sel:[0,0] op_sel_hi:[0,1]
	v_pk_mul_f32 v[86:87], v[8:9], v[2:3] op_sel:[1,0] op_sel_hi:[1,1]
	v_pk_fma_f32 v[84:85], v[10:11], v[4:5], v[84:85] op_sel:[0,0,0] op_sel_hi:[0,1,1]
	v_pk_fma_f32 v[86:87], v[10:11], v[6:7], v[86:87] op_sel:[1,0,0] op_sel_hi:[1,1,1]
	ds_read_b128 v[8:11], v100 offset:4608
	ds_read_b128 v[12:15], v100 offset:4864
	ds_read_b128 v[16:19], v100 offset:5120
	ds_read_b128 v[20:23], v100 offset:5376
	ds_read_b128 v[24:27], v100 offset:5632
	ds_read_b64 v[28:29], v101 offset:5888
	v_pk_mul_f32 v[80:81], v[44:45], v[0:1] op_sel:[0,0] op_sel_hi:[0,1]
	v_pk_mul_f32 v[82:83], v[44:45], v[2:3] op_sel:[1,0] op_sel_hi:[1,1]
	v_pk_fma_f32 v[80:81], v[46:47], v[4:5], v[80:81] op_sel:[0,0,0] op_sel_hi:[0,1,1]
	v_pk_fma_f32 v[82:83], v[46:47], v[6:7], v[82:83] op_sel:[1,0,0] op_sel_hi:[1,1,1]
	v_pk_add_f32 v[84:85], v[84:85], v[86:87]
	v_pk_add_f32 v[80:81], v[80:81], v[82:83]
	v_pk_mul_f32 v[0:1], v[36:37], v[0:1] op_sel:[0,0] op_sel_hi:[0,1]
	v_pk_mul_f32 v[2:3], v[36:37], v[2:3] op_sel:[1,0] op_sel_hi:[1,1]
	v_add_f32_dpp v80, v80, v80 quad_perm:[1,0,3,2] row_mask:0xf bank_mask:0xf
	v_add_f32_dpp v81, v81, v81 quad_perm:[1,0,3,2] row_mask:0xf bank_mask:0xf
	v_pk_mul_f32 v[4:5], v[38:39], v[4:5] op_sel:[0,0] op_sel_hi:[0,1]
	v_add_f32_dpp v80, v80, v80 quad_perm:[2,3,0,1] row_mask:0xf bank_mask:0xf
	v_add_f32_dpp v81, v81, v81 quad_perm:[2,3,0,1] row_mask:0xf bank_mask:0xf
	v_pk_mul_f32 v[6:7], v[38:39], v[6:7] op_sel:[1,0] op_sel_hi:[1,1]
	v_add_f32_dpp v80, v80, v80 row_half_mirror row_mask:0xf bank_mask:0xf
	v_add_f32_dpp v81, v81, v81 row_half_mirror row_mask:0xf bank_mask:0xf
	ds_write_b64 v102, v[84:85] offset:0
	v_add_f32_dpp v80, v80, v80 row_mirror row_mask:0xf bank_mask:0xf
	v_add_f32_dpp v81, v81, v81 row_mirror row_mask:0xf bank_mask:0xf
	v_pk_fma_f32 v[0:1], v[80:81], v[48:49], v[0:1] op_sel:[0,0,0] op_sel_hi:[1,0,1] neg_lo:[1,0,0] neg_hi:[1,0,0]
	v_pk_fma_f32 v[2:3], v[80:81], v[48:49], v[2:3] op_sel:[0,1,0] op_sel_hi:[1,1,1] neg_lo:[1,0,0] neg_hi:[1,0,0]
	v_pk_fma_f32 v[4:5], v[80:81], v[50:51], v[4:5] op_sel:[0,0,0] op_sel_hi:[1,0,1] neg_lo:[1,0,0] neg_hi:[1,0,0]
	v_pk_fma_f32 v[6:7], v[80:81], v[50:51], v[6:7] op_sel:[0,1,0] op_sel_hi:[1,1,1] neg_lo:[1,0,0] neg_hi:[1,0,0]
	v_pk_fma_f32 v[0:1], v[52:53], v[40:41], v[0:1] op_sel:[0,0,0] op_sel_hi:[1,0,1]
	v_pk_fma_f32 v[2:3], v[52:53], v[40:41], v[2:3] op_sel:[0,1,0] op_sel_hi:[1,1,1]
	v_pk_fma_f32 v[4:5], v[52:53], v[42:43], v[4:5] op_sel:[0,0,0] op_sel_hi:[1,0,1]
	v_pk_fma_f32 v[6:7], v[52:53], v[42:43], v[6:7] op_sel:[0,1,0] op_sel_hi:[1,1,1]
	v_pk_mul_f32 v[88:89], v[32:33], v[0:1] op_sel:[0,0] op_sel_hi:[0,1]
	v_pk_mul_f32 v[90:91], v[32:33], v[2:3] op_sel:[1,0] op_sel_hi:[1,1]
	v_pk_fma_f32 v[88:89], v[34:35], v[4:5], v[88:89] op_sel:[0,0,0] op_sel_hi:[0,1,1]
	v_pk_fma_f32 v[90:91], v[34:35], v[6:7], v[90:91] op_sel:[1,0,0] op_sel_hi:[1,1,1]
	ds_read_b128 v[32:35], v100 offset:6144
	ds_read_b128 v[36:39], v100 offset:6400
	ds_read_b128 v[40:43], v100 offset:6656
	ds_read_b128 v[44:47], v100 offset:6912
	ds_read_b128 v[48:51], v100 offset:7168
	ds_read_b64 v[52:53], v101 offset:7424
	s_waitcnt lgkmcnt(13)
	v_pk_mul_f32 v[80:81], v[68:69], v[0:1] op_sel:[0,0] op_sel_hi:[0,1]
	v_pk_mul_f32 v[82:83], v[68:69], v[2:3] op_sel:[1,0] op_sel_hi:[1,1]
	v_pk_fma_f32 v[80:81], v[70:71], v[4:5], v[80:81] op_sel:[0,0,0] op_sel_hi:[0,1,1]
	v_pk_fma_f32 v[82:83], v[70:71], v[6:7], v[82:83] op_sel:[1,0,0] op_sel_hi:[1,1,1]
	v_pk_add_f32 v[88:89], v[88:89], v[90:91]
	v_pk_add_f32 v[80:81], v[80:81], v[82:83]
	v_pk_mul_f32 v[0:1], v[60:61], v[0:1] op_sel:[0,0] op_sel_hi:[0,1]
	v_pk_mul_f32 v[2:3], v[60:61], v[2:3] op_sel:[1,0] op_sel_hi:[1,1]
	v_add_f32_dpp v80, v80, v80 quad_perm:[1,0,3,2] row_mask:0xf bank_mask:0xf
	v_add_f32_dpp v81, v81, v81 quad_perm:[1,0,3,2] row_mask:0xf bank_mask:0xf
	v_pk_mul_f32 v[4:5], v[62:63], v[4:5] op_sel:[0,0] op_sel_hi:[0,1]
	v_add_f32_dpp v80, v80, v80 quad_perm:[2,3,0,1] row_mask:0xf bank_mask:0xf
	v_add_f32_dpp v81, v81, v81 quad_perm:[2,3,0,1] row_mask:0xf bank_mask:0xf
	v_pk_mul_f32 v[6:7], v[62:63], v[6:7] op_sel:[1,0] op_sel_hi:[1,1]
	v_add_f32_dpp v80, v80, v80 row_half_mirror row_mask:0xf bank_mask:0xf
	v_add_f32_dpp v81, v81, v81 row_half_mirror row_mask:0xf bank_mask:0xf
	ds_write_b64 v102, v[88:89] offset:2048
	v_add_f32_dpp v80, v80, v80 row_mirror row_mask:0xf bank_mask:0xf
	v_add_f32_dpp v81, v81, v81 row_mirror row_mask:0xf bank_mask:0xf
	v_pk_fma_f32 v[0:1], v[80:81], v[72:73], v[0:1] op_sel:[0,0,0] op_sel_hi:[1,0,1] neg_lo:[1,0,0] neg_hi:[1,0,0]
	v_pk_fma_f32 v[2:3], v[80:81], v[72:73], v[2:3] op_sel:[0,1,0] op_sel_hi:[1,1,1] neg_lo:[1,0,0] neg_hi:[1,0,0]
	v_pk_fma_f32 v[4:5], v[80:81], v[74:75], v[4:5] op_sel:[0,0,0] op_sel_hi:[1,0,1] neg_lo:[1,0,0] neg_hi:[1,0,0]
	v_pk_fma_f32 v[6:7], v[80:81], v[74:75], v[6:7] op_sel:[0,1,0] op_sel_hi:[1,1,1] neg_lo:[1,0,0] neg_hi:[1,0,0]
	v_pk_fma_f32 v[0:1], v[76:77], v[64:65], v[0:1] op_sel:[0,0,0] op_sel_hi:[1,0,1]
	v_pk_fma_f32 v[2:3], v[76:77], v[64:65], v[2:3] op_sel:[0,1,0] op_sel_hi:[1,1,1]
	v_pk_fma_f32 v[4:5], v[76:77], v[66:67], v[4:5] op_sel:[0,0,0] op_sel_hi:[1,0,1]
	v_pk_fma_f32 v[6:7], v[76:77], v[66:67], v[6:7] op_sel:[0,1,0] op_sel_hi:[1,1,1]
	v_pk_mul_f32 v[84:85], v[56:57], v[0:1] op_sel:[0,0] op_sel_hi:[0,1]
	v_pk_mul_f32 v[86:87], v[56:57], v[2:3] op_sel:[1,0] op_sel_hi:[1,1]
	v_pk_fma_f32 v[84:85], v[58:59], v[4:5], v[84:85] op_sel:[0,0,0] op_sel_hi:[0,1,1]
	v_pk_fma_f32 v[86:87], v[58:59], v[6:7], v[86:87] op_sel:[1,0,0] op_sel_hi:[1,1,1]
	ds_read_b128 v[56:59], v100 offset:7680
	ds_read_b128 v[60:63], v100 offset:7936
	ds_read_b128 v[64:67], v100 offset:8192
	ds_read_b128 v[68:71], v100 offset:8448
	ds_read_b128 v[72:75], v100 offset:8704
	ds_read_b64 v[76:77], v101 offset:8960
	s_waitcnt lgkmcnt(14)
	v_pk_mul_f32 v[80:81], v[20:21], v[0:1] op_sel:[0,0] op_sel_hi:[0,1]
	v_pk_mul_f32 v[82:83], v[20:21], v[2:3] op_sel:[1,0] op_sel_hi:[1,1]
	v_pk_fma_f32 v[80:81], v[22:23], v[4:5], v[80:81] op_sel:[0,0,0] op_sel_hi:[0,1,1]
	v_pk_fma_f32 v[82:83], v[22:23], v[6:7], v[82:83] op_sel:[1,0,0] op_sel_hi:[1,1,1]
	v_pk_add_f32 v[84:85], v[84:85], v[86:87]
	v_pk_add_f32 v[80:81], v[80:81], v[82:83]
	v_pk_mul_f32 v[0:1], v[12:13], v[0:1] op_sel:[0,0] op_sel_hi:[0,1]
	v_pk_mul_f32 v[2:3], v[12:13], v[2:3] op_sel:[1,0] op_sel_hi:[1,1]
	v_add_f32_dpp v80, v80, v80 quad_perm:[1,0,3,2] row_mask:0xf bank_mask:0xf
	v_add_f32_dpp v81, v81, v81 quad_perm:[1,0,3,2] row_mask:0xf bank_mask:0xf
	v_pk_mul_f32 v[4:5], v[14:15], v[4:5] op_sel:[0,0] op_sel_hi:[0,1]
	v_add_f32_dpp v80, v80, v80 quad_perm:[2,3,0,1] row_mask:0xf bank_mask:0xf
	v_add_f32_dpp v81, v81, v81 quad_perm:[2,3,0,1] row_mask:0xf bank_mask:0xf
	v_pk_mul_f32 v[6:7], v[14:15], v[6:7] op_sel:[1,0] op_sel_hi:[1,1]
	v_add_f32_dpp v80, v80, v80 row_half_mirror row_mask:0xf bank_mask:0xf
	v_add_f32_dpp v81, v81, v81 row_half_mirror row_mask:0xf bank_mask:0xf
	ds_write_b64 v102, v[84:85] offset:4096
	v_add_f32_dpp v80, v80, v80 row_mirror row_mask:0xf bank_mask:0xf
	v_add_f32_dpp v81, v81, v81 row_mirror row_mask:0xf bank_mask:0xf
	v_pk_fma_f32 v[0:1], v[80:81], v[24:25], v[0:1] op_sel:[0,0,0] op_sel_hi:[1,0,1] neg_lo:[1,0,0] neg_hi:[1,0,0]
	v_pk_fma_f32 v[2:3], v[80:81], v[24:25], v[2:3] op_sel:[0,1,0] op_sel_hi:[1,1,1] neg_lo:[1,0,0] neg_hi:[1,0,0]
	v_pk_fma_f32 v[4:5], v[80:81], v[26:27], v[4:5] op_sel:[0,0,0] op_sel_hi:[1,0,1] neg_lo:[1,0,0] neg_hi:[1,0,0]
	v_pk_fma_f32 v[6:7], v[80:81], v[26:27], v[6:7] op_sel:[0,1,0] op_sel_hi:[1,1,1] neg_lo:[1,0,0] neg_hi:[1,0,0]
	v_pk_fma_f32 v[0:1], v[28:29], v[16:17], v[0:1] op_sel:[0,0,0] op_sel_hi:[1,0,1]
	v_pk_fma_f32 v[2:3], v[28:29], v[16:17], v[2:3] op_sel:[0,1,0] op_sel_hi:[1,1,1]
	v_pk_fma_f32 v[4:5], v[28:29], v[18:19], v[4:5] op_sel:[0,0,0] op_sel_hi:[1,0,1]
	v_pk_fma_f32 v[6:7], v[28:29], v[18:19], v[6:7] op_sel:[0,1,0] op_sel_hi:[1,1,1]
	v_pk_mul_f32 v[88:89], v[8:9], v[0:1] op_sel:[0,0] op_sel_hi:[0,1]
	v_pk_mul_f32 v[90:91], v[8:9], v[2:3] op_sel:[1,0] op_sel_hi:[1,1]
	v_pk_fma_f32 v[88:89], v[10:11], v[4:5], v[88:89] op_sel:[0,0,0] op_sel_hi:[0,1,1]
	v_pk_fma_f32 v[90:91], v[10:11], v[6:7], v[90:91] op_sel:[1,0,0] op_sel_hi:[1,1,1]
	ds_read_b128 v[8:11], v100 offset:9216
	ds_read_b128 v[12:15], v100 offset:9472
	ds_read_b128 v[16:19], v100 offset:9728
	ds_read_b128 v[20:23], v100 offset:9984
	ds_read_b128 v[24:27], v100 offset:10240
	ds_read_b64 v[28:29], v101 offset:10496
	s_waitcnt lgkmcnt(14)
	v_pk_mul_f32 v[80:81], v[44:45], v[0:1] op_sel:[0,0] op_sel_hi:[0,1]
	v_pk_mul_f32 v[82:83], v[44:45], v[2:3] op_sel:[1,0] op_sel_hi:[1,1]
	v_pk_fma_f32 v[80:81], v[46:47], v[4:5], v[80:81] op_sel:[0,0,0] op_sel_hi:[0,1,1]
	v_pk_fma_f32 v[82:83], v[46:47], v[6:7], v[82:83] op_sel:[1,0,0] op_sel_hi:[1,1,1]
	v_pk_add_f32 v[88:89], v[88:89], v[90:91]
	v_pk_add_f32 v[80:81], v[80:81], v[82:83]
	v_pk_mul_f32 v[0:1], v[36:37], v[0:1] op_sel:[0,0] op_sel_hi:[0,1]
	v_pk_mul_f32 v[2:3], v[36:37], v[2:3] op_sel:[1,0] op_sel_hi:[1,1]
	v_add_f32_dpp v80, v80, v80 quad_perm:[1,0,3,2] row_mask:0xf bank_mask:0xf
	v_add_f32_dpp v81, v81, v81 quad_perm:[1,0,3,2] row_mask:0xf bank_mask:0xf
	v_pk_mul_f32 v[4:5], v[38:39], v[4:5] op_sel:[0,0] op_sel_hi:[0,1]
	v_add_f32_dpp v80, v80, v80 quad_perm:[2,3,0,1] row_mask:0xf bank_mask:0xf
	v_add_f32_dpp v81, v81, v81 quad_perm:[2,3,0,1] row_mask:0xf bank_mask:0xf
	v_pk_mul_f32 v[6:7], v[38:39], v[6:7] op_sel:[1,0] op_sel_hi:[1,1]
	v_add_f32_dpp v80, v80, v80 row_half_mirror row_mask:0xf bank_mask:0xf
	v_add_f32_dpp v81, v81, v81 row_half_mirror row_mask:0xf bank_mask:0xf
	ds_write_b64 v102, v[88:89] offset:6144
	v_add_f32_dpp v80, v80, v80 row_mirror row_mask:0xf bank_mask:0xf
	v_add_f32_dpp v81, v81, v81 row_mirror row_mask:0xf bank_mask:0xf
	v_pk_fma_f32 v[0:1], v[80:81], v[48:49], v[0:1] op_sel:[0,0,0] op_sel_hi:[1,0,1] neg_lo:[1,0,0] neg_hi:[1,0,0]
	v_pk_fma_f32 v[2:3], v[80:81], v[48:49], v[2:3] op_sel:[0,1,0] op_sel_hi:[1,1,1] neg_lo:[1,0,0] neg_hi:[1,0,0]
	v_pk_fma_f32 v[4:5], v[80:81], v[50:51], v[4:5] op_sel:[0,0,0] op_sel_hi:[1,0,1] neg_lo:[1,0,0] neg_hi:[1,0,0]
	v_pk_fma_f32 v[6:7], v[80:81], v[50:51], v[6:7] op_sel:[0,1,0] op_sel_hi:[1,1,1] neg_lo:[1,0,0] neg_hi:[1,0,0]
	v_pk_fma_f32 v[0:1], v[52:53], v[40:41], v[0:1] op_sel:[0,0,0] op_sel_hi:[1,0,1]
	v_pk_fma_f32 v[2:3], v[52:53], v[40:41], v[2:3] op_sel:[0,1,0] op_sel_hi:[1,1,1]
	v_pk_fma_f32 v[4:5], v[52:53], v[42:43], v[4:5] op_sel:[0,0,0] op_sel_hi:[1,0,1]
	v_pk_fma_f32 v[6:7], v[52:53], v[42:43], v[6:7] op_sel:[0,1,0] op_sel_hi:[1,1,1]
	v_pk_mul_f32 v[84:85], v[32:33], v[0:1] op_sel:[0,0] op_sel_hi:[0,1]
	v_pk_mul_f32 v[86:87], v[32:33], v[2:3] op_sel:[1,0] op_sel_hi:[1,1]
	v_pk_fma_f32 v[84:85], v[34:35], v[4:5], v[84:85] op_sel:[0,0,0] op_sel_hi:[0,1,1]
	v_pk_fma_f32 v[86:87], v[34:35], v[6:7], v[86:87] op_sel:[1,0,0] op_sel_hi:[1,1,1]
	ds_read_b128 v[32:35], v100 offset:10752
	ds_read_b128 v[36:39], v100 offset:11008
	ds_read_b128 v[40:43], v100 offset:11264
	ds_read_b128 v[44:47], v100 offset:11520
	ds_read_b128 v[48:51], v100 offset:11776
	ds_read_b64 v[52:53], v101 offset:12032
	s_waitcnt lgkmcnt(14)
	v_pk_mul_f32 v[80:81], v[68:69], v[0:1] op_sel:[0,0] op_sel_hi:[0,1]
	v_pk_mul_f32 v[82:83], v[68:69], v[2:3] op_sel:[1,0] op_sel_hi:[1,1]
	v_pk_fma_f32 v[80:81], v[70:71], v[4:5], v[80:81] op_sel:[0,0,0] op_sel_hi:[0,1,1]
	v_pk_fma_f32 v[82:83], v[70:71], v[6:7], v[82:83] op_sel:[1,0,0] op_sel_hi:[1,1,1]
	v_pk_add_f32 v[84:85], v[84:85], v[86:87]
	v_pk_add_f32 v[80:81], v[80:81], v[82:83]
	v_pk_mul_f32 v[0:1], v[60:61], v[0:1] op_sel:[0,0] op_sel_hi:[0,1]
	v_pk_mul_f32 v[2:3], v[60:61], v[2:3] op_sel:[1,0] op_sel_hi:[1,1]
	v_add_f32_dpp v80, v80, v80 quad_perm:[1,0,3,2] row_mask:0xf bank_mask:0xf
	v_add_f32_dpp v81, v81, v81 quad_perm:[1,0,3,2] row_mask:0xf bank_mask:0xf
	v_pk_mul_f32 v[4:5], v[62:63], v[4:5] op_sel:[0,0] op_sel_hi:[0,1]
	v_add_f32_dpp v80, v80, v80 quad_perm:[2,3,0,1] row_mask:0xf bank_mask:0xf
	v_add_f32_dpp v81, v81, v81 quad_perm:[2,3,0,1] row_mask:0xf bank_mask:0xf
	v_pk_mul_f32 v[6:7], v[62:63], v[6:7] op_sel:[1,0] op_sel_hi:[1,1]
	v_add_f32_dpp v80, v80, v80 row_half_mirror row_mask:0xf bank_mask:0xf
	v_add_f32_dpp v81, v81, v81 row_half_mirror row_mask:0xf bank_mask:0xf
	ds_write_b64 v102, v[84:85] offset:8192
	v_add_f32_dpp v80, v80, v80 row_mirror row_mask:0xf bank_mask:0xf
	v_add_f32_dpp v81, v81, v81 row_mirror row_mask:0xf bank_mask:0xf
	v_pk_fma_f32 v[0:1], v[80:81], v[72:73], v[0:1] op_sel:[0,0,0] op_sel_hi:[1,0,1] neg_lo:[1,0,0] neg_hi:[1,0,0]
	v_pk_fma_f32 v[2:3], v[80:81], v[72:73], v[2:3] op_sel:[0,1,0] op_sel_hi:[1,1,1] neg_lo:[1,0,0] neg_hi:[1,0,0]
	v_pk_fma_f32 v[4:5], v[80:81], v[74:75], v[4:5] op_sel:[0,0,0] op_sel_hi:[1,0,1] neg_lo:[1,0,0] neg_hi:[1,0,0]
	v_pk_fma_f32 v[6:7], v[80:81], v[74:75], v[6:7] op_sel:[0,1,0] op_sel_hi:[1,1,1] neg_lo:[1,0,0] neg_hi:[1,0,0]
	v_pk_fma_f32 v[0:1], v[76:77], v[64:65], v[0:1] op_sel:[0,0,0] op_sel_hi:[1,0,1]
	v_pk_fma_f32 v[2:3], v[76:77], v[64:65], v[2:3] op_sel:[0,1,0] op_sel_hi:[1,1,1]
	v_pk_fma_f32 v[4:5], v[76:77], v[66:67], v[4:5] op_sel:[0,0,0] op_sel_hi:[1,0,1]
	v_pk_fma_f32 v[6:7], v[76:77], v[66:67], v[6:7] op_sel:[0,1,0] op_sel_hi:[1,1,1]
	v_pk_mul_f32 v[88:89], v[56:57], v[0:1] op_sel:[0,0] op_sel_hi:[0,1]
	v_pk_mul_f32 v[90:91], v[56:57], v[2:3] op_sel:[1,0] op_sel_hi:[1,1]
	v_pk_fma_f32 v[88:89], v[58:59], v[4:5], v[88:89] op_sel:[0,0,0] op_sel_hi:[0,1,1]
	v_pk_fma_f32 v[90:91], v[58:59], v[6:7], v[90:91] op_sel:[1,0,0] op_sel_hi:[1,1,1]
	ds_read_b128 v[56:59], v100 offset:12288
	ds_read_b128 v[60:63], v100 offset:12544
	ds_read_b128 v[64:67], v100 offset:12800
	ds_read_b128 v[68:71], v100 offset:13056
	ds_read_b128 v[72:75], v100 offset:13312
	ds_read_b64 v[76:77], v101 offset:13568
	s_waitcnt lgkmcnt(14)
	v_pk_mul_f32 v[80:81], v[20:21], v[0:1] op_sel:[0,0] op_sel_hi:[0,1]
	v_pk_mul_f32 v[82:83], v[20:21], v[2:3] op_sel:[1,0] op_sel_hi:[1,1]
	v_pk_fma_f32 v[80:81], v[22:23], v[4:5], v[80:81] op_sel:[0,0,0] op_sel_hi:[0,1,1]
	v_pk_fma_f32 v[82:83], v[22:23], v[6:7], v[82:83] op_sel:[1,0,0] op_sel_hi:[1,1,1]
	v_pk_add_f32 v[88:89], v[88:89], v[90:91]
	v_pk_add_f32 v[80:81], v[80:81], v[82:83]
	v_pk_mul_f32 v[0:1], v[12:13], v[0:1] op_sel:[0,0] op_sel_hi:[0,1]
	v_pk_mul_f32 v[2:3], v[12:13], v[2:3] op_sel:[1,0] op_sel_hi:[1,1]
	v_add_f32_dpp v80, v80, v80 quad_perm:[1,0,3,2] row_mask:0xf bank_mask:0xf
	v_add_f32_dpp v81, v81, v81 quad_perm:[1,0,3,2] row_mask:0xf bank_mask:0xf
	v_pk_mul_f32 v[4:5], v[14:15], v[4:5] op_sel:[0,0] op_sel_hi:[0,1]
	v_add_f32_dpp v80, v80, v80 quad_perm:[2,3,0,1] row_mask:0xf bank_mask:0xf
	v_add_f32_dpp v81, v81, v81 quad_perm:[2,3,0,1] row_mask:0xf bank_mask:0xf
	v_pk_mul_f32 v[6:7], v[14:15], v[6:7] op_sel:[1,0] op_sel_hi:[1,1]
	v_add_f32_dpp v80, v80, v80 row_half_mirror row_mask:0xf bank_mask:0xf
	v_add_f32_dpp v81, v81, v81 row_half_mirror row_mask:0xf bank_mask:0xf
	ds_write_b64 v102, v[88:89] offset:10240
	v_add_f32_dpp v80, v80, v80 row_mirror row_mask:0xf bank_mask:0xf
	v_add_f32_dpp v81, v81, v81 row_mirror row_mask:0xf bank_mask:0xf
	v_pk_fma_f32 v[0:1], v[80:81], v[24:25], v[0:1] op_sel:[0,0,0] op_sel_hi:[1,0,1] neg_lo:[1,0,0] neg_hi:[1,0,0]
	v_pk_fma_f32 v[2:3], v[80:81], v[24:25], v[2:3] op_sel:[0,1,0] op_sel_hi:[1,1,1] neg_lo:[1,0,0] neg_hi:[1,0,0]
	v_pk_fma_f32 v[4:5], v[80:81], v[26:27], v[4:5] op_sel:[0,0,0] op_sel_hi:[1,0,1] neg_lo:[1,0,0] neg_hi:[1,0,0]
	v_pk_fma_f32 v[6:7], v[80:81], v[26:27], v[6:7] op_sel:[0,1,0] op_sel_hi:[1,1,1] neg_lo:[1,0,0] neg_hi:[1,0,0]
	v_pk_fma_f32 v[0:1], v[28:29], v[16:17], v[0:1] op_sel:[0,0,0] op_sel_hi:[1,0,1]
	v_pk_fma_f32 v[2:3], v[28:29], v[16:17], v[2:3] op_sel:[0,1,0] op_sel_hi:[1,1,1]
	v_pk_fma_f32 v[4:5], v[28:29], v[18:19], v[4:5] op_sel:[0,0,0] op_sel_hi:[1,0,1]
	v_pk_fma_f32 v[6:7], v[28:29], v[18:19], v[6:7] op_sel:[0,1,0] op_sel_hi:[1,1,1]
	v_pk_mul_f32 v[84:85], v[8:9], v[0:1] op_sel:[0,0] op_sel_hi:[0,1]
	v_pk_mul_f32 v[86:87], v[8:9], v[2:3] op_sel:[1,0] op_sel_hi:[1,1]
	v_pk_fma_f32 v[84:85], v[10:11], v[4:5], v[84:85] op_sel:[0,0,0] op_sel_hi:[0,1,1]
	v_pk_fma_f32 v[86:87], v[10:11], v[6:7], v[86:87] op_sel:[1,0,0] op_sel_hi:[1,1,1]
	ds_read_b128 v[8:11], v100 offset:13824
	ds_read_b128 v[12:15], v100 offset:14080
	ds_read_b128 v[16:19], v100 offset:14336
	ds_read_b128 v[20:23], v100 offset:14592
	ds_read_b128 v[24:27], v100 offset:14848
	ds_read_b64 v[28:29], v101 offset:15104
	s_waitcnt lgkmcnt(14)
	v_pk_mul_f32 v[80:81], v[44:45], v[0:1] op_sel:[0,0] op_sel_hi:[0,1]
	v_pk_mul_f32 v[82:83], v[44:45], v[2:3] op_sel:[1,0] op_sel_hi:[1,1]
	v_pk_fma_f32 v[80:81], v[46:47], v[4:5], v[80:81] op_sel:[0,0,0] op_sel_hi:[0,1,1]
	v_pk_fma_f32 v[82:83], v[46:47], v[6:7], v[82:83] op_sel:[1,0,0] op_sel_hi:[1,1,1]
	v_pk_add_f32 v[84:85], v[84:85], v[86:87]
	v_pk_add_f32 v[80:81], v[80:81], v[82:83]
	v_pk_mul_f32 v[0:1], v[36:37], v[0:1] op_sel:[0,0] op_sel_hi:[0,1]
	v_pk_mul_f32 v[2:3], v[36:37], v[2:3] op_sel:[1,0] op_sel_hi:[1,1]
	v_add_f32_dpp v80, v80, v80 quad_perm:[1,0,3,2] row_mask:0xf bank_mask:0xf
	v_add_f32_dpp v81, v81, v81 quad_perm:[1,0,3,2] row_mask:0xf bank_mask:0xf
	v_pk_mul_f32 v[4:5], v[38:39], v[4:5] op_sel:[0,0] op_sel_hi:[0,1]
	v_add_f32_dpp v80, v80, v80 quad_perm:[2,3,0,1] row_mask:0xf bank_mask:0xf
	v_add_f32_dpp v81, v81, v81 quad_perm:[2,3,0,1] row_mask:0xf bank_mask:0xf
	v_pk_mul_f32 v[6:7], v[38:39], v[6:7] op_sel:[1,0] op_sel_hi:[1,1]
	v_add_f32_dpp v80, v80, v80 row_half_mirror row_mask:0xf bank_mask:0xf
	v_add_f32_dpp v81, v81, v81 row_half_mirror row_mask:0xf bank_mask:0xf
	ds_write_b64 v102, v[84:85] offset:12288
	v_add_f32_dpp v80, v80, v80 row_mirror row_mask:0xf bank_mask:0xf
	v_add_f32_dpp v81, v81, v81 row_mirror row_mask:0xf bank_mask:0xf
	v_pk_fma_f32 v[0:1], v[80:81], v[48:49], v[0:1] op_sel:[0,0,0] op_sel_hi:[1,0,1] neg_lo:[1,0,0] neg_hi:[1,0,0]
	v_pk_fma_f32 v[2:3], v[80:81], v[48:49], v[2:3] op_sel:[0,1,0] op_sel_hi:[1,1,1] neg_lo:[1,0,0] neg_hi:[1,0,0]
	v_pk_fma_f32 v[4:5], v[80:81], v[50:51], v[4:5] op_sel:[0,0,0] op_sel_hi:[1,0,1] neg_lo:[1,0,0] neg_hi:[1,0,0]
	v_pk_fma_f32 v[6:7], v[80:81], v[50:51], v[6:7] op_sel:[0,1,0] op_sel_hi:[1,1,1] neg_lo:[1,0,0] neg_hi:[1,0,0]
	v_pk_fma_f32 v[0:1], v[52:53], v[40:41], v[0:1] op_sel:[0,0,0] op_sel_hi:[1,0,1]
	v_pk_fma_f32 v[2:3], v[52:53], v[40:41], v[2:3] op_sel:[0,1,0] op_sel_hi:[1,1,1]
	v_pk_fma_f32 v[4:5], v[52:53], v[42:43], v[4:5] op_sel:[0,0,0] op_sel_hi:[1,0,1]
	v_pk_fma_f32 v[6:7], v[52:53], v[42:43], v[6:7] op_sel:[0,1,0] op_sel_hi:[1,1,1]
	v_pk_mul_f32 v[88:89], v[32:33], v[0:1] op_sel:[0,0] op_sel_hi:[0,1]
	v_pk_mul_f32 v[90:91], v[32:33], v[2:3] op_sel:[1,0] op_sel_hi:[1,1]
	v_pk_fma_f32 v[88:89], v[34:35], v[4:5], v[88:89] op_sel:[0,0,0] op_sel_hi:[0,1,1]
	v_pk_fma_f32 v[90:91], v[34:35], v[6:7], v[90:91] op_sel:[1,0,0] op_sel_hi:[1,1,1]
	ds_read_b128 v[32:35], v100 offset:15360
	ds_read_b128 v[36:39], v100 offset:15616
	ds_read_b128 v[40:43], v100 offset:15872
	ds_read_b128 v[44:47], v100 offset:16128
	ds_read_b128 v[48:51], v100 offset:16384
	ds_read_b64 v[52:53], v101 offset:16640
	s_waitcnt lgkmcnt(14)
	v_pk_mul_f32 v[80:81], v[68:69], v[0:1] op_sel:[0,0] op_sel_hi:[0,1]
	v_pk_mul_f32 v[82:83], v[68:69], v[2:3] op_sel:[1,0] op_sel_hi:[1,1]
	v_pk_fma_f32 v[80:81], v[70:71], v[4:5], v[80:81] op_sel:[0,0,0] op_sel_hi:[0,1,1]
	v_pk_fma_f32 v[82:83], v[70:71], v[6:7], v[82:83] op_sel:[1,0,0] op_sel_hi:[1,1,1]
	v_pk_add_f32 v[88:89], v[88:89], v[90:91]
	v_pk_add_f32 v[80:81], v[80:81], v[82:83]
	v_pk_mul_f32 v[0:1], v[60:61], v[0:1] op_sel:[0,0] op_sel_hi:[0,1]
	v_pk_mul_f32 v[2:3], v[60:61], v[2:3] op_sel:[1,0] op_sel_hi:[1,1]
	v_add_f32_dpp v80, v80, v80 quad_perm:[1,0,3,2] row_mask:0xf bank_mask:0xf
	v_add_f32_dpp v81, v81, v81 quad_perm:[1,0,3,2] row_mask:0xf bank_mask:0xf
	v_pk_mul_f32 v[4:5], v[62:63], v[4:5] op_sel:[0,0] op_sel_hi:[0,1]
	v_add_f32_dpp v80, v80, v80 quad_perm:[2,3,0,1] row_mask:0xf bank_mask:0xf
	v_add_f32_dpp v81, v81, v81 quad_perm:[2,3,0,1] row_mask:0xf bank_mask:0xf
	v_pk_mul_f32 v[6:7], v[62:63], v[6:7] op_sel:[1,0] op_sel_hi:[1,1]
	v_add_f32_dpp v80, v80, v80 row_half_mirror row_mask:0xf bank_mask:0xf
	v_add_f32_dpp v81, v81, v81 row_half_mirror row_mask:0xf bank_mask:0xf
	ds_write_b64 v102, v[88:89] offset:14336
	v_add_f32_dpp v80, v80, v80 row_mirror row_mask:0xf bank_mask:0xf
	v_add_f32_dpp v81, v81, v81 row_mirror row_mask:0xf bank_mask:0xf
	v_pk_fma_f32 v[0:1], v[80:81], v[72:73], v[0:1] op_sel:[0,0,0] op_sel_hi:[1,0,1] neg_lo:[1,0,0] neg_hi:[1,0,0]
	v_pk_fma_f32 v[2:3], v[80:81], v[72:73], v[2:3] op_sel:[0,1,0] op_sel_hi:[1,1,1] neg_lo:[1,0,0] neg_hi:[1,0,0]
	v_pk_fma_f32 v[4:5], v[80:81], v[74:75], v[4:5] op_sel:[0,0,0] op_sel_hi:[1,0,1] neg_lo:[1,0,0] neg_hi:[1,0,0]
	v_pk_fma_f32 v[6:7], v[80:81], v[74:75], v[6:7] op_sel:[0,1,0] op_sel_hi:[1,1,1] neg_lo:[1,0,0] neg_hi:[1,0,0]
	v_pk_fma_f32 v[0:1], v[76:77], v[64:65], v[0:1] op_sel:[0,0,0] op_sel_hi:[1,0,1]
	v_pk_fma_f32 v[2:3], v[76:77], v[64:65], v[2:3] op_sel:[0,1,0] op_sel_hi:[1,1,1]
	v_pk_fma_f32 v[4:5], v[76:77], v[66:67], v[4:5] op_sel:[0,0,0] op_sel_hi:[1,0,1]
	v_pk_fma_f32 v[6:7], v[76:77], v[66:67], v[6:7] op_sel:[0,1,0] op_sel_hi:[1,1,1]
	v_pk_mul_f32 v[84:85], v[56:57], v[0:1] op_sel:[0,0] op_sel_hi:[0,1]
	v_pk_mul_f32 v[86:87], v[56:57], v[2:3] op_sel:[1,0] op_sel_hi:[1,1]
	v_pk_fma_f32 v[84:85], v[58:59], v[4:5], v[84:85] op_sel:[0,0,0] op_sel_hi:[0,1,1]
	v_pk_fma_f32 v[86:87], v[58:59], v[6:7], v[86:87] op_sel:[1,0,0] op_sel_hi:[1,1,1]
	ds_read_b128 v[56:59], v100 offset:16896
	ds_read_b128 v[60:63], v100 offset:17152
	ds_read_b128 v[64:67], v100 offset:17408
	ds_read_b128 v[68:71], v100 offset:17664
	ds_read_b128 v[72:75], v100 offset:17920
	ds_read_b64 v[76:77], v101 offset:18176
	s_waitcnt lgkmcnt(14)
	v_pk_mul_f32 v[80:81], v[20:21], v[0:1] op_sel:[0,0] op_sel_hi:[0,1]
	v_pk_mul_f32 v[82:83], v[20:21], v[2:3] op_sel:[1,0] op_sel_hi:[1,1]
	v_pk_fma_f32 v[80:81], v[22:23], v[4:5], v[80:81] op_sel:[0,0,0] op_sel_hi:[0,1,1]
	v_pk_fma_f32 v[82:83], v[22:23], v[6:7], v[82:83] op_sel:[1,0,0] op_sel_hi:[1,1,1]
	v_pk_add_f32 v[84:85], v[84:85], v[86:87]
	v_pk_add_f32 v[80:81], v[80:81], v[82:83]
	v_pk_mul_f32 v[0:1], v[12:13], v[0:1] op_sel:[0,0] op_sel_hi:[0,1]
	v_pk_mul_f32 v[2:3], v[12:13], v[2:3] op_sel:[1,0] op_sel_hi:[1,1]
	v_add_f32_dpp v80, v80, v80 quad_perm:[1,0,3,2] row_mask:0xf bank_mask:0xf
	v_add_f32_dpp v81, v81, v81 quad_perm:[1,0,3,2] row_mask:0xf bank_mask:0xf
	v_pk_mul_f32 v[4:5], v[14:15], v[4:5] op_sel:[0,0] op_sel_hi:[0,1]
	v_add_f32_dpp v80, v80, v80 quad_perm:[2,3,0,1] row_mask:0xf bank_mask:0xf
	v_add_f32_dpp v81, v81, v81 quad_perm:[2,3,0,1] row_mask:0xf bank_mask:0xf
	v_pk_mul_f32 v[6:7], v[14:15], v[6:7] op_sel:[1,0] op_sel_hi:[1,1]
	v_add_f32_dpp v80, v80, v80 row_half_mirror row_mask:0xf bank_mask:0xf
	v_add_f32_dpp v81, v81, v81 row_half_mirror row_mask:0xf bank_mask:0xf
	ds_write_b64 v102, v[84:85] offset:16384
	v_add_f32_dpp v80, v80, v80 row_mirror row_mask:0xf bank_mask:0xf
	v_add_f32_dpp v81, v81, v81 row_mirror row_mask:0xf bank_mask:0xf
	v_pk_fma_f32 v[0:1], v[80:81], v[24:25], v[0:1] op_sel:[0,0,0] op_sel_hi:[1,0,1] neg_lo:[1,0,0] neg_hi:[1,0,0]
	v_pk_fma_f32 v[2:3], v[80:81], v[24:25], v[2:3] op_sel:[0,1,0] op_sel_hi:[1,1,1] neg_lo:[1,0,0] neg_hi:[1,0,0]
	v_pk_fma_f32 v[4:5], v[80:81], v[26:27], v[4:5] op_sel:[0,0,0] op_sel_hi:[1,0,1] neg_lo:[1,0,0] neg_hi:[1,0,0]
	v_pk_fma_f32 v[6:7], v[80:81], v[26:27], v[6:7] op_sel:[0,1,0] op_sel_hi:[1,1,1] neg_lo:[1,0,0] neg_hi:[1,0,0]
	v_pk_fma_f32 v[0:1], v[28:29], v[16:17], v[0:1] op_sel:[0,0,0] op_sel_hi:[1,0,1]
	v_pk_fma_f32 v[2:3], v[28:29], v[16:17], v[2:3] op_sel:[0,1,0] op_sel_hi:[1,1,1]
	v_pk_fma_f32 v[4:5], v[28:29], v[18:19], v[4:5] op_sel:[0,0,0] op_sel_hi:[1,0,1]
	v_pk_fma_f32 v[6:7], v[28:29], v[18:19], v[6:7] op_sel:[0,1,0] op_sel_hi:[1,1,1]
	v_pk_mul_f32 v[88:89], v[8:9], v[0:1] op_sel:[0,0] op_sel_hi:[0,1]
	v_pk_mul_f32 v[90:91], v[8:9], v[2:3] op_sel:[1,0] op_sel_hi:[1,1]
	v_pk_fma_f32 v[88:89], v[10:11], v[4:5], v[88:89] op_sel:[0,0,0] op_sel_hi:[0,1,1]
	v_pk_fma_f32 v[90:91], v[10:11], v[6:7], v[90:91] op_sel:[1,0,0] op_sel_hi:[1,1,1]
	ds_read_b128 v[8:11], v100 offset:18432
	ds_read_b128 v[12:15], v100 offset:18688
	ds_read_b128 v[16:19], v100 offset:18944
	ds_read_b128 v[20:23], v100 offset:19200
	ds_read_b128 v[24:27], v100 offset:19456
	ds_read_b64 v[28:29], v101 offset:19712
	s_waitcnt lgkmcnt(14)
	v_pk_mul_f32 v[80:81], v[44:45], v[0:1] op_sel:[0,0] op_sel_hi:[0,1]
	v_pk_mul_f32 v[82:83], v[44:45], v[2:3] op_sel:[1,0] op_sel_hi:[1,1]
	v_pk_fma_f32 v[80:81], v[46:47], v[4:5], v[80:81] op_sel:[0,0,0] op_sel_hi:[0,1,1]
	v_pk_fma_f32 v[82:83], v[46:47], v[6:7], v[82:83] op_sel:[1,0,0] op_sel_hi:[1,1,1]
	v_pk_add_f32 v[88:89], v[88:89], v[90:91]
	v_pk_add_f32 v[80:81], v[80:81], v[82:83]
	v_pk_mul_f32 v[0:1], v[36:37], v[0:1] op_sel:[0,0] op_sel_hi:[0,1]
	v_pk_mul_f32 v[2:3], v[36:37], v[2:3] op_sel:[1,0] op_sel_hi:[1,1]
	v_add_f32_dpp v80, v80, v80 quad_perm:[1,0,3,2] row_mask:0xf bank_mask:0xf
	v_add_f32_dpp v81, v81, v81 quad_perm:[1,0,3,2] row_mask:0xf bank_mask:0xf
	v_pk_mul_f32 v[4:5], v[38:39], v[4:5] op_sel:[0,0] op_sel_hi:[0,1]
	v_add_f32_dpp v80, v80, v80 quad_perm:[2,3,0,1] row_mask:0xf bank_mask:0xf
	v_add_f32_dpp v81, v81, v81 quad_perm:[2,3,0,1] row_mask:0xf bank_mask:0xf
	v_pk_mul_f32 v[6:7], v[38:39], v[6:7] op_sel:[1,0] op_sel_hi:[1,1]
	v_add_f32_dpp v80, v80, v80 row_half_mirror row_mask:0xf bank_mask:0xf
	v_add_f32_dpp v81, v81, v81 row_half_mirror row_mask:0xf bank_mask:0xf
	ds_write_b64 v102, v[88:89] offset:18432
	v_add_f32_dpp v80, v80, v80 row_mirror row_mask:0xf bank_mask:0xf
	v_add_f32_dpp v81, v81, v81 row_mirror row_mask:0xf bank_mask:0xf
	v_pk_fma_f32 v[0:1], v[80:81], v[48:49], v[0:1] op_sel:[0,0,0] op_sel_hi:[1,0,1] neg_lo:[1,0,0] neg_hi:[1,0,0]
	v_pk_fma_f32 v[2:3], v[80:81], v[48:49], v[2:3] op_sel:[0,1,0] op_sel_hi:[1,1,1] neg_lo:[1,0,0] neg_hi:[1,0,0]
	v_pk_fma_f32 v[4:5], v[80:81], v[50:51], v[4:5] op_sel:[0,0,0] op_sel_hi:[1,0,1] neg_lo:[1,0,0] neg_hi:[1,0,0]
	v_pk_fma_f32 v[6:7], v[80:81], v[50:51], v[6:7] op_sel:[0,1,0] op_sel_hi:[1,1,1] neg_lo:[1,0,0] neg_hi:[1,0,0]
	v_pk_fma_f32 v[0:1], v[52:53], v[40:41], v[0:1] op_sel:[0,0,0] op_sel_hi:[1,0,1]
	v_pk_fma_f32 v[2:3], v[52:53], v[40:41], v[2:3] op_sel:[0,1,0] op_sel_hi:[1,1,1]
	v_pk_fma_f32 v[4:5], v[52:53], v[42:43], v[4:5] op_sel:[0,0,0] op_sel_hi:[1,0,1]
	v_pk_fma_f32 v[6:7], v[52:53], v[42:43], v[6:7] op_sel:[0,1,0] op_sel_hi:[1,1,1]
	v_pk_mul_f32 v[84:85], v[32:33], v[0:1] op_sel:[0,0] op_sel_hi:[0,1]
	v_pk_mul_f32 v[86:87], v[32:33], v[2:3] op_sel:[1,0] op_sel_hi:[1,1]
	v_pk_fma_f32 v[84:85], v[34:35], v[4:5], v[84:85] op_sel:[0,0,0] op_sel_hi:[0,1,1]
	v_pk_fma_f32 v[86:87], v[34:35], v[6:7], v[86:87] op_sel:[1,0,0] op_sel_hi:[1,1,1]
	ds_read_b128 v[32:35], v100 offset:19968
	ds_read_b128 v[36:39], v100 offset:20224
	ds_read_b128 v[40:43], v100 offset:20480
	ds_read_b128 v[44:47], v100 offset:20736
	ds_read_b128 v[48:51], v100 offset:20992
	ds_read_b64 v[52:53], v101 offset:21248
	s_waitcnt lgkmcnt(14)
	v_pk_mul_f32 v[80:81], v[68:69], v[0:1] op_sel:[0,0] op_sel_hi:[0,1]
	v_pk_mul_f32 v[82:83], v[68:69], v[2:3] op_sel:[1,0] op_sel_hi:[1,1]
	v_pk_fma_f32 v[80:81], v[70:71], v[4:5], v[80:81] op_sel:[0,0,0] op_sel_hi:[0,1,1]
	v_pk_fma_f32 v[82:83], v[70:71], v[6:7], v[82:83] op_sel:[1,0,0] op_sel_hi:[1,1,1]
	v_pk_add_f32 v[84:85], v[84:85], v[86:87]
	v_pk_add_f32 v[80:81], v[80:81], v[82:83]
	v_pk_mul_f32 v[0:1], v[60:61], v[0:1] op_sel:[0,0] op_sel_hi:[0,1]
	v_pk_mul_f32 v[2:3], v[60:61], v[2:3] op_sel:[1,0] op_sel_hi:[1,1]
	v_add_f32_dpp v80, v80, v80 quad_perm:[1,0,3,2] row_mask:0xf bank_mask:0xf
	v_add_f32_dpp v81, v81, v81 quad_perm:[1,0,3,2] row_mask:0xf bank_mask:0xf
	v_pk_mul_f32 v[4:5], v[62:63], v[4:5] op_sel:[0,0] op_sel_hi:[0,1]
	v_add_f32_dpp v80, v80, v80 quad_perm:[2,3,0,1] row_mask:0xf bank_mask:0xf
	v_add_f32_dpp v81, v81, v81 quad_perm:[2,3,0,1] row_mask:0xf bank_mask:0xf
	v_pk_mul_f32 v[6:7], v[62:63], v[6:7] op_sel:[1,0] op_sel_hi:[1,1]
	v_add_f32_dpp v80, v80, v80 row_half_mirror row_mask:0xf bank_mask:0xf
	v_add_f32_dpp v81, v81, v81 row_half_mirror row_mask:0xf bank_mask:0xf
	ds_write_b64 v102, v[84:85] offset:20480
	v_add_f32_dpp v80, v80, v80 row_mirror row_mask:0xf bank_mask:0xf
	v_add_f32_dpp v81, v81, v81 row_mirror row_mask:0xf bank_mask:0xf
	v_pk_fma_f32 v[0:1], v[80:81], v[72:73], v[0:1] op_sel:[0,0,0] op_sel_hi:[1,0,1] neg_lo:[1,0,0] neg_hi:[1,0,0]
	v_pk_fma_f32 v[2:3], v[80:81], v[72:73], v[2:3] op_sel:[0,1,0] op_sel_hi:[1,1,1] neg_lo:[1,0,0] neg_hi:[1,0,0]
	v_pk_fma_f32 v[4:5], v[80:81], v[74:75], v[4:5] op_sel:[0,0,0] op_sel_hi:[1,0,1] neg_lo:[1,0,0] neg_hi:[1,0,0]
	v_pk_fma_f32 v[6:7], v[80:81], v[74:75], v[6:7] op_sel:[0,1,0] op_sel_hi:[1,1,1] neg_lo:[1,0,0] neg_hi:[1,0,0]
	v_pk_fma_f32 v[0:1], v[76:77], v[64:65], v[0:1] op_sel:[0,0,0] op_sel_hi:[1,0,1]
	v_pk_fma_f32 v[2:3], v[76:77], v[64:65], v[2:3] op_sel:[0,1,0] op_sel_hi:[1,1,1]
	v_pk_fma_f32 v[4:5], v[76:77], v[66:67], v[4:5] op_sel:[0,0,0] op_sel_hi:[1,0,1]
	v_pk_fma_f32 v[6:7], v[76:77], v[66:67], v[6:7] op_sel:[0,1,0] op_sel_hi:[1,1,1]
	v_pk_mul_f32 v[88:89], v[56:57], v[0:1] op_sel:[0,0] op_sel_hi:[0,1]
	v_pk_mul_f32 v[90:91], v[56:57], v[2:3] op_sel:[1,0] op_sel_hi:[1,1]
	v_pk_fma_f32 v[88:89], v[58:59], v[4:5], v[88:89] op_sel:[0,0,0] op_sel_hi:[0,1,1]
	v_pk_fma_f32 v[90:91], v[58:59], v[6:7], v[90:91] op_sel:[1,0,0] op_sel_hi:[1,1,1]
	ds_read_b128 v[56:59], v100 offset:21504
	ds_read_b128 v[60:63], v100 offset:21760
	ds_read_b128 v[64:67], v100 offset:22016
	ds_read_b128 v[68:71], v100 offset:22272
	ds_read_b128 v[72:75], v100 offset:22528
	ds_read_b64 v[76:77], v101 offset:22784
	s_waitcnt lgkmcnt(14)
	v_pk_mul_f32 v[80:81], v[20:21], v[0:1] op_sel:[0,0] op_sel_hi:[0,1]
	v_pk_mul_f32 v[82:83], v[20:21], v[2:3] op_sel:[1,0] op_sel_hi:[1,1]
	v_pk_fma_f32 v[80:81], v[22:23], v[4:5], v[80:81] op_sel:[0,0,0] op_sel_hi:[0,1,1]
	v_pk_fma_f32 v[82:83], v[22:23], v[6:7], v[82:83] op_sel:[1,0,0] op_sel_hi:[1,1,1]
	v_pk_add_f32 v[88:89], v[88:89], v[90:91]
	v_pk_add_f32 v[80:81], v[80:81], v[82:83]
	v_pk_mul_f32 v[0:1], v[12:13], v[0:1] op_sel:[0,0] op_sel_hi:[0,1]
	v_pk_mul_f32 v[2:3], v[12:13], v[2:3] op_sel:[1,0] op_sel_hi:[1,1]
	v_add_f32_dpp v80, v80, v80 quad_perm:[1,0,3,2] row_mask:0xf bank_mask:0xf
	v_add_f32_dpp v81, v81, v81 quad_perm:[1,0,3,2] row_mask:0xf bank_mask:0xf
	v_pk_mul_f32 v[4:5], v[14:15], v[4:5] op_sel:[0,0] op_sel_hi:[0,1]
	v_add_f32_dpp v80, v80, v80 quad_perm:[2,3,0,1] row_mask:0xf bank_mask:0xf
	v_add_f32_dpp v81, v81, v81 quad_perm:[2,3,0,1] row_mask:0xf bank_mask:0xf
	v_pk_mul_f32 v[6:7], v[14:15], v[6:7] op_sel:[1,0] op_sel_hi:[1,1]
	v_add_f32_dpp v80, v80, v80 row_half_mirror row_mask:0xf bank_mask:0xf
	v_add_f32_dpp v81, v81, v81 row_half_mirror row_mask:0xf bank_mask:0xf
	ds_write_b64 v102, v[88:89] offset:22528
	v_add_f32_dpp v80, v80, v80 row_mirror row_mask:0xf bank_mask:0xf
	v_add_f32_dpp v81, v81, v81 row_mirror row_mask:0xf bank_mask:0xf
	v_pk_fma_f32 v[0:1], v[80:81], v[24:25], v[0:1] op_sel:[0,0,0] op_sel_hi:[1,0,1] neg_lo:[1,0,0] neg_hi:[1,0,0]
	v_pk_fma_f32 v[2:3], v[80:81], v[24:25], v[2:3] op_sel:[0,1,0] op_sel_hi:[1,1,1] neg_lo:[1,0,0] neg_hi:[1,0,0]
	v_pk_fma_f32 v[4:5], v[80:81], v[26:27], v[4:5] op_sel:[0,0,0] op_sel_hi:[1,0,1] neg_lo:[1,0,0] neg_hi:[1,0,0]
	v_pk_fma_f32 v[6:7], v[80:81], v[26:27], v[6:7] op_sel:[0,1,0] op_sel_hi:[1,1,1] neg_lo:[1,0,0] neg_hi:[1,0,0]
	v_pk_fma_f32 v[0:1], v[28:29], v[16:17], v[0:1] op_sel:[0,0,0] op_sel_hi:[1,0,1]
	v_pk_fma_f32 v[2:3], v[28:29], v[16:17], v[2:3] op_sel:[0,1,0] op_sel_hi:[1,1,1]
	v_pk_fma_f32 v[4:5], v[28:29], v[18:19], v[4:5] op_sel:[0,0,0] op_sel_hi:[1,0,1]
	v_pk_fma_f32 v[6:7], v[28:29], v[18:19], v[6:7] op_sel:[0,1,0] op_sel_hi:[1,1,1]
	v_pk_mul_f32 v[84:85], v[8:9], v[0:1] op_sel:[0,0] op_sel_hi:[0,1]
	v_pk_mul_f32 v[86:87], v[8:9], v[2:3] op_sel:[1,0] op_sel_hi:[1,1]
	v_pk_fma_f32 v[84:85], v[10:11], v[4:5], v[84:85] op_sel:[0,0,0] op_sel_hi:[0,1,1]
	v_pk_fma_f32 v[86:87], v[10:11], v[6:7], v[86:87] op_sel:[1,0,0] op_sel_hi:[1,1,1]
	ds_read_b128 v[8:11], v100 offset:23040
	ds_read_b128 v[12:15], v100 offset:23296
	ds_read_b128 v[16:19], v100 offset:23552
	ds_read_b128 v[20:23], v100 offset:23808
	ds_read_b128 v[24:27], v100 offset:24064
	ds_read_b64 v[28:29], v101 offset:24320
	s_waitcnt lgkmcnt(14)
	v_pk_mul_f32 v[80:81], v[44:45], v[0:1] op_sel:[0,0] op_sel_hi:[0,1]
	v_pk_mul_f32 v[82:83], v[44:45], v[2:3] op_sel:[1,0] op_sel_hi:[1,1]
	v_pk_fma_f32 v[80:81], v[46:47], v[4:5], v[80:81] op_sel:[0,0,0] op_sel_hi:[0,1,1]
	v_pk_fma_f32 v[82:83], v[46:47], v[6:7], v[82:83] op_sel:[1,0,0] op_sel_hi:[1,1,1]
	v_pk_add_f32 v[84:85], v[84:85], v[86:87]
	v_pk_add_f32 v[80:81], v[80:81], v[82:83]
	v_pk_mul_f32 v[0:1], v[36:37], v[0:1] op_sel:[0,0] op_sel_hi:[0,1]
	v_pk_mul_f32 v[2:3], v[36:37], v[2:3] op_sel:[1,0] op_sel_hi:[1,1]
	v_add_f32_dpp v80, v80, v80 quad_perm:[1,0,3,2] row_mask:0xf bank_mask:0xf
	v_add_f32_dpp v81, v81, v81 quad_perm:[1,0,3,2] row_mask:0xf bank_mask:0xf
	v_pk_mul_f32 v[4:5], v[38:39], v[4:5] op_sel:[0,0] op_sel_hi:[0,1]
	v_add_f32_dpp v80, v80, v80 quad_perm:[2,3,0,1] row_mask:0xf bank_mask:0xf
	v_add_f32_dpp v81, v81, v81 quad_perm:[2,3,0,1] row_mask:0xf bank_mask:0xf
	v_pk_mul_f32 v[6:7], v[38:39], v[6:7] op_sel:[1,0] op_sel_hi:[1,1]
	v_add_f32_dpp v80, v80, v80 row_half_mirror row_mask:0xf bank_mask:0xf
	v_add_f32_dpp v81, v81, v81 row_half_mirror row_mask:0xf bank_mask:0xf
	ds_write_b64 v102, v[84:85] offset:24576
	v_add_f32_dpp v80, v80, v80 row_mirror row_mask:0xf bank_mask:0xf
	v_add_f32_dpp v81, v81, v81 row_mirror row_mask:0xf bank_mask:0xf
	v_pk_fma_f32 v[0:1], v[80:81], v[48:49], v[0:1] op_sel:[0,0,0] op_sel_hi:[1,0,1] neg_lo:[1,0,0] neg_hi:[1,0,0]
	v_pk_fma_f32 v[2:3], v[80:81], v[48:49], v[2:3] op_sel:[0,1,0] op_sel_hi:[1,1,1] neg_lo:[1,0,0] neg_hi:[1,0,0]
	v_pk_fma_f32 v[4:5], v[80:81], v[50:51], v[4:5] op_sel:[0,0,0] op_sel_hi:[1,0,1] neg_lo:[1,0,0] neg_hi:[1,0,0]
	v_pk_fma_f32 v[6:7], v[80:81], v[50:51], v[6:7] op_sel:[0,1,0] op_sel_hi:[1,1,1] neg_lo:[1,0,0] neg_hi:[1,0,0]
	v_pk_fma_f32 v[0:1], v[52:53], v[40:41], v[0:1] op_sel:[0,0,0] op_sel_hi:[1,0,1]
	v_pk_fma_f32 v[2:3], v[52:53], v[40:41], v[2:3] op_sel:[0,1,0] op_sel_hi:[1,1,1]
	v_pk_fma_f32 v[4:5], v[52:53], v[42:43], v[4:5] op_sel:[0,0,0] op_sel_hi:[1,0,1]
	v_pk_fma_f32 v[6:7], v[52:53], v[42:43], v[6:7] op_sel:[0,1,0] op_sel_hi:[1,1,1]
	v_pk_mul_f32 v[88:89], v[32:33], v[0:1] op_sel:[0,0] op_sel_hi:[0,1]
	v_pk_mul_f32 v[90:91], v[32:33], v[2:3] op_sel:[1,0] op_sel_hi:[1,1]
	v_pk_fma_f32 v[88:89], v[34:35], v[4:5], v[88:89] op_sel:[0,0,0] op_sel_hi:[0,1,1]
	v_pk_fma_f32 v[90:91], v[34:35], v[6:7], v[90:91] op_sel:[1,0,0] op_sel_hi:[1,1,1]
	s_waitcnt lgkmcnt(8)
	v_pk_mul_f32 v[80:81], v[68:69], v[0:1] op_sel:[0,0] op_sel_hi:[0,1]
	v_pk_mul_f32 v[82:83], v[68:69], v[2:3] op_sel:[1,0] op_sel_hi:[1,1]
	v_pk_fma_f32 v[80:81], v[70:71], v[4:5], v[80:81] op_sel:[0,0,0] op_sel_hi:[0,1,1]
	v_pk_fma_f32 v[82:83], v[70:71], v[6:7], v[82:83] op_sel:[1,0,0] op_sel_hi:[1,1,1]
	v_pk_add_f32 v[88:89], v[88:89], v[90:91]
	v_pk_add_f32 v[80:81], v[80:81], v[82:83]
	v_pk_mul_f32 v[0:1], v[60:61], v[0:1] op_sel:[0,0] op_sel_hi:[0,1]
	v_pk_mul_f32 v[2:3], v[60:61], v[2:3] op_sel:[1,0] op_sel_hi:[1,1]
	v_add_f32_dpp v80, v80, v80 quad_perm:[1,0,3,2] row_mask:0xf bank_mask:0xf
	v_add_f32_dpp v81, v81, v81 quad_perm:[1,0,3,2] row_mask:0xf bank_mask:0xf
	v_pk_mul_f32 v[4:5], v[62:63], v[4:5] op_sel:[0,0] op_sel_hi:[0,1]
	v_add_f32_dpp v80, v80, v80 quad_perm:[2,3,0,1] row_mask:0xf bank_mask:0xf
	v_add_f32_dpp v81, v81, v81 quad_perm:[2,3,0,1] row_mask:0xf bank_mask:0xf
	v_pk_mul_f32 v[6:7], v[62:63], v[6:7] op_sel:[1,0] op_sel_hi:[1,1]
	v_add_f32_dpp v80, v80, v80 row_half_mirror row_mask:0xf bank_mask:0xf
	v_add_f32_dpp v81, v81, v81 row_half_mirror row_mask:0xf bank_mask:0xf
	ds_write_b64 v102, v[88:89] offset:26624
	v_add_f32_dpp v80, v80, v80 row_mirror row_mask:0xf bank_mask:0xf
	v_add_f32_dpp v81, v81, v81 row_mirror row_mask:0xf bank_mask:0xf
	v_pk_fma_f32 v[0:1], v[80:81], v[72:73], v[0:1] op_sel:[0,0,0] op_sel_hi:[1,0,1] neg_lo:[1,0,0] neg_hi:[1,0,0]
	v_pk_fma_f32 v[2:3], v[80:81], v[72:73], v[2:3] op_sel:[0,1,0] op_sel_hi:[1,1,1] neg_lo:[1,0,0] neg_hi:[1,0,0]
	v_pk_fma_f32 v[4:5], v[80:81], v[74:75], v[4:5] op_sel:[0,0,0] op_sel_hi:[1,0,1] neg_lo:[1,0,0] neg_hi:[1,0,0]
	v_pk_fma_f32 v[6:7], v[80:81], v[74:75], v[6:7] op_sel:[0,1,0] op_sel_hi:[1,1,1] neg_lo:[1,0,0] neg_hi:[1,0,0]
	v_pk_fma_f32 v[0:1], v[76:77], v[64:65], v[0:1] op_sel:[0,0,0] op_sel_hi:[1,0,1]
	v_pk_fma_f32 v[2:3], v[76:77], v[64:65], v[2:3] op_sel:[0,1,0] op_sel_hi:[1,1,1]
	v_pk_fma_f32 v[4:5], v[76:77], v[66:67], v[4:5] op_sel:[0,0,0] op_sel_hi:[1,0,1]
	v_pk_fma_f32 v[6:7], v[76:77], v[66:67], v[6:7] op_sel:[0,1,0] op_sel_hi:[1,1,1]
	v_pk_mul_f32 v[84:85], v[56:57], v[0:1] op_sel:[0,0] op_sel_hi:[0,1]
	v_pk_mul_f32 v[86:87], v[56:57], v[2:3] op_sel:[1,0] op_sel_hi:[1,1]
	v_pk_fma_f32 v[84:85], v[58:59], v[4:5], v[84:85] op_sel:[0,0,0] op_sel_hi:[0,1,1]
	v_pk_fma_f32 v[86:87], v[58:59], v[6:7], v[86:87] op_sel:[1,0,0] op_sel_hi:[1,1,1]
	s_waitcnt lgkmcnt(2)
	v_pk_mul_f32 v[80:81], v[20:21], v[0:1] op_sel:[0,0] op_sel_hi:[0,1]
	v_pk_mul_f32 v[82:83], v[20:21], v[2:3] op_sel:[1,0] op_sel_hi:[1,1]
	v_pk_fma_f32 v[80:81], v[22:23], v[4:5], v[80:81] op_sel:[0,0,0] op_sel_hi:[0,1,1]
	v_pk_fma_f32 v[82:83], v[22:23], v[6:7], v[82:83] op_sel:[1,0,0] op_sel_hi:[1,1,1]
	v_pk_add_f32 v[84:85], v[84:85], v[86:87]
	v_pk_add_f32 v[80:81], v[80:81], v[82:83]
	v_pk_mul_f32 v[0:1], v[12:13], v[0:1] op_sel:[0,0] op_sel_hi:[0,1]
	v_pk_mul_f32 v[2:3], v[12:13], v[2:3] op_sel:[1,0] op_sel_hi:[1,1]
	v_add_f32_dpp v80, v80, v80 quad_perm:[1,0,3,2] row_mask:0xf bank_mask:0xf
	v_add_f32_dpp v81, v81, v81 quad_perm:[1,0,3,2] row_mask:0xf bank_mask:0xf
	v_pk_mul_f32 v[4:5], v[14:15], v[4:5] op_sel:[0,0] op_sel_hi:[0,1]
	v_add_f32_dpp v80, v80, v80 quad_perm:[2,3,0,1] row_mask:0xf bank_mask:0xf
	v_add_f32_dpp v81, v81, v81 quad_perm:[2,3,0,1] row_mask:0xf bank_mask:0xf
	v_pk_mul_f32 v[6:7], v[14:15], v[6:7] op_sel:[1,0] op_sel_hi:[1,1]
	v_add_f32_dpp v80, v80, v80 row_half_mirror row_mask:0xf bank_mask:0xf
	v_add_f32_dpp v81, v81, v81 row_half_mirror row_mask:0xf bank_mask:0xf
	ds_write_b64 v102, v[84:85] offset:28672
	v_add_f32_dpp v80, v80, v80 row_mirror row_mask:0xf bank_mask:0xf
	v_add_f32_dpp v81, v81, v81 row_mirror row_mask:0xf bank_mask:0xf
	v_pk_fma_f32 v[0:1], v[80:81], v[24:25], v[0:1] op_sel:[0,0,0] op_sel_hi:[1,0,1] neg_lo:[1,0,0] neg_hi:[1,0,0]
	v_pk_fma_f32 v[2:3], v[80:81], v[24:25], v[2:3] op_sel:[0,1,0] op_sel_hi:[1,1,1] neg_lo:[1,0,0] neg_hi:[1,0,0]
	v_pk_fma_f32 v[4:5], v[80:81], v[26:27], v[4:5] op_sel:[0,0,0] op_sel_hi:[1,0,1] neg_lo:[1,0,0] neg_hi:[1,0,0]
	v_pk_fma_f32 v[6:7], v[80:81], v[26:27], v[6:7] op_sel:[0,1,0] op_sel_hi:[1,1,1] neg_lo:[1,0,0] neg_hi:[1,0,0]
	v_pk_fma_f32 v[0:1], v[28:29], v[16:17], v[0:1] op_sel:[0,0,0] op_sel_hi:[1,0,1]
	v_pk_fma_f32 v[2:3], v[28:29], v[16:17], v[2:3] op_sel:[0,1,0] op_sel_hi:[1,1,1]
	v_pk_fma_f32 v[4:5], v[28:29], v[18:19], v[4:5] op_sel:[0,0,0] op_sel_hi:[1,0,1]
	v_pk_fma_f32 v[6:7], v[28:29], v[18:19], v[6:7] op_sel:[0,1,0] op_sel_hi:[1,1,1]
	v_pk_mul_f32 v[88:89], v[8:9], v[0:1] op_sel:[0,0] op_sel_hi:[0,1]
	v_pk_mul_f32 v[90:91], v[8:9], v[2:3] op_sel:[1,0] op_sel_hi:[1,1]
	v_pk_fma_f32 v[88:89], v[10:11], v[4:5], v[88:89] op_sel:[0,0,0] op_sel_hi:[0,1,1]
	v_pk_fma_f32 v[90:91], v[10:11], v[6:7], v[90:91] op_sel:[1,0,0] op_sel_hi:[1,1,1]
	s_nop 0
	v_pk_add_f32 v[88:89], v[88:89], v[90:91]
	s_nop 0
	ds_write_b64 v102, v[88:89] offset:30720
	s_waitcnt lgkmcnt(0)
	s_barrier
	ds_read_b128 v[8:11], v100 offset:24576
	ds_read_b128 v[12:15], v100 offset:24832
	ds_read_b128 v[16:19], v100 offset:25088
	ds_read_b128 v[20:23], v100 offset:25344
	ds_read_b128 v[24:27], v100 offset:25600
	ds_read_b64 v[28:29], v101 offset:25856
	ds_read_b128 v[32:35], v100 offset:26112
	ds_read_b128 v[36:39], v100 offset:26368
	ds_read_b128 v[40:43], v100 offset:26624
	ds_read_b128 v[44:47], v100 offset:26880
	ds_read_b128 v[48:51], v100 offset:27136
	ds_read_b64 v[52:53], v101 offset:27392
	ds_read_b128 v[56:59], v103 offset:0
	v_xor_b32_e32 v93, 16, v103
	ds_read_b128 v[60:63], v93 offset:0
	v_xor_b32_e32 v93, 32, v103
	ds_read_b128 v[64:67], v93 offset:0
	v_xor_b32_e32 v93, 48, v103
	ds_read_b128 v[68:71], v93 offset:0
	v_xor_b32_e32 v93, 64, v103
	ds_read_b128 v[72:75], v93 offset:0
	v_xor_b32_e32 v93, 80, v103
	ds_read_b128 v[76:79], v93 offset:0
	v_xor_b32_e32 v93, 96, v103
	ds_read_b128 v[80:83], v93 offset:0
	v_xor_b32_e32 v93, 112, v103
	ds_read_b128 v[84:87], v93 offset:0
	s_waitcnt lgkmcnt(0)
	v_pk_add_f32 v[56:57], v[56:57], v[58:59]
	v_pk_add_f32 v[60:61], v[60:61], v[62:63]
	v_pk_add_f32 v[64:65], v[64:65], v[66:67]
	v_pk_add_f32 v[68:69], v[68:69], v[70:71]
	v_pk_add_f32 v[72:73], v[72:73], v[74:75]
	v_pk_add_f32 v[76:77], v[76:77], v[78:79]
	v_pk_add_f32 v[80:81], v[80:81], v[82:83]
	v_pk_add_f32 v[84:85], v[84:85], v[86:87]
	v_pk_add_f32 v[56:57], v[56:57], v[60:61]
	v_pk_add_f32 v[64:65], v[64:65], v[68:69]
	v_pk_add_f32 v[72:73], v[72:73], v[76:77]
	v_pk_add_f32 v[80:81], v[80:81], v[84:85]
	v_pk_add_f32 v[56:57], v[56:57], v[64:65]
	v_pk_add_f32 v[72:73], v[72:73], v[80:81]
	s_nop 0
	v_pk_add_f32 v[56:57], v[56:57], v[72:73]
	s_nop 0
	v_cvt_pk_bf16_f32 v92, v56, v57
	global_store_dword v[104:105], v92, off
	v_lshl_add_u64 v[104:105], v[104:105], 0, s[52:53]
	ds_read_b128 v[56:59], v100 offset:27648
	ds_read_b128 v[60:63], v100 offset:27904
	ds_read_b128 v[64:67], v100 offset:28160
	ds_read_b128 v[68:71], v100 offset:28416
	ds_read_b128 v[72:75], v100 offset:28672
	ds_read_b64 v[76:77], v101 offset:28928
	v_pk_mul_f32 v[80:81], v[20:21], v[0:1] op_sel:[0,0] op_sel_hi:[0,1]
	v_pk_mul_f32 v[82:83], v[20:21], v[2:3] op_sel:[1,0] op_sel_hi:[1,1]
	v_pk_fma_f32 v[80:81], v[22:23], v[4:5], v[80:81] op_sel:[0,0,0] op_sel_hi:[0,1,1]
	v_pk_fma_f32 v[82:83], v[22:23], v[6:7], v[82:83] op_sel:[1,0,0] op_sel_hi:[1,1,1]
	s_nop 0
	v_pk_add_f32 v[80:81], v[80:81], v[82:83]
	v_pk_mul_f32 v[0:1], v[12:13], v[0:1] op_sel:[0,0] op_sel_hi:[0,1]
	v_pk_mul_f32 v[2:3], v[12:13], v[2:3] op_sel:[1,0] op_sel_hi:[1,1]
	v_add_f32_dpp v80, v80, v80 quad_perm:[1,0,3,2] row_mask:0xf bank_mask:0xf
	v_add_f32_dpp v81, v81, v81 quad_perm:[1,0,3,2] row_mask:0xf bank_mask:0xf
	v_pk_mul_f32 v[4:5], v[14:15], v[4:5] op_sel:[0,0] op_sel_hi:[0,1]
	v_add_f32_dpp v80, v80, v80 quad_perm:[2,3,0,1] row_mask:0xf bank_mask:0xf
	v_add_f32_dpp v81, v81, v81 quad_perm:[2,3,0,1] row_mask:0xf bank_mask:0xf
	v_pk_mul_f32 v[6:7], v[14:15], v[6:7] op_sel:[1,0] op_sel_hi:[1,1]
	v_add_f32_dpp v80, v80, v80 row_half_mirror row_mask:0xf bank_mask:0xf
	v_add_f32_dpp v81, v81, v81 row_half_mirror row_mask:0xf bank_mask:0xf
	s_nop 0
	v_add_f32_dpp v80, v80, v80 row_mirror row_mask:0xf bank_mask:0xf
	v_add_f32_dpp v81, v81, v81 row_mirror row_mask:0xf bank_mask:0xf
	v_pk_fma_f32 v[0:1], v[80:81], v[24:25], v[0:1] op_sel:[0,0,0] op_sel_hi:[1,0,1] neg_lo:[1,0,0] neg_hi:[1,0,0]
	v_pk_fma_f32 v[2:3], v[80:81], v[24:25], v[2:3] op_sel:[0,1,0] op_sel_hi:[1,1,1] neg_lo:[1,0,0] neg_hi:[1,0,0]
	v_pk_fma_f32 v[4:5], v[80:81], v[26:27], v[4:5] op_sel:[0,0,0] op_sel_hi:[1,0,1] neg_lo:[1,0,0] neg_hi:[1,0,0]
	v_pk_fma_f32 v[6:7], v[80:81], v[26:27], v[6:7] op_sel:[0,1,0] op_sel_hi:[1,1,1] neg_lo:[1,0,0] neg_hi:[1,0,0]
	v_pk_fma_f32 v[0:1], v[28:29], v[16:17], v[0:1] op_sel:[0,0,0] op_sel_hi:[1,0,1]
	v_pk_fma_f32 v[2:3], v[28:29], v[16:17], v[2:3] op_sel:[0,1,0] op_sel_hi:[1,1,1]
	v_pk_fma_f32 v[4:5], v[28:29], v[18:19], v[4:5] op_sel:[0,0,0] op_sel_hi:[1,0,1]
	v_pk_fma_f32 v[6:7], v[28:29], v[18:19], v[6:7] op_sel:[0,1,0] op_sel_hi:[1,1,1]
	v_pk_mul_f32 v[84:85], v[8:9], v[0:1] op_sel:[0,0] op_sel_hi:[0,1]
	v_pk_mul_f32 v[86:87], v[8:9], v[2:3] op_sel:[1,0] op_sel_hi:[1,1]
	v_pk_fma_f32 v[84:85], v[10:11], v[4:5], v[84:85] op_sel:[0,0,0] op_sel_hi:[0,1,1]
	v_pk_fma_f32 v[86:87], v[10:11], v[6:7], v[86:87] op_sel:[1,0,0] op_sel_hi:[1,1,1]
	ds_read_b128 v[8:11], v100 offset:29184
	ds_read_b128 v[12:15], v100 offset:29440
	ds_read_b128 v[16:19], v100 offset:29696
	ds_read_b128 v[20:23], v100 offset:29952
	ds_read_b128 v[24:27], v100 offset:30208
	ds_read_b64 v[28:29], v101 offset:30464
	v_pk_mul_f32 v[80:81], v[44:45], v[0:1] op_sel:[0,0] op_sel_hi:[0,1]
	v_pk_mul_f32 v[82:83], v[44:45], v[2:3] op_sel:[1,0] op_sel_hi:[1,1]
	v_pk_fma_f32 v[80:81], v[46:47], v[4:5], v[80:81] op_sel:[0,0,0] op_sel_hi:[0,1,1]
	v_pk_fma_f32 v[82:83], v[46:47], v[6:7], v[82:83] op_sel:[1,0,0] op_sel_hi:[1,1,1]
	v_pk_add_f32 v[84:85], v[84:85], v[86:87]
	v_pk_add_f32 v[80:81], v[80:81], v[82:83]
	v_pk_mul_f32 v[0:1], v[36:37], v[0:1] op_sel:[0,0] op_sel_hi:[0,1]
	v_pk_mul_f32 v[2:3], v[36:37], v[2:3] op_sel:[1,0] op_sel_hi:[1,1]
	v_add_f32_dpp v80, v80, v80 quad_perm:[1,0,3,2] row_mask:0xf bank_mask:0xf
	v_add_f32_dpp v81, v81, v81 quad_perm:[1,0,3,2] row_mask:0xf bank_mask:0xf
	v_pk_mul_f32 v[4:5], v[38:39], v[4:5] op_sel:[0,0] op_sel_hi:[0,1]
	v_add_f32_dpp v80, v80, v80 quad_perm:[2,3,0,1] row_mask:0xf bank_mask:0xf
	v_add_f32_dpp v81, v81, v81 quad_perm:[2,3,0,1] row_mask:0xf bank_mask:0xf
	v_pk_mul_f32 v[6:7], v[38:39], v[6:7] op_sel:[1,0] op_sel_hi:[1,1]
	v_add_f32_dpp v80, v80, v80 row_half_mirror row_mask:0xf bank_mask:0xf
	v_add_f32_dpp v81, v81, v81 row_half_mirror row_mask:0xf bank_mask:0xf
	ds_write_b64 v102, v[84:85] offset:32768
	v_add_f32_dpp v80, v80, v80 row_mirror row_mask:0xf bank_mask:0xf
	v_add_f32_dpp v81, v81, v81 row_mirror row_mask:0xf bank_mask:0xf
	v_pk_fma_f32 v[0:1], v[80:81], v[48:49], v[0:1] op_sel:[0,0,0] op_sel_hi:[1,0,1] neg_lo:[1,0,0] neg_hi:[1,0,0]
	v_pk_fma_f32 v[2:3], v[80:81], v[48:49], v[2:3] op_sel:[0,1,0] op_sel_hi:[1,1,1] neg_lo:[1,0,0] neg_hi:[1,0,0]
	v_pk_fma_f32 v[4:5], v[80:81], v[50:51], v[4:5] op_sel:[0,0,0] op_sel_hi:[1,0,1] neg_lo:[1,0,0] neg_hi:[1,0,0]
	v_pk_fma_f32 v[6:7], v[80:81], v[50:51], v[6:7] op_sel:[0,1,0] op_sel_hi:[1,1,1] neg_lo:[1,0,0] neg_hi:[1,0,0]
	v_pk_fma_f32 v[0:1], v[52:53], v[40:41], v[0:1] op_sel:[0,0,0] op_sel_hi:[1,0,1]
	v_pk_fma_f32 v[2:3], v[52:53], v[40:41], v[2:3] op_sel:[0,1,0] op_sel_hi:[1,1,1]
	v_pk_fma_f32 v[4:5], v[52:53], v[42:43], v[4:5] op_sel:[0,0,0] op_sel_hi:[1,0,1]
	v_pk_fma_f32 v[6:7], v[52:53], v[42:43], v[6:7] op_sel:[0,1,0] op_sel_hi:[1,1,1]
	v_pk_mul_f32 v[88:89], v[32:33], v[0:1] op_sel:[0,0] op_sel_hi:[0,1]
	v_pk_mul_f32 v[90:91], v[32:33], v[2:3] op_sel:[1,0] op_sel_hi:[1,1]
	v_pk_fma_f32 v[88:89], v[34:35], v[4:5], v[88:89] op_sel:[0,0,0] op_sel_hi:[0,1,1]
	v_pk_fma_f32 v[90:91], v[34:35], v[6:7], v[90:91] op_sel:[1,0,0] op_sel_hi:[1,1,1]
	ds_read_b128 v[32:35], v100 offset:30720
	ds_read_b128 v[36:39], v100 offset:30976
	ds_read_b128 v[40:43], v100 offset:31232
	ds_read_b128 v[44:47], v100 offset:31488
	ds_read_b128 v[48:51], v100 offset:31744
	ds_read_b64 v[52:53], v101 offset:32000
	s_waitcnt lgkmcnt(13)
	v_pk_mul_f32 v[80:81], v[68:69], v[0:1] op_sel:[0,0] op_sel_hi:[0,1]
	v_pk_mul_f32 v[82:83], v[68:69], v[2:3] op_sel:[1,0] op_sel_hi:[1,1]
	v_pk_fma_f32 v[80:81], v[70:71], v[4:5], v[80:81] op_sel:[0,0,0] op_sel_hi:[0,1,1]
	v_pk_fma_f32 v[82:83], v[70:71], v[6:7], v[82:83] op_sel:[1,0,0] op_sel_hi:[1,1,1]
	v_pk_add_f32 v[88:89], v[88:89], v[90:91]
	v_pk_add_f32 v[80:81], v[80:81], v[82:83]
	v_pk_mul_f32 v[0:1], v[60:61], v[0:1] op_sel:[0,0] op_sel_hi:[0,1]
	v_pk_mul_f32 v[2:3], v[60:61], v[2:3] op_sel:[1,0] op_sel_hi:[1,1]
	v_add_f32_dpp v80, v80, v80 quad_perm:[1,0,3,2] row_mask:0xf bank_mask:0xf
	v_add_f32_dpp v81, v81, v81 quad_perm:[1,0,3,2] row_mask:0xf bank_mask:0xf
	v_pk_mul_f32 v[4:5], v[62:63], v[4:5] op_sel:[0,0] op_sel_hi:[0,1]
	v_add_f32_dpp v80, v80, v80 quad_perm:[2,3,0,1] row_mask:0xf bank_mask:0xf
	v_add_f32_dpp v81, v81, v81 quad_perm:[2,3,0,1] row_mask:0xf bank_mask:0xf
	v_pk_mul_f32 v[6:7], v[62:63], v[6:7] op_sel:[1,0] op_sel_hi:[1,1]
	v_add_f32_dpp v80, v80, v80 row_half_mirror row_mask:0xf bank_mask:0xf
	v_add_f32_dpp v81, v81, v81 row_half_mirror row_mask:0xf bank_mask:0xf
	ds_write_b64 v102, v[88:89] offset:34816
	v_add_f32_dpp v80, v80, v80 row_mirror row_mask:0xf bank_mask:0xf
	v_add_f32_dpp v81, v81, v81 row_mirror row_mask:0xf bank_mask:0xf
	v_pk_fma_f32 v[0:1], v[80:81], v[72:73], v[0:1] op_sel:[0,0,0] op_sel_hi:[1,0,1] neg_lo:[1,0,0] neg_hi:[1,0,0]
	v_pk_fma_f32 v[2:3], v[80:81], v[72:73], v[2:3] op_sel:[0,1,0] op_sel_hi:[1,1,1] neg_lo:[1,0,0] neg_hi:[1,0,0]
	v_pk_fma_f32 v[4:5], v[80:81], v[74:75], v[4:5] op_sel:[0,0,0] op_sel_hi:[1,0,1] neg_lo:[1,0,0] neg_hi:[1,0,0]
	v_pk_fma_f32 v[6:7], v[80:81], v[74:75], v[6:7] op_sel:[0,1,0] op_sel_hi:[1,1,1] neg_lo:[1,0,0] neg_hi:[1,0,0]
	v_pk_fma_f32 v[0:1], v[76:77], v[64:65], v[0:1] op_sel:[0,0,0] op_sel_hi:[1,0,1]
	v_pk_fma_f32 v[2:3], v[76:77], v[64:65], v[2:3] op_sel:[0,1,0] op_sel_hi:[1,1,1]
	v_pk_fma_f32 v[4:5], v[76:77], v[66:67], v[4:5] op_sel:[0,0,0] op_sel_hi:[1,0,1]
	v_pk_fma_f32 v[6:7], v[76:77], v[66:67], v[6:7] op_sel:[0,1,0] op_sel_hi:[1,1,1]
	v_pk_mul_f32 v[84:85], v[56:57], v[0:1] op_sel:[0,0] op_sel_hi:[0,1]
	v_pk_mul_f32 v[86:87], v[56:57], v[2:3] op_sel:[1,0] op_sel_hi:[1,1]
	v_pk_fma_f32 v[84:85], v[58:59], v[4:5], v[84:85] op_sel:[0,0,0] op_sel_hi:[0,1,1]
	v_pk_fma_f32 v[86:87], v[58:59], v[6:7], v[86:87] op_sel:[1,0,0] op_sel_hi:[1,1,1]
	ds_read_b128 v[56:59], v100 offset:32256
	ds_read_b128 v[60:63], v100 offset:32512
	ds_read_b128 v[64:67], v100 offset:32768
	ds_read_b128 v[68:71], v100 offset:33024
	ds_read_b128 v[72:75], v100 offset:33280
	ds_read_b64 v[76:77], v101 offset:33536
	s_waitcnt lgkmcnt(14)
	v_pk_mul_f32 v[80:81], v[20:21], v[0:1] op_sel:[0,0] op_sel_hi:[0,1]
	v_pk_mul_f32 v[82:83], v[20:21], v[2:3] op_sel:[1,0] op_sel_hi:[1,1]
	v_pk_fma_f32 v[80:81], v[22:23], v[4:5], v[80:81] op_sel:[0,0,0] op_sel_hi:[0,1,1]
	v_pk_fma_f32 v[82:83], v[22:23], v[6:7], v[82:83] op_sel:[1,0,0] op_sel_hi:[1,1,1]
	v_pk_add_f32 v[84:85], v[84:85], v[86:87]
	v_pk_add_f32 v[80:81], v[80:81], v[82:83]
	v_pk_mul_f32 v[0:1], v[12:13], v[0:1] op_sel:[0,0] op_sel_hi:[0,1]
	v_pk_mul_f32 v[2:3], v[12:13], v[2:3] op_sel:[1,0] op_sel_hi:[1,1]
	v_add_f32_dpp v80, v80, v80 quad_perm:[1,0,3,2] row_mask:0xf bank_mask:0xf
	v_add_f32_dpp v81, v81, v81 quad_perm:[1,0,3,2] row_mask:0xf bank_mask:0xf
	v_pk_mul_f32 v[4:5], v[14:15], v[4:5] op_sel:[0,0] op_sel_hi:[0,1]
	v_add_f32_dpp v80, v80, v80 quad_perm:[2,3,0,1] row_mask:0xf bank_mask:0xf
	v_add_f32_dpp v81, v81, v81 quad_perm:[2,3,0,1] row_mask:0xf bank_mask:0xf
	v_pk_mul_f32 v[6:7], v[14:15], v[6:7] op_sel:[1,0] op_sel_hi:[1,1]
	v_add_f32_dpp v80, v80, v80 row_half_mirror row_mask:0xf bank_mask:0xf
	v_add_f32_dpp v81, v81, v81 row_half_mirror row_mask:0xf bank_mask:0xf
	ds_write_b64 v102, v[84:85] offset:36864
	v_add_f32_dpp v80, v80, v80 row_mirror row_mask:0xf bank_mask:0xf
	v_add_f32_dpp v81, v81, v81 row_mirror row_mask:0xf bank_mask:0xf
	v_pk_fma_f32 v[0:1], v[80:81], v[24:25], v[0:1] op_sel:[0,0,0] op_sel_hi:[1,0,1] neg_lo:[1,0,0] neg_hi:[1,0,0]
	v_pk_fma_f32 v[2:3], v[80:81], v[24:25], v[2:3] op_sel:[0,1,0] op_sel_hi:[1,1,1] neg_lo:[1,0,0] neg_hi:[1,0,0]
	v_pk_fma_f32 v[4:5], v[80:81], v[26:27], v[4:5] op_sel:[0,0,0] op_sel_hi:[1,0,1] neg_lo:[1,0,0] neg_hi:[1,0,0]
	v_pk_fma_f32 v[6:7], v[80:81], v[26:27], v[6:7] op_sel:[0,1,0] op_sel_hi:[1,1,1] neg_lo:[1,0,0] neg_hi:[1,0,0]
	v_pk_fma_f32 v[0:1], v[28:29], v[16:17], v[0:1] op_sel:[0,0,0] op_sel_hi:[1,0,1]
	v_pk_fma_f32 v[2:3], v[28:29], v[16:17], v[2:3] op_sel:[0,1,0] op_sel_hi:[1,1,1]
	v_pk_fma_f32 v[4:5], v[28:29], v[18:19], v[4:5] op_sel:[0,0,0] op_sel_hi:[1,0,1]
	v_pk_fma_f32 v[6:7], v[28:29], v[18:19], v[6:7] op_sel:[0,1,0] op_sel_hi:[1,1,1]
	v_pk_mul_f32 v[88:89], v[8:9], v[0:1] op_sel:[0,0] op_sel_hi:[0,1]
	v_pk_mul_f32 v[90:91], v[8:9], v[2:3] op_sel:[1,0] op_sel_hi:[1,1]
	v_pk_fma_f32 v[88:89], v[10:11], v[4:5], v[88:89] op_sel:[0,0,0] op_sel_hi:[0,1,1]
	v_pk_fma_f32 v[90:91], v[10:11], v[6:7], v[90:91] op_sel:[1,0,0] op_sel_hi:[1,1,1]
	ds_read_b128 v[8:11], v100 offset:33792
	ds_read_b128 v[12:15], v100 offset:34048
	ds_read_b128 v[16:19], v100 offset:34304
	ds_read_b128 v[20:23], v100 offset:34560
	ds_read_b128 v[24:27], v100 offset:34816
	ds_read_b64 v[28:29], v101 offset:35072
	s_waitcnt lgkmcnt(14)
	v_pk_mul_f32 v[80:81], v[44:45], v[0:1] op_sel:[0,0] op_sel_hi:[0,1]
	v_pk_mul_f32 v[82:83], v[44:45], v[2:3] op_sel:[1,0] op_sel_hi:[1,1]
	v_pk_fma_f32 v[80:81], v[46:47], v[4:5], v[80:81] op_sel:[0,0,0] op_sel_hi:[0,1,1]
	v_pk_fma_f32 v[82:83], v[46:47], v[6:7], v[82:83] op_sel:[1,0,0] op_sel_hi:[1,1,1]
	v_pk_add_f32 v[88:89], v[88:89], v[90:91]
	v_pk_add_f32 v[80:81], v[80:81], v[82:83]
	v_pk_mul_f32 v[0:1], v[36:37], v[0:1] op_sel:[0,0] op_sel_hi:[0,1]
	v_pk_mul_f32 v[2:3], v[36:37], v[2:3] op_sel:[1,0] op_sel_hi:[1,1]
	v_add_f32_dpp v80, v80, v80 quad_perm:[1,0,3,2] row_mask:0xf bank_mask:0xf
	v_add_f32_dpp v81, v81, v81 quad_perm:[1,0,3,2] row_mask:0xf bank_mask:0xf
	v_pk_mul_f32 v[4:5], v[38:39], v[4:5] op_sel:[0,0] op_sel_hi:[0,1]
	v_add_f32_dpp v80, v80, v80 quad_perm:[2,3,0,1] row_mask:0xf bank_mask:0xf
	v_add_f32_dpp v81, v81, v81 quad_perm:[2,3,0,1] row_mask:0xf bank_mask:0xf
	v_pk_mul_f32 v[6:7], v[38:39], v[6:7] op_sel:[1,0] op_sel_hi:[1,1]
	v_add_f32_dpp v80, v80, v80 row_half_mirror row_mask:0xf bank_mask:0xf
	v_add_f32_dpp v81, v81, v81 row_half_mirror row_mask:0xf bank_mask:0xf
	ds_write_b64 v102, v[88:89] offset:38912
	v_add_f32_dpp v80, v80, v80 row_mirror row_mask:0xf bank_mask:0xf
	v_add_f32_dpp v81, v81, v81 row_mirror row_mask:0xf bank_mask:0xf
	v_pk_fma_f32 v[0:1], v[80:81], v[48:49], v[0:1] op_sel:[0,0,0] op_sel_hi:[1,0,1] neg_lo:[1,0,0] neg_hi:[1,0,0]
	v_pk_fma_f32 v[2:3], v[80:81], v[48:49], v[2:3] op_sel:[0,1,0] op_sel_hi:[1,1,1] neg_lo:[1,0,0] neg_hi:[1,0,0]
	v_pk_fma_f32 v[4:5], v[80:81], v[50:51], v[4:5] op_sel:[0,0,0] op_sel_hi:[1,0,1] neg_lo:[1,0,0] neg_hi:[1,0,0]
	v_pk_fma_f32 v[6:7], v[80:81], v[50:51], v[6:7] op_sel:[0,1,0] op_sel_hi:[1,1,1] neg_lo:[1,0,0] neg_hi:[1,0,0]
	v_pk_fma_f32 v[0:1], v[52:53], v[40:41], v[0:1] op_sel:[0,0,0] op_sel_hi:[1,0,1]
	v_pk_fma_f32 v[2:3], v[52:53], v[40:41], v[2:3] op_sel:[0,1,0] op_sel_hi:[1,1,1]
	v_pk_fma_f32 v[4:5], v[52:53], v[42:43], v[4:5] op_sel:[0,0,0] op_sel_hi:[1,0,1]
	v_pk_fma_f32 v[6:7], v[52:53], v[42:43], v[6:7] op_sel:[0,1,0] op_sel_hi:[1,1,1]
	v_pk_mul_f32 v[84:85], v[32:33], v[0:1] op_sel:[0,0] op_sel_hi:[0,1]
	v_pk_mul_f32 v[86:87], v[32:33], v[2:3] op_sel:[1,0] op_sel_hi:[1,1]
	v_pk_fma_f32 v[84:85], v[34:35], v[4:5], v[84:85] op_sel:[0,0,0] op_sel_hi:[0,1,1]
	v_pk_fma_f32 v[86:87], v[34:35], v[6:7], v[86:87] op_sel:[1,0,0] op_sel_hi:[1,1,1]
	ds_read_b128 v[32:35], v100 offset:35328
	ds_read_b128 v[36:39], v100 offset:35584
	ds_read_b128 v[40:43], v100 offset:35840
	ds_read_b128 v[44:47], v100 offset:36096
	ds_read_b128 v[48:51], v100 offset:36352
	ds_read_b64 v[52:53], v101 offset:36608
	s_waitcnt lgkmcnt(14)
	v_pk_mul_f32 v[80:81], v[68:69], v[0:1] op_sel:[0,0] op_sel_hi:[0,1]
	v_pk_mul_f32 v[82:83], v[68:69], v[2:3] op_sel:[1,0] op_sel_hi:[1,1]
	v_pk_fma_f32 v[80:81], v[70:71], v[4:5], v[80:81] op_sel:[0,0,0] op_sel_hi:[0,1,1]
	v_pk_fma_f32 v[82:83], v[70:71], v[6:7], v[82:83] op_sel:[1,0,0] op_sel_hi:[1,1,1]
	v_pk_add_f32 v[84:85], v[84:85], v[86:87]
	v_pk_add_f32 v[80:81], v[80:81], v[82:83]
	v_pk_mul_f32 v[0:1], v[60:61], v[0:1] op_sel:[0,0] op_sel_hi:[0,1]
	v_pk_mul_f32 v[2:3], v[60:61], v[2:3] op_sel:[1,0] op_sel_hi:[1,1]
	v_add_f32_dpp v80, v80, v80 quad_perm:[1,0,3,2] row_mask:0xf bank_mask:0xf
	v_add_f32_dpp v81, v81, v81 quad_perm:[1,0,3,2] row_mask:0xf bank_mask:0xf
	v_pk_mul_f32 v[4:5], v[62:63], v[4:5] op_sel:[0,0] op_sel_hi:[0,1]
	v_add_f32_dpp v80, v80, v80 quad_perm:[2,3,0,1] row_mask:0xf bank_mask:0xf
	v_add_f32_dpp v81, v81, v81 quad_perm:[2,3,0,1] row_mask:0xf bank_mask:0xf
	v_pk_mul_f32 v[6:7], v[62:63], v[6:7] op_sel:[1,0] op_sel_hi:[1,1]
	v_add_f32_dpp v80, v80, v80 row_half_mirror row_mask:0xf bank_mask:0xf
	v_add_f32_dpp v81, v81, v81 row_half_mirror row_mask:0xf bank_mask:0xf
	ds_write_b64 v102, v[84:85] offset:40960
	v_add_f32_dpp v80, v80, v80 row_mirror row_mask:0xf bank_mask:0xf
	v_add_f32_dpp v81, v81, v81 row_mirror row_mask:0xf bank_mask:0xf
	v_pk_fma_f32 v[0:1], v[80:81], v[72:73], v[0:1] op_sel:[0,0,0] op_sel_hi:[1,0,1] neg_lo:[1,0,0] neg_hi:[1,0,0]
	v_pk_fma_f32 v[2:3], v[80:81], v[72:73], v[2:3] op_sel:[0,1,0] op_sel_hi:[1,1,1] neg_lo:[1,0,0] neg_hi:[1,0,0]
	v_pk_fma_f32 v[4:5], v[80:81], v[74:75], v[4:5] op_sel:[0,0,0] op_sel_hi:[1,0,1] neg_lo:[1,0,0] neg_hi:[1,0,0]
	v_pk_fma_f32 v[6:7], v[80:81], v[74:75], v[6:7] op_sel:[0,1,0] op_sel_hi:[1,1,1] neg_lo:[1,0,0] neg_hi:[1,0,0]
	v_pk_fma_f32 v[0:1], v[76:77], v[64:65], v[0:1] op_sel:[0,0,0] op_sel_hi:[1,0,1]
	v_pk_fma_f32 v[2:3], v[76:77], v[64:65], v[2:3] op_sel:[0,1,0] op_sel_hi:[1,1,1]
	v_pk_fma_f32 v[4:5], v[76:77], v[66:67], v[4:5] op_sel:[0,0,0] op_sel_hi:[1,0,1]
	v_pk_fma_f32 v[6:7], v[76:77], v[66:67], v[6:7] op_sel:[0,1,0] op_sel_hi:[1,1,1]
	v_pk_mul_f32 v[88:89], v[56:57], v[0:1] op_sel:[0,0] op_sel_hi:[0,1]
	v_pk_mul_f32 v[90:91], v[56:57], v[2:3] op_sel:[1,0] op_sel_hi:[1,1]
	v_pk_fma_f32 v[88:89], v[58:59], v[4:5], v[88:89] op_sel:[0,0,0] op_sel_hi:[0,1,1]
	v_pk_fma_f32 v[90:91], v[58:59], v[6:7], v[90:91] op_sel:[1,0,0] op_sel_hi:[1,1,1]
	ds_read_b128 v[56:59], v100 offset:36864
	ds_read_b128 v[60:63], v100 offset:37120
	ds_read_b128 v[64:67], v100 offset:37376
	ds_read_b128 v[68:71], v100 offset:37632
	ds_read_b128 v[72:75], v100 offset:37888
	ds_read_b64 v[76:77], v101 offset:38144
	s_waitcnt lgkmcnt(14)
	v_pk_mul_f32 v[80:81], v[20:21], v[0:1] op_sel:[0,0] op_sel_hi:[0,1]
	v_pk_mul_f32 v[82:83], v[20:21], v[2:3] op_sel:[1,0] op_sel_hi:[1,1]
	v_pk_fma_f32 v[80:81], v[22:23], v[4:5], v[80:81] op_sel:[0,0,0] op_sel_hi:[0,1,1]
	v_pk_fma_f32 v[82:83], v[22:23], v[6:7], v[82:83] op_sel:[1,0,0] op_sel_hi:[1,1,1]
	v_pk_add_f32 v[88:89], v[88:89], v[90:91]
	v_pk_add_f32 v[80:81], v[80:81], v[82:83]
	v_pk_mul_f32 v[0:1], v[12:13], v[0:1] op_sel:[0,0] op_sel_hi:[0,1]
	v_pk_mul_f32 v[2:3], v[12:13], v[2:3] op_sel:[1,0] op_sel_hi:[1,1]
	v_add_f32_dpp v80, v80, v80 quad_perm:[1,0,3,2] row_mask:0xf bank_mask:0xf
	v_add_f32_dpp v81, v81, v81 quad_perm:[1,0,3,2] row_mask:0xf bank_mask:0xf
	v_pk_mul_f32 v[4:5], v[14:15], v[4:5] op_sel:[0,0] op_sel_hi:[0,1]
	v_add_f32_dpp v80, v80, v80 quad_perm:[2,3,0,1] row_mask:0xf bank_mask:0xf
	v_add_f32_dpp v81, v81, v81 quad_perm:[2,3,0,1] row_mask:0xf bank_mask:0xf
	v_pk_mul_f32 v[6:7], v[14:15], v[6:7] op_sel:[1,0] op_sel_hi:[1,1]
	v_add_f32_dpp v80, v80, v80 row_half_mirror row_mask:0xf bank_mask:0xf
	v_add_f32_dpp v81, v81, v81 row_half_mirror row_mask:0xf bank_mask:0xf
	ds_write_b64 v102, v[88:89] offset:43008
	v_add_f32_dpp v80, v80, v80 row_mirror row_mask:0xf bank_mask:0xf
	v_add_f32_dpp v81, v81, v81 row_mirror row_mask:0xf bank_mask:0xf
	v_pk_fma_f32 v[0:1], v[80:81], v[24:25], v[0:1] op_sel:[0,0,0] op_sel_hi:[1,0,1] neg_lo:[1,0,0] neg_hi:[1,0,0]
	v_pk_fma_f32 v[2:3], v[80:81], v[24:25], v[2:3] op_sel:[0,1,0] op_sel_hi:[1,1,1] neg_lo:[1,0,0] neg_hi:[1,0,0]
	v_pk_fma_f32 v[4:5], v[80:81], v[26:27], v[4:5] op_sel:[0,0,0] op_sel_hi:[1,0,1] neg_lo:[1,0,0] neg_hi:[1,0,0]
	v_pk_fma_f32 v[6:7], v[80:81], v[26:27], v[6:7] op_sel:[0,1,0] op_sel_hi:[1,1,1] neg_lo:[1,0,0] neg_hi:[1,0,0]
	v_pk_fma_f32 v[0:1], v[28:29], v[16:17], v[0:1] op_sel:[0,0,0] op_sel_hi:[1,0,1]
	v_pk_fma_f32 v[2:3], v[28:29], v[16:17], v[2:3] op_sel:[0,1,0] op_sel_hi:[1,1,1]
	v_pk_fma_f32 v[4:5], v[28:29], v[18:19], v[4:5] op_sel:[0,0,0] op_sel_hi:[1,0,1]
	v_pk_fma_f32 v[6:7], v[28:29], v[18:19], v[6:7] op_sel:[0,1,0] op_sel_hi:[1,1,1]
	v_pk_mul_f32 v[84:85], v[8:9], v[0:1] op_sel:[0,0] op_sel_hi:[0,1]
	v_pk_mul_f32 v[86:87], v[8:9], v[2:3] op_sel:[1,0] op_sel_hi:[1,1]
	v_pk_fma_f32 v[84:85], v[10:11], v[4:5], v[84:85] op_sel:[0,0,0] op_sel_hi:[0,1,1]
	v_pk_fma_f32 v[86:87], v[10:11], v[6:7], v[86:87] op_sel:[1,0,0] op_sel_hi:[1,1,1]
	ds_read_b128 v[8:11], v100 offset:38400
	ds_read_b128 v[12:15], v100 offset:38656
	ds_read_b128 v[16:19], v100 offset:38912
	ds_read_b128 v[20:23], v100 offset:39168
	ds_read_b128 v[24:27], v100 offset:39424
	ds_read_b64 v[28:29], v101 offset:39680
	s_waitcnt lgkmcnt(14)
	v_pk_mul_f32 v[80:81], v[44:45], v[0:1] op_sel:[0,0] op_sel_hi:[0,1]
	v_pk_mul_f32 v[82:83], v[44:45], v[2:3] op_sel:[1,0] op_sel_hi:[1,1]
	v_pk_fma_f32 v[80:81], v[46:47], v[4:5], v[80:81] op_sel:[0,0,0] op_sel_hi:[0,1,1]
	v_pk_fma_f32 v[82:83], v[46:47], v[6:7], v[82:83] op_sel:[1,0,0] op_sel_hi:[1,1,1]
	v_pk_add_f32 v[84:85], v[84:85], v[86:87]
	v_pk_add_f32 v[80:81], v[80:81], v[82:83]
	v_pk_mul_f32 v[0:1], v[36:37], v[0:1] op_sel:[0,0] op_sel_hi:[0,1]
	v_pk_mul_f32 v[2:3], v[36:37], v[2:3] op_sel:[1,0] op_sel_hi:[1,1]
	v_add_f32_dpp v80, v80, v80 quad_perm:[1,0,3,2] row_mask:0xf bank_mask:0xf
	v_add_f32_dpp v81, v81, v81 quad_perm:[1,0,3,2] row_mask:0xf bank_mask:0xf
	v_pk_mul_f32 v[4:5], v[38:39], v[4:5] op_sel:[0,0] op_sel_hi:[0,1]
	v_add_f32_dpp v80, v80, v80 quad_perm:[2,3,0,1] row_mask:0xf bank_mask:0xf
	v_add_f32_dpp v81, v81, v81 quad_perm:[2,3,0,1] row_mask:0xf bank_mask:0xf
	v_pk_mul_f32 v[6:7], v[38:39], v[6:7] op_sel:[1,0] op_sel_hi:[1,1]
	v_add_f32_dpp v80, v80, v80 row_half_mirror row_mask:0xf bank_mask:0xf
	v_add_f32_dpp v81, v81, v81 row_half_mirror row_mask:0xf bank_mask:0xf
	ds_write_b64 v102, v[84:85] offset:45056
	v_add_f32_dpp v80, v80, v80 row_mirror row_mask:0xf bank_mask:0xf
	v_add_f32_dpp v81, v81, v81 row_mirror row_mask:0xf bank_mask:0xf
	v_pk_fma_f32 v[0:1], v[80:81], v[48:49], v[0:1] op_sel:[0,0,0] op_sel_hi:[1,0,1] neg_lo:[1,0,0] neg_hi:[1,0,0]
	v_pk_fma_f32 v[2:3], v[80:81], v[48:49], v[2:3] op_sel:[0,1,0] op_sel_hi:[1,1,1] neg_lo:[1,0,0] neg_hi:[1,0,0]
	v_pk_fma_f32 v[4:5], v[80:81], v[50:51], v[4:5] op_sel:[0,0,0] op_sel_hi:[1,0,1] neg_lo:[1,0,0] neg_hi:[1,0,0]
	v_pk_fma_f32 v[6:7], v[80:81], v[50:51], v[6:7] op_sel:[0,1,0] op_sel_hi:[1,1,1] neg_lo:[1,0,0] neg_hi:[1,0,0]
	v_pk_fma_f32 v[0:1], v[52:53], v[40:41], v[0:1] op_sel:[0,0,0] op_sel_hi:[1,0,1]
	v_pk_fma_f32 v[2:3], v[52:53], v[40:41], v[2:3] op_sel:[0,1,0] op_sel_hi:[1,1,1]
	v_pk_fma_f32 v[4:5], v[52:53], v[42:43], v[4:5] op_sel:[0,0,0] op_sel_hi:[1,0,1]
	v_pk_fma_f32 v[6:7], v[52:53], v[42:43], v[6:7] op_sel:[0,1,0] op_sel_hi:[1,1,1]
	v_pk_mul_f32 v[88:89], v[32:33], v[0:1] op_sel:[0,0] op_sel_hi:[0,1]
	v_pk_mul_f32 v[90:91], v[32:33], v[2:3] op_sel:[1,0] op_sel_hi:[1,1]
	v_pk_fma_f32 v[88:89], v[34:35], v[4:5], v[88:89] op_sel:[0,0,0] op_sel_hi:[0,1,1]
	v_pk_fma_f32 v[90:91], v[34:35], v[6:7], v[90:91] op_sel:[1,0,0] op_sel_hi:[1,1,1]
	ds_read_b128 v[32:35], v100 offset:39936
	ds_read_b128 v[36:39], v100 offset:40192
	ds_read_b128 v[40:43], v100 offset:40448
	ds_read_b128 v[44:47], v100 offset:40704
	ds_read_b128 v[48:51], v100 offset:40960
	ds_read_b64 v[52:53], v101 offset:41216
	s_waitcnt lgkmcnt(14)
	v_pk_mul_f32 v[80:81], v[68:69], v[0:1] op_sel:[0,0] op_sel_hi:[0,1]
	v_pk_mul_f32 v[82:83], v[68:69], v[2:3] op_sel:[1,0] op_sel_hi:[1,1]
	v_pk_fma_f32 v[80:81], v[70:71], v[4:5], v[80:81] op_sel:[0,0,0] op_sel_hi:[0,1,1]
	v_pk_fma_f32 v[82:83], v[70:71], v[6:7], v[82:83] op_sel:[1,0,0] op_sel_hi:[1,1,1]
	v_pk_add_f32 v[88:89], v[88:89], v[90:91]
	v_pk_add_f32 v[80:81], v[80:81], v[82:83]
	v_pk_mul_f32 v[0:1], v[60:61], v[0:1] op_sel:[0,0] op_sel_hi:[0,1]
	v_pk_mul_f32 v[2:3], v[60:61], v[2:3] op_sel:[1,0] op_sel_hi:[1,1]
	v_add_f32_dpp v80, v80, v80 quad_perm:[1,0,3,2] row_mask:0xf bank_mask:0xf
	v_add_f32_dpp v81, v81, v81 quad_perm:[1,0,3,2] row_mask:0xf bank_mask:0xf
	v_pk_mul_f32 v[4:5], v[62:63], v[4:5] op_sel:[0,0] op_sel_hi:[0,1]
	v_add_f32_dpp v80, v80, v80 quad_perm:[2,3,0,1] row_mask:0xf bank_mask:0xf
	v_add_f32_dpp v81, v81, v81 quad_perm:[2,3,0,1] row_mask:0xf bank_mask:0xf
	v_pk_mul_f32 v[6:7], v[62:63], v[6:7] op_sel:[1,0] op_sel_hi:[1,1]
	v_add_f32_dpp v80, v80, v80 row_half_mirror row_mask:0xf bank_mask:0xf
	v_add_f32_dpp v81, v81, v81 row_half_mirror row_mask:0xf bank_mask:0xf
	ds_write_b64 v102, v[88:89] offset:47104
	v_add_f32_dpp v80, v80, v80 row_mirror row_mask:0xf bank_mask:0xf
	v_add_f32_dpp v81, v81, v81 row_mirror row_mask:0xf bank_mask:0xf
	v_pk_fma_f32 v[0:1], v[80:81], v[72:73], v[0:1] op_sel:[0,0,0] op_sel_hi:[1,0,1] neg_lo:[1,0,0] neg_hi:[1,0,0]
	v_pk_fma_f32 v[2:3], v[80:81], v[72:73], v[2:3] op_sel:[0,1,0] op_sel_hi:[1,1,1] neg_lo:[1,0,0] neg_hi:[1,0,0]
	v_pk_fma_f32 v[4:5], v[80:81], v[74:75], v[4:5] op_sel:[0,0,0] op_sel_hi:[1,0,1] neg_lo:[1,0,0] neg_hi:[1,0,0]
	v_pk_fma_f32 v[6:7], v[80:81], v[74:75], v[6:7] op_sel:[0,1,0] op_sel_hi:[1,1,1] neg_lo:[1,0,0] neg_hi:[1,0,0]
	v_pk_fma_f32 v[0:1], v[76:77], v[64:65], v[0:1] op_sel:[0,0,0] op_sel_hi:[1,0,1]
	v_pk_fma_f32 v[2:3], v[76:77], v[64:65], v[2:3] op_sel:[0,1,0] op_sel_hi:[1,1,1]
	v_pk_fma_f32 v[4:5], v[76:77], v[66:67], v[4:5] op_sel:[0,0,0] op_sel_hi:[1,0,1]
	v_pk_fma_f32 v[6:7], v[76:77], v[66:67], v[6:7] op_sel:[0,1,0] op_sel_hi:[1,1,1]
	v_pk_mul_f32 v[84:85], v[56:57], v[0:1] op_sel:[0,0] op_sel_hi:[0,1]
	v_pk_mul_f32 v[86:87], v[56:57], v[2:3] op_sel:[1,0] op_sel_hi:[1,1]
	v_pk_fma_f32 v[84:85], v[58:59], v[4:5], v[84:85] op_sel:[0,0,0] op_sel_hi:[0,1,1]
	v_pk_fma_f32 v[86:87], v[58:59], v[6:7], v[86:87] op_sel:[1,0,0] op_sel_hi:[1,1,1]
	ds_read_b128 v[56:59], v100 offset:41472
	ds_read_b128 v[60:63], v100 offset:41728
	ds_read_b128 v[64:67], v100 offset:41984
	ds_read_b128 v[68:71], v100 offset:42240
	ds_read_b128 v[72:75], v100 offset:42496
	ds_read_b64 v[76:77], v101 offset:42752
	s_waitcnt lgkmcnt(14)
	v_pk_mul_f32 v[80:81], v[20:21], v[0:1] op_sel:[0,0] op_sel_hi:[0,1]
	v_pk_mul_f32 v[82:83], v[20:21], v[2:3] op_sel:[1,0] op_sel_hi:[1,1]
	v_pk_fma_f32 v[80:81], v[22:23], v[4:5], v[80:81] op_sel:[0,0,0] op_sel_hi:[0,1,1]
	v_pk_fma_f32 v[82:83], v[22:23], v[6:7], v[82:83] op_sel:[1,0,0] op_sel_hi:[1,1,1]
	v_pk_add_f32 v[84:85], v[84:85], v[86:87]
	v_pk_add_f32 v[80:81], v[80:81], v[82:83]
	v_pk_mul_f32 v[0:1], v[12:13], v[0:1] op_sel:[0,0] op_sel_hi:[0,1]
	v_pk_mul_f32 v[2:3], v[12:13], v[2:3] op_sel:[1,0] op_sel_hi:[1,1]
	v_add_f32_dpp v80, v80, v80 quad_perm:[1,0,3,2] row_mask:0xf bank_mask:0xf
	v_add_f32_dpp v81, v81, v81 quad_perm:[1,0,3,2] row_mask:0xf bank_mask:0xf
	v_pk_mul_f32 v[4:5], v[14:15], v[4:5] op_sel:[0,0] op_sel_hi:[0,1]
	v_add_f32_dpp v80, v80, v80 quad_perm:[2,3,0,1] row_mask:0xf bank_mask:0xf
	v_add_f32_dpp v81, v81, v81 quad_perm:[2,3,0,1] row_mask:0xf bank_mask:0xf
	v_pk_mul_f32 v[6:7], v[14:15], v[6:7] op_sel:[1,0] op_sel_hi:[1,1]
	v_add_f32_dpp v80, v80, v80 row_half_mirror row_mask:0xf bank_mask:0xf
	v_add_f32_dpp v81, v81, v81 row_half_mirror row_mask:0xf bank_mask:0xf
	ds_write_b64 v102, v[84:85] offset:49152
	v_add_f32_dpp v80, v80, v80 row_mirror row_mask:0xf bank_mask:0xf
	v_add_f32_dpp v81, v81, v81 row_mirror row_mask:0xf bank_mask:0xf
	v_pk_fma_f32 v[0:1], v[80:81], v[24:25], v[0:1] op_sel:[0,0,0] op_sel_hi:[1,0,1] neg_lo:[1,0,0] neg_hi:[1,0,0]
	v_pk_fma_f32 v[2:3], v[80:81], v[24:25], v[2:3] op_sel:[0,1,0] op_sel_hi:[1,1,1] neg_lo:[1,0,0] neg_hi:[1,0,0]
	v_pk_fma_f32 v[4:5], v[80:81], v[26:27], v[4:5] op_sel:[0,0,0] op_sel_hi:[1,0,1] neg_lo:[1,0,0] neg_hi:[1,0,0]
	v_pk_fma_f32 v[6:7], v[80:81], v[26:27], v[6:7] op_sel:[0,1,0] op_sel_hi:[1,1,1] neg_lo:[1,0,0] neg_hi:[1,0,0]
	v_pk_fma_f32 v[0:1], v[28:29], v[16:17], v[0:1] op_sel:[0,0,0] op_sel_hi:[1,0,1]
	v_pk_fma_f32 v[2:3], v[28:29], v[16:17], v[2:3] op_sel:[0,1,0] op_sel_hi:[1,1,1]
	v_pk_fma_f32 v[4:5], v[28:29], v[18:19], v[4:5] op_sel:[0,0,0] op_sel_hi:[1,0,1]
	v_pk_fma_f32 v[6:7], v[28:29], v[18:19], v[6:7] op_sel:[0,1,0] op_sel_hi:[1,1,1]
	v_pk_mul_f32 v[88:89], v[8:9], v[0:1] op_sel:[0,0] op_sel_hi:[0,1]
	v_pk_mul_f32 v[90:91], v[8:9], v[2:3] op_sel:[1,0] op_sel_hi:[1,1]
	v_pk_fma_f32 v[88:89], v[10:11], v[4:5], v[88:89] op_sel:[0,0,0] op_sel_hi:[0,1,1]
	v_pk_fma_f32 v[90:91], v[10:11], v[6:7], v[90:91] op_sel:[1,0,0] op_sel_hi:[1,1,1]
	ds_read_b128 v[8:11], v100 offset:43008
	ds_read_b128 v[12:15], v100 offset:43264
	ds_read_b128 v[16:19], v100 offset:43520
	ds_read_b128 v[20:23], v100 offset:43776
	ds_read_b128 v[24:27], v100 offset:44032
	ds_read_b64 v[28:29], v101 offset:44288
	s_waitcnt lgkmcnt(14)
	v_pk_mul_f32 v[80:81], v[44:45], v[0:1] op_sel:[0,0] op_sel_hi:[0,1]
	v_pk_mul_f32 v[82:83], v[44:45], v[2:3] op_sel:[1,0] op_sel_hi:[1,1]
	v_pk_fma_f32 v[80:81], v[46:47], v[4:5], v[80:81] op_sel:[0,0,0] op_sel_hi:[0,1,1]
	v_pk_fma_f32 v[82:83], v[46:47], v[6:7], v[82:83] op_sel:[1,0,0] op_sel_hi:[1,1,1]
	v_pk_add_f32 v[88:89], v[88:89], v[90:91]
	v_pk_add_f32 v[80:81], v[80:81], v[82:83]
	v_pk_mul_f32 v[0:1], v[36:37], v[0:1] op_sel:[0,0] op_sel_hi:[0,1]
	v_pk_mul_f32 v[2:3], v[36:37], v[2:3] op_sel:[1,0] op_sel_hi:[1,1]
	v_add_f32_dpp v80, v80, v80 quad_perm:[1,0,3,2] row_mask:0xf bank_mask:0xf
	v_add_f32_dpp v81, v81, v81 quad_perm:[1,0,3,2] row_mask:0xf bank_mask:0xf
	v_pk_mul_f32 v[4:5], v[38:39], v[4:5] op_sel:[0,0] op_sel_hi:[0,1]
	v_add_f32_dpp v80, v80, v80 quad_perm:[2,3,0,1] row_mask:0xf bank_mask:0xf
	v_add_f32_dpp v81, v81, v81 quad_perm:[2,3,0,1] row_mask:0xf bank_mask:0xf
	v_pk_mul_f32 v[6:7], v[38:39], v[6:7] op_sel:[1,0] op_sel_hi:[1,1]
	v_add_f32_dpp v80, v80, v80 row_half_mirror row_mask:0xf bank_mask:0xf
	v_add_f32_dpp v81, v81, v81 row_half_mirror row_mask:0xf bank_mask:0xf
	ds_write_b64 v102, v[88:89] offset:51200
	v_add_f32_dpp v80, v80, v80 row_mirror row_mask:0xf bank_mask:0xf
	v_add_f32_dpp v81, v81, v81 row_mirror row_mask:0xf bank_mask:0xf
	v_pk_fma_f32 v[0:1], v[80:81], v[48:49], v[0:1] op_sel:[0,0,0] op_sel_hi:[1,0,1] neg_lo:[1,0,0] neg_hi:[1,0,0]
	v_pk_fma_f32 v[2:3], v[80:81], v[48:49], v[2:3] op_sel:[0,1,0] op_sel_hi:[1,1,1] neg_lo:[1,0,0] neg_hi:[1,0,0]
	v_pk_fma_f32 v[4:5], v[80:81], v[50:51], v[4:5] op_sel:[0,0,0] op_sel_hi:[1,0,1] neg_lo:[1,0,0] neg_hi:[1,0,0]
	v_pk_fma_f32 v[6:7], v[80:81], v[50:51], v[6:7] op_sel:[0,1,0] op_sel_hi:[1,1,1] neg_lo:[1,0,0] neg_hi:[1,0,0]
	v_pk_fma_f32 v[0:1], v[52:53], v[40:41], v[0:1] op_sel:[0,0,0] op_sel_hi:[1,0,1]
	v_pk_fma_f32 v[2:3], v[52:53], v[40:41], v[2:3] op_sel:[0,1,0] op_sel_hi:[1,1,1]
	v_pk_fma_f32 v[4:5], v[52:53], v[42:43], v[4:5] op_sel:[0,0,0] op_sel_hi:[1,0,1]
	v_pk_fma_f32 v[6:7], v[52:53], v[42:43], v[6:7] op_sel:[0,1,0] op_sel_hi:[1,1,1]
	v_pk_mul_f32 v[84:85], v[32:33], v[0:1] op_sel:[0,0] op_sel_hi:[0,1]
	v_pk_mul_f32 v[86:87], v[32:33], v[2:3] op_sel:[1,0] op_sel_hi:[1,1]
	v_pk_fma_f32 v[84:85], v[34:35], v[4:5], v[84:85] op_sel:[0,0,0] op_sel_hi:[0,1,1]
	v_pk_fma_f32 v[86:87], v[34:35], v[6:7], v[86:87] op_sel:[1,0,0] op_sel_hi:[1,1,1]
	ds_read_b128 v[32:35], v100 offset:44544
	ds_read_b128 v[36:39], v100 offset:44800
	ds_read_b128 v[40:43], v100 offset:45056
	ds_read_b128 v[44:47], v100 offset:45312
	ds_read_b128 v[48:51], v100 offset:45568
	ds_read_b64 v[52:53], v101 offset:45824
	s_waitcnt lgkmcnt(14)
	v_pk_mul_f32 v[80:81], v[68:69], v[0:1] op_sel:[0,0] op_sel_hi:[0,1]
	v_pk_mul_f32 v[82:83], v[68:69], v[2:3] op_sel:[1,0] op_sel_hi:[1,1]
	v_pk_fma_f32 v[80:81], v[70:71], v[4:5], v[80:81] op_sel:[0,0,0] op_sel_hi:[0,1,1]
	v_pk_fma_f32 v[82:83], v[70:71], v[6:7], v[82:83] op_sel:[1,0,0] op_sel_hi:[1,1,1]
	v_pk_add_f32 v[84:85], v[84:85], v[86:87]
	v_pk_add_f32 v[80:81], v[80:81], v[82:83]
	v_pk_mul_f32 v[0:1], v[60:61], v[0:1] op_sel:[0,0] op_sel_hi:[0,1]
	v_pk_mul_f32 v[2:3], v[60:61], v[2:3] op_sel:[1,0] op_sel_hi:[1,1]
	v_add_f32_dpp v80, v80, v80 quad_perm:[1,0,3,2] row_mask:0xf bank_mask:0xf
	v_add_f32_dpp v81, v81, v81 quad_perm:[1,0,3,2] row_mask:0xf bank_mask:0xf
	v_pk_mul_f32 v[4:5], v[62:63], v[4:5] op_sel:[0,0] op_sel_hi:[0,1]
	v_add_f32_dpp v80, v80, v80 quad_perm:[2,3,0,1] row_mask:0xf bank_mask:0xf
	v_add_f32_dpp v81, v81, v81 quad_perm:[2,3,0,1] row_mask:0xf bank_mask:0xf
	v_pk_mul_f32 v[6:7], v[62:63], v[6:7] op_sel:[1,0] op_sel_hi:[1,1]
	v_add_f32_dpp v80, v80, v80 row_half_mirror row_mask:0xf bank_mask:0xf
	v_add_f32_dpp v81, v81, v81 row_half_mirror row_mask:0xf bank_mask:0xf
	ds_write_b64 v102, v[84:85] offset:53248
	v_add_f32_dpp v80, v80, v80 row_mirror row_mask:0xf bank_mask:0xf
	v_add_f32_dpp v81, v81, v81 row_mirror row_mask:0xf bank_mask:0xf
	v_pk_fma_f32 v[0:1], v[80:81], v[72:73], v[0:1] op_sel:[0,0,0] op_sel_hi:[1,0,1] neg_lo:[1,0,0] neg_hi:[1,0,0]
	v_pk_fma_f32 v[2:3], v[80:81], v[72:73], v[2:3] op_sel:[0,1,0] op_sel_hi:[1,1,1] neg_lo:[1,0,0] neg_hi:[1,0,0]
	v_pk_fma_f32 v[4:5], v[80:81], v[74:75], v[4:5] op_sel:[0,0,0] op_sel_hi:[1,0,1] neg_lo:[1,0,0] neg_hi:[1,0,0]
	v_pk_fma_f32 v[6:7], v[80:81], v[74:75], v[6:7] op_sel:[0,1,0] op_sel_hi:[1,1,1] neg_lo:[1,0,0] neg_hi:[1,0,0]
	v_pk_fma_f32 v[0:1], v[76:77], v[64:65], v[0:1] op_sel:[0,0,0] op_sel_hi:[1,0,1]
	v_pk_fma_f32 v[2:3], v[76:77], v[64:65], v[2:3] op_sel:[0,1,0] op_sel_hi:[1,1,1]
	v_pk_fma_f32 v[4:5], v[76:77], v[66:67], v[4:5] op_sel:[0,0,0] op_sel_hi:[1,0,1]
	v_pk_fma_f32 v[6:7], v[76:77], v[66:67], v[6:7] op_sel:[0,1,0] op_sel_hi:[1,1,1]
	v_pk_mul_f32 v[88:89], v[56:57], v[0:1] op_sel:[0,0] op_sel_hi:[0,1]
	v_pk_mul_f32 v[90:91], v[56:57], v[2:3] op_sel:[1,0] op_sel_hi:[1,1]
	v_pk_fma_f32 v[88:89], v[58:59], v[4:5], v[88:89] op_sel:[0,0,0] op_sel_hi:[0,1,1]
	v_pk_fma_f32 v[90:91], v[58:59], v[6:7], v[90:91] op_sel:[1,0,0] op_sel_hi:[1,1,1]
	ds_read_b128 v[56:59], v100 offset:46080
	ds_read_b128 v[60:63], v100 offset:46336
	ds_read_b128 v[64:67], v100 offset:46592
	ds_read_b128 v[68:71], v100 offset:46848
	ds_read_b128 v[72:75], v100 offset:47104
	ds_read_b64 v[76:77], v101 offset:47360
	s_waitcnt lgkmcnt(14)
	v_pk_mul_f32 v[80:81], v[20:21], v[0:1] op_sel:[0,0] op_sel_hi:[0,1]
	v_pk_mul_f32 v[82:83], v[20:21], v[2:3] op_sel:[1,0] op_sel_hi:[1,1]
	v_pk_fma_f32 v[80:81], v[22:23], v[4:5], v[80:81] op_sel:[0,0,0] op_sel_hi:[0,1,1]
	v_pk_fma_f32 v[82:83], v[22:23], v[6:7], v[82:83] op_sel:[1,0,0] op_sel_hi:[1,1,1]
	v_pk_add_f32 v[88:89], v[88:89], v[90:91]
	v_pk_add_f32 v[80:81], v[80:81], v[82:83]
	v_pk_mul_f32 v[0:1], v[12:13], v[0:1] op_sel:[0,0] op_sel_hi:[0,1]
	v_pk_mul_f32 v[2:3], v[12:13], v[2:3] op_sel:[1,0] op_sel_hi:[1,1]
	v_add_f32_dpp v80, v80, v80 quad_perm:[1,0,3,2] row_mask:0xf bank_mask:0xf
	v_add_f32_dpp v81, v81, v81 quad_perm:[1,0,3,2] row_mask:0xf bank_mask:0xf
	v_pk_mul_f32 v[4:5], v[14:15], v[4:5] op_sel:[0,0] op_sel_hi:[0,1]
	v_add_f32_dpp v80, v80, v80 quad_perm:[2,3,0,1] row_mask:0xf bank_mask:0xf
	v_add_f32_dpp v81, v81, v81 quad_perm:[2,3,0,1] row_mask:0xf bank_mask:0xf
	v_pk_mul_f32 v[6:7], v[14:15], v[6:7] op_sel:[1,0] op_sel_hi:[1,1]
	v_add_f32_dpp v80, v80, v80 row_half_mirror row_mask:0xf bank_mask:0xf
	v_add_f32_dpp v81, v81, v81 row_half_mirror row_mask:0xf bank_mask:0xf
	ds_write_b64 v102, v[88:89] offset:55296
	v_add_f32_dpp v80, v80, v80 row_mirror row_mask:0xf bank_mask:0xf
	v_add_f32_dpp v81, v81, v81 row_mirror row_mask:0xf bank_mask:0xf
	v_pk_fma_f32 v[0:1], v[80:81], v[24:25], v[0:1] op_sel:[0,0,0] op_sel_hi:[1,0,1] neg_lo:[1,0,0] neg_hi:[1,0,0]
	v_pk_fma_f32 v[2:3], v[80:81], v[24:25], v[2:3] op_sel:[0,1,0] op_sel_hi:[1,1,1] neg_lo:[1,0,0] neg_hi:[1,0,0]
	v_pk_fma_f32 v[4:5], v[80:81], v[26:27], v[4:5] op_sel:[0,0,0] op_sel_hi:[1,0,1] neg_lo:[1,0,0] neg_hi:[1,0,0]
	v_pk_fma_f32 v[6:7], v[80:81], v[26:27], v[6:7] op_sel:[0,1,0] op_sel_hi:[1,1,1] neg_lo:[1,0,0] neg_hi:[1,0,0]
	v_pk_fma_f32 v[0:1], v[28:29], v[16:17], v[0:1] op_sel:[0,0,0] op_sel_hi:[1,0,1]
	v_pk_fma_f32 v[2:3], v[28:29], v[16:17], v[2:3] op_sel:[0,1,0] op_sel_hi:[1,1,1]
	v_pk_fma_f32 v[4:5], v[28:29], v[18:19], v[4:5] op_sel:[0,0,0] op_sel_hi:[1,0,1]
	v_pk_fma_f32 v[6:7], v[28:29], v[18:19], v[6:7] op_sel:[0,1,0] op_sel_hi:[1,1,1]
	v_pk_mul_f32 v[84:85], v[8:9], v[0:1] op_sel:[0,0] op_sel_hi:[0,1]
	v_pk_mul_f32 v[86:87], v[8:9], v[2:3] op_sel:[1,0] op_sel_hi:[1,1]
	v_pk_fma_f32 v[84:85], v[10:11], v[4:5], v[84:85] op_sel:[0,0,0] op_sel_hi:[0,1,1]
	v_pk_fma_f32 v[86:87], v[10:11], v[6:7], v[86:87] op_sel:[1,0,0] op_sel_hi:[1,1,1]
	ds_read_b128 v[8:11], v100 offset:47616
	ds_read_b128 v[12:15], v100 offset:47872
	ds_read_b128 v[16:19], v100 offset:48128
	ds_read_b128 v[20:23], v100 offset:48384
	ds_read_b128 v[24:27], v100 offset:48640
	ds_read_b64 v[28:29], v101 offset:48896
	s_waitcnt lgkmcnt(14)
	v_pk_mul_f32 v[80:81], v[44:45], v[0:1] op_sel:[0,0] op_sel_hi:[0,1]
	v_pk_mul_f32 v[82:83], v[44:45], v[2:3] op_sel:[1,0] op_sel_hi:[1,1]
	v_pk_fma_f32 v[80:81], v[46:47], v[4:5], v[80:81] op_sel:[0,0,0] op_sel_hi:[0,1,1]
	v_pk_fma_f32 v[82:83], v[46:47], v[6:7], v[82:83] op_sel:[1,0,0] op_sel_hi:[1,1,1]
	v_pk_add_f32 v[84:85], v[84:85], v[86:87]
	v_pk_add_f32 v[80:81], v[80:81], v[82:83]
	v_pk_mul_f32 v[0:1], v[36:37], v[0:1] op_sel:[0,0] op_sel_hi:[0,1]
	v_pk_mul_f32 v[2:3], v[36:37], v[2:3] op_sel:[1,0] op_sel_hi:[1,1]
	v_add_f32_dpp v80, v80, v80 quad_perm:[1,0,3,2] row_mask:0xf bank_mask:0xf
	v_add_f32_dpp v81, v81, v81 quad_perm:[1,0,3,2] row_mask:0xf bank_mask:0xf
	v_pk_mul_f32 v[4:5], v[38:39], v[4:5] op_sel:[0,0] op_sel_hi:[0,1]
	v_add_f32_dpp v80, v80, v80 quad_perm:[2,3,0,1] row_mask:0xf bank_mask:0xf
	v_add_f32_dpp v81, v81, v81 quad_perm:[2,3,0,1] row_mask:0xf bank_mask:0xf
	v_pk_mul_f32 v[6:7], v[38:39], v[6:7] op_sel:[1,0] op_sel_hi:[1,1]
	v_add_f32_dpp v80, v80, v80 row_half_mirror row_mask:0xf bank_mask:0xf
	v_add_f32_dpp v81, v81, v81 row_half_mirror row_mask:0xf bank_mask:0xf
	ds_write_b64 v102, v[84:85] offset:57344
	v_add_f32_dpp v80, v80, v80 row_mirror row_mask:0xf bank_mask:0xf
	v_add_f32_dpp v81, v81, v81 row_mirror row_mask:0xf bank_mask:0xf
	v_pk_fma_f32 v[0:1], v[80:81], v[48:49], v[0:1] op_sel:[0,0,0] op_sel_hi:[1,0,1] neg_lo:[1,0,0] neg_hi:[1,0,0]
	v_pk_fma_f32 v[2:3], v[80:81], v[48:49], v[2:3] op_sel:[0,1,0] op_sel_hi:[1,1,1] neg_lo:[1,0,0] neg_hi:[1,0,0]
	v_pk_fma_f32 v[4:5], v[80:81], v[50:51], v[4:5] op_sel:[0,0,0] op_sel_hi:[1,0,1] neg_lo:[1,0,0] neg_hi:[1,0,0]
	v_pk_fma_f32 v[6:7], v[80:81], v[50:51], v[6:7] op_sel:[0,1,0] op_sel_hi:[1,1,1] neg_lo:[1,0,0] neg_hi:[1,0,0]
	v_pk_fma_f32 v[0:1], v[52:53], v[40:41], v[0:1] op_sel:[0,0,0] op_sel_hi:[1,0,1]
	v_pk_fma_f32 v[2:3], v[52:53], v[40:41], v[2:3] op_sel:[0,1,0] op_sel_hi:[1,1,1]
	v_pk_fma_f32 v[4:5], v[52:53], v[42:43], v[4:5] op_sel:[0,0,0] op_sel_hi:[1,0,1]
	v_pk_fma_f32 v[6:7], v[52:53], v[42:43], v[6:7] op_sel:[0,1,0] op_sel_hi:[1,1,1]
	v_pk_mul_f32 v[88:89], v[32:33], v[0:1] op_sel:[0,0] op_sel_hi:[0,1]
	v_pk_mul_f32 v[90:91], v[32:33], v[2:3] op_sel:[1,0] op_sel_hi:[1,1]
	v_pk_fma_f32 v[88:89], v[34:35], v[4:5], v[88:89] op_sel:[0,0,0] op_sel_hi:[0,1,1]
	v_pk_fma_f32 v[90:91], v[34:35], v[6:7], v[90:91] op_sel:[1,0,0] op_sel_hi:[1,1,1]
	s_waitcnt lgkmcnt(8)
	v_pk_mul_f32 v[80:81], v[68:69], v[0:1] op_sel:[0,0] op_sel_hi:[0,1]
	v_pk_mul_f32 v[82:83], v[68:69], v[2:3] op_sel:[1,0] op_sel_hi:[1,1]
	v_pk_fma_f32 v[80:81], v[70:71], v[4:5], v[80:81] op_sel:[0,0,0] op_sel_hi:[0,1,1]
	v_pk_fma_f32 v[82:83], v[70:71], v[6:7], v[82:83] op_sel:[1,0,0] op_sel_hi:[1,1,1]
	v_pk_add_f32 v[88:89], v[88:89], v[90:91]
	v_pk_add_f32 v[80:81], v[80:81], v[82:83]
	v_pk_mul_f32 v[0:1], v[60:61], v[0:1] op_sel:[0,0] op_sel_hi:[0,1]
	v_pk_mul_f32 v[2:3], v[60:61], v[2:3] op_sel:[1,0] op_sel_hi:[1,1]
	v_add_f32_dpp v80, v80, v80 quad_perm:[1,0,3,2] row_mask:0xf bank_mask:0xf
	v_add_f32_dpp v81, v81, v81 quad_perm:[1,0,3,2] row_mask:0xf bank_mask:0xf
	v_pk_mul_f32 v[4:5], v[62:63], v[4:5] op_sel:[0,0] op_sel_hi:[0,1]
	v_add_f32_dpp v80, v80, v80 quad_perm:[2,3,0,1] row_mask:0xf bank_mask:0xf
	v_add_f32_dpp v81, v81, v81 quad_perm:[2,3,0,1] row_mask:0xf bank_mask:0xf
	v_pk_mul_f32 v[6:7], v[62:63], v[6:7] op_sel:[1,0] op_sel_hi:[1,1]
	v_add_f32_dpp v80, v80, v80 row_half_mirror row_mask:0xf bank_mask:0xf
	v_add_f32_dpp v81, v81, v81 row_half_mirror row_mask:0xf bank_mask:0xf
	ds_write_b64 v102, v[88:89] offset:59392
	v_add_f32_dpp v80, v80, v80 row_mirror row_mask:0xf bank_mask:0xf
	v_add_f32_dpp v81, v81, v81 row_mirror row_mask:0xf bank_mask:0xf
	v_pk_fma_f32 v[0:1], v[80:81], v[72:73], v[0:1] op_sel:[0,0,0] op_sel_hi:[1,0,1] neg_lo:[1,0,0] neg_hi:[1,0,0]
	v_pk_fma_f32 v[2:3], v[80:81], v[72:73], v[2:3] op_sel:[0,1,0] op_sel_hi:[1,1,1] neg_lo:[1,0,0] neg_hi:[1,0,0]
	v_pk_fma_f32 v[4:5], v[80:81], v[74:75], v[4:5] op_sel:[0,0,0] op_sel_hi:[1,0,1] neg_lo:[1,0,0] neg_hi:[1,0,0]
	v_pk_fma_f32 v[6:7], v[80:81], v[74:75], v[6:7] op_sel:[0,1,0] op_sel_hi:[1,1,1] neg_lo:[1,0,0] neg_hi:[1,0,0]
	v_pk_fma_f32 v[0:1], v[76:77], v[64:65], v[0:1] op_sel:[0,0,0] op_sel_hi:[1,0,1]
	v_pk_fma_f32 v[2:3], v[76:77], v[64:65], v[2:3] op_sel:[0,1,0] op_sel_hi:[1,1,1]
	v_pk_fma_f32 v[4:5], v[76:77], v[66:67], v[4:5] op_sel:[0,0,0] op_sel_hi:[1,0,1]
	v_pk_fma_f32 v[6:7], v[76:77], v[66:67], v[6:7] op_sel:[0,1,0] op_sel_hi:[1,1,1]
	v_pk_mul_f32 v[84:85], v[56:57], v[0:1] op_sel:[0,0] op_sel_hi:[0,1]
	v_pk_mul_f32 v[86:87], v[56:57], v[2:3] op_sel:[1,0] op_sel_hi:[1,1]
	v_pk_fma_f32 v[84:85], v[58:59], v[4:5], v[84:85] op_sel:[0,0,0] op_sel_hi:[0,1,1]
	v_pk_fma_f32 v[86:87], v[58:59], v[6:7], v[86:87] op_sel:[1,0,0] op_sel_hi:[1,1,1]
	s_waitcnt lgkmcnt(2)
	v_pk_mul_f32 v[80:81], v[20:21], v[0:1] op_sel:[0,0] op_sel_hi:[0,1]
	v_pk_mul_f32 v[82:83], v[20:21], v[2:3] op_sel:[1,0] op_sel_hi:[1,1]
	v_pk_fma_f32 v[80:81], v[22:23], v[4:5], v[80:81] op_sel:[0,0,0] op_sel_hi:[0,1,1]
	v_pk_fma_f32 v[82:83], v[22:23], v[6:7], v[82:83] op_sel:[1,0,0] op_sel_hi:[1,1,1]
	v_pk_add_f32 v[84:85], v[84:85], v[86:87]
	v_pk_add_f32 v[80:81], v[80:81], v[82:83]
	v_pk_mul_f32 v[0:1], v[12:13], v[0:1] op_sel:[0,0] op_sel_hi:[0,1]
	v_pk_mul_f32 v[2:3], v[12:13], v[2:3] op_sel:[1,0] op_sel_hi:[1,1]
	v_add_f32_dpp v80, v80, v80 quad_perm:[1,0,3,2] row_mask:0xf bank_mask:0xf
	v_add_f32_dpp v81, v81, v81 quad_perm:[1,0,3,2] row_mask:0xf bank_mask:0xf
	v_pk_mul_f32 v[4:5], v[14:15], v[4:5] op_sel:[0,0] op_sel_hi:[0,1]
	v_add_f32_dpp v80, v80, v80 quad_perm:[2,3,0,1] row_mask:0xf bank_mask:0xf
	v_add_f32_dpp v81, v81, v81 quad_perm:[2,3,0,1] row_mask:0xf bank_mask:0xf
	v_pk_mul_f32 v[6:7], v[14:15], v[6:7] op_sel:[1,0] op_sel_hi:[1,1]
	v_add_f32_dpp v80, v80, v80 row_half_mirror row_mask:0xf bank_mask:0xf
	v_add_f32_dpp v81, v81, v81 row_half_mirror row_mask:0xf bank_mask:0xf
	ds_write_b64 v102, v[84:85] offset:61440
	v_add_f32_dpp v80, v80, v80 row_mirror row_mask:0xf bank_mask:0xf
	v_add_f32_dpp v81, v81, v81 row_mirror row_mask:0xf bank_mask:0xf
	v_pk_fma_f32 v[0:1], v[80:81], v[24:25], v[0:1] op_sel:[0,0,0] op_sel_hi:[1,0,1] neg_lo:[1,0,0] neg_hi:[1,0,0]
	v_pk_fma_f32 v[2:3], v[80:81], v[24:25], v[2:3] op_sel:[0,1,0] op_sel_hi:[1,1,1] neg_lo:[1,0,0] neg_hi:[1,0,0]
	v_pk_fma_f32 v[4:5], v[80:81], v[26:27], v[4:5] op_sel:[0,0,0] op_sel_hi:[1,0,1] neg_lo:[1,0,0] neg_hi:[1,0,0]
	v_pk_fma_f32 v[6:7], v[80:81], v[26:27], v[6:7] op_sel:[0,1,0] op_sel_hi:[1,1,1] neg_lo:[1,0,0] neg_hi:[1,0,0]
	v_pk_fma_f32 v[0:1], v[28:29], v[16:17], v[0:1] op_sel:[0,0,0] op_sel_hi:[1,0,1]
	v_pk_fma_f32 v[2:3], v[28:29], v[16:17], v[2:3] op_sel:[0,1,0] op_sel_hi:[1,1,1]
	v_pk_fma_f32 v[4:5], v[28:29], v[18:19], v[4:5] op_sel:[0,0,0] op_sel_hi:[1,0,1]
	v_pk_fma_f32 v[6:7], v[28:29], v[18:19], v[6:7] op_sel:[0,1,0] op_sel_hi:[1,1,1]
	v_pk_mul_f32 v[88:89], v[8:9], v[0:1] op_sel:[0,0] op_sel_hi:[0,1]
	v_pk_mul_f32 v[90:91], v[8:9], v[2:3] op_sel:[1,0] op_sel_hi:[1,1]
	v_pk_fma_f32 v[88:89], v[10:11], v[4:5], v[88:89] op_sel:[0,0,0] op_sel_hi:[0,1,1]
	v_pk_fma_f32 v[90:91], v[10:11], v[6:7], v[90:91] op_sel:[1,0,0] op_sel_hi:[1,1,1]
	s_nop 0
	v_pk_add_f32 v[88:89], v[88:89], v[90:91]
	s_nop 0
	ds_write_b64 v102, v[88:89] offset:63488
	s_waitcnt lgkmcnt(0)
	s_barrier
	s_add_i32 s16, s16, 2
	s_cmp_lt_u32 s16, 0x100
	s_cbranch_scc1 .Lrc_loop
	ds_read_b128 v[56:59], v103 offset:32768
	v_xor_b32_e32 v93, 16, v103
	ds_read_b128 v[60:63], v93 offset:32768
	v_xor_b32_e32 v93, 32, v103
	ds_read_b128 v[64:67], v93 offset:32768
	v_xor_b32_e32 v93, 48, v103
	ds_read_b128 v[68:71], v93 offset:32768
	v_xor_b32_e32 v93, 64, v103
	ds_read_b128 v[72:75], v93 offset:32768
	v_xor_b32_e32 v93, 80, v103
	ds_read_b128 v[76:79], v93 offset:32768
	v_xor_b32_e32 v93, 96, v103
	ds_read_b128 v[80:83], v93 offset:32768
	v_xor_b32_e32 v93, 112, v103
	ds_read_b128 v[84:87], v93 offset:32768
	s_waitcnt lgkmcnt(0)
	v_pk_add_f32 v[56:57], v[56:57], v[58:59]
	v_pk_add_f32 v[60:61], v[60:61], v[62:63]
	v_pk_add_f32 v[64:65], v[64:65], v[66:67]
	v_pk_add_f32 v[68:69], v[68:69], v[70:71]
	v_pk_add_f32 v[72:73], v[72:73], v[74:75]
	v_pk_add_f32 v[76:77], v[76:77], v[78:79]
	v_pk_add_f32 v[80:81], v[80:81], v[82:83]
	v_pk_add_f32 v[84:85], v[84:85], v[86:87]
	v_pk_add_f32 v[56:57], v[56:57], v[60:61]
	v_pk_add_f32 v[64:65], v[64:65], v[68:69]
	v_pk_add_f32 v[72:73], v[72:73], v[76:77]
	v_pk_add_f32 v[80:81], v[80:81], v[84:85]
	v_pk_add_f32 v[56:57], v[56:57], v[64:65]
	v_pk_add_f32 v[72:73], v[72:73], v[80:81]
	s_nop 0
	v_pk_add_f32 v[56:57], v[56:57], v[72:73]
	s_nop 0
	v_cvt_pk_bf16_f32 v92, v56, v57
	global_store_dword v[104:105], v92, off
	v_lshl_add_u64 v[104:105], v[104:105], 0, s[52:53]
	s_waitcnt vmcnt(0) lgkmcnt(0)
	s_setprio 0

.LBB0_1080:
	s_andn2_b64 vcc, exec, s[0:1]
	s_cbranch_vccnz .LBB0_1123
	s_bfe_u32 s19, s2, 0x20004
	s_bfe_u32 s18, s2, 0x20002
	s_and_b32 s34, s2, 3
	s_cmp_lt_u32 s2, 64
	s_cselect_b64 s[10:11], -1, 0
	s_cmp_gt_u32 s2, 63
	s_movk_i32 s12, 0x100
	s_cselect_b64 s[0:1], -1, 0
	v_cmp_gt_u32_e32 vcc, s12, v164
	s_and_saveexec_b64 s[12:13], vcc
	s_xor_b64 s[12:13], exec, s[12:13]
	s_cbranch_execz .LBB0_1087
	s_setprio 3
	s_lshr_b32 s10, s2, 6
	s_bfe_u32 s11, s2, 0x20004
	s_bfe_u32 s17, s2, 0x20002
	s_and_b32 s18, s2, 3
	s_add_u32 s22, s28, 0xdc00000
	s_addc_u32 s23, s29, 0
	s_cmp_eq_u32 s10, 0
	s_cselect_b32 s22, s22, s26
	s_cselect_b32 s23, s23, s27
	s_mov_b32 s14, 0x8000
	s_mov_b32 s15, 0
	s_mov_b32 s55, 1
	s_lshl_b32 s56, s11, 12
	s_cmp_eq_u32 s10, 0
	s_cbranch_scc1 .Lhc_fwd
	s_mov_b32 s14, 0xffff8000
	s_mov_b32 s15, -1
	s_mov_b32 s55, -1
	s_add_u32 s56, s56, 0xfff
.Lhc_fwd:
	s_lshl_b32 s57, s18, 5
	s_lshl_b32 s58, s17, 7
	s_add_u32 s57, s57, s58
	v_and_b32_e32 v106, 15, v164
	v_lshrrev_b32_e32 v107, 4, v164
	v_lshrrev_b32_e32 v100, 3, v106
	v_lshlrev_b32_e32 v100, 4, v100
	v_lshl_add_u32 v100, v106, 5, v100
	v_lshlrev_b32_e32 v101, 3, v107
	v_lshlrev_b32_e32 v102, 3, v164
	v_add_u32_e32 v102, 37888, v102
	v_lshlrev_b32_e32 v103, 7, v164
	v_add_u32_e32 v103, 37888, v103
	v_bfe_u32 v89, v164, 1, 3
	v_lshl_or_b32 v103, v89, 4, v103
	v_mul_lo_u32 v108, v107, s55
	v_add_u32_e32 v108, s56, v108
	v_lshlrev_b32_e32 v108, 11, v108
	v_lshl_add_u32 v109, v106, 1, s57
	v_lshl_add_u32 v108, v109, 1, v108
	v_mov_b32_e32 v109, 0
	v_lshl_add_u64 v[104:105], v[108:109], 0, s[22:23]
	v_mov_b32_e32 v0, 0
	v_mov_b32_e32 v1, 0
	v_mov_b32_e32 v2, 0
	v_mov_b32_e32 v3, 0
	v_mov_b32_e32 v4, 0
	v_mov_b32_e32 v5, 0
	v_mov_b32_e32 v6, 0
	v_mov_b32_e32 v7, 0
	v_mov_b32_e32 v8, 0
	v_mov_b32_e32 v9, 0
	v_mov_b32_e32 v10, 0
	v_mov_b32_e32 v11, 0
	v_mov_b32_e32 v12, 0
	v_mov_b32_e32 v13, 0
	v_mov_b32_e32 v14, 0
	v_mov_b32_e32 v15, 0
	s_mov_b32 s16, 0
	s_barrier
.Lhc_loop:
	ds_read_b128 v[16:19], v100 offset:0
	ds_read_b128 v[20:23], v100 offset:16
	ds_read_b128 v[24:27], v100 offset:528
	ds_read_b128 v[28:31], v100 offset:544
	ds_read_b64 v[32:33], v101 offset:33792
	ds_read_b128 v[36:39], v100 offset:1056
	ds_read_b128 v[40:43], v100 offset:1072
	ds_read_b128 v[44:47], v100 offset:1584
	ds_read_b128 v[48:51], v100 offset:1600
	ds_read_b64 v[52:53], v101 offset:33920
	ds_read_b128 v[56:59], v103 offset:32768
	v_xor_b32_e32 v89, 16, v103
	ds_read_b128 v[60:63], v89 offset:32768
	v_xor_b32_e32 v89, 32, v103
	ds_read_b128 v[64:67], v89 offset:32768
	v_xor_b32_e32 v89, 48, v103
	ds_read_b128 v[68:71], v89 offset:32768
	v_xor_b32_e32 v89, 64, v103
	ds_read_b128 v[72:75], v89 offset:32768
	v_xor_b32_e32 v89, 80, v103
	ds_read_b128 v[76:79], v89 offset:32768
	v_xor_b32_e32 v89, 96, v103
	ds_read_b128 v[80:83], v89 offset:32768
	v_xor_b32_e32 v89, 112, v103
	ds_read_b128 v[84:87], v89 offset:32768
	s_waitcnt lgkmcnt(0)
	v_pk_add_f32 v[56:57], v[56:57], v[58:59]
	v_pk_add_f32 v[60:61], v[60:61], v[62:63]
	v_pk_add_f32 v[64:65], v[64:65], v[66:67]
	v_pk_add_f32 v[68:69], v[68:69], v[70:71]
	v_pk_add_f32 v[72:73], v[72:73], v[74:75]
	v_pk_add_f32 v[76:77], v[76:77], v[78:79]
	v_pk_add_f32 v[80:81], v[80:81], v[82:83]
	v_pk_add_f32 v[84:85], v[84:85], v[86:87]
	v_pk_add_f32 v[56:57], v[56:57], v[60:61]
	v_pk_add_f32 v[64:65], v[64:65], v[68:69]
	v_pk_add_f32 v[72:73], v[72:73], v[76:77]
	v_pk_add_f32 v[80:81], v[80:81], v[84:85]
	v_pk_add_f32 v[56:57], v[56:57], v[64:65]
	v_pk_add_f32 v[72:73], v[72:73], v[80:81]
	s_nop 0
	v_pk_add_f32 v[56:57], v[56:57], v[72:73]
	s_nop 0
	v_cvt_pk_bf16_f32 v88, v56, v57
	s_cmp_eq_u32 s16, 0
	s_cselect_b64 s[46:47], 0, -1
	s_cselect_b64 s[50:51], 0, s[14:15]
	s_mov_b64 exec, s[46:47]
	global_store_dword v[104:105], v88, off
	s_mov_b64 exec, -1
	v_lshl_add_u64 v[104:105], v[104:105], 0, s[50:51]
	ds_read_b128 v[56:59], v100 offset:2112
	ds_read_b128 v[60:63], v100 offset:2128
	ds_read_b128 v[64:67], v100 offset:2640
	ds_read_b128 v[68:71], v100 offset:2656
	ds_read_b64 v[72:73], v101 offset:34048
	v_pk_add_f32 v[76:77], v[0:1], v[32:33] neg_lo:[0,1] neg_hi:[0,1]
	v_pk_add_f32 v[78:79], v[2:3], v[32:33] neg_lo:[0,1] neg_hi:[0,1]
	v_pk_add_f32 v[80:81], v[4:5], v[32:33] neg_lo:[0,1] neg_hi:[0,1]
	v_pk_add_f32 v[82:83], v[6:7], v[32:33] neg_lo:[0,1] neg_hi:[0,1]
	v_pk_add_f32 v[84:85], v[8:9], v[32:33] neg_lo:[0,1] neg_hi:[0,1]
	v_pk_add_f32 v[86:87], v[10:11], v[32:33] neg_lo:[0,1] neg_hi:[0,1]
	v_pk_add_f32 v[88:89], v[12:13], v[32:33] neg_lo:[0,1] neg_hi:[0,1]
	v_pk_add_f32 v[90:91], v[14:15], v[32:33] neg_lo:[0,1] neg_hi:[0,1]
	v_pk_fma_f32 v[0:1], v[16:17], v[76:77], v[32:33] op_sel:[0,0,0] op_sel_hi:[0,1,1]
	v_pk_fma_f32 v[2:3], v[16:17], v[78:79], v[32:33] op_sel:[1,0,0] op_sel_hi:[1,1,1]
	v_pk_fma_f32 v[4:5], v[18:19], v[80:81], v[32:33] op_sel:[0,0,0] op_sel_hi:[0,1,1]
	v_pk_fma_f32 v[6:7], v[18:19], v[82:83], v[32:33] op_sel:[1,0,0] op_sel_hi:[1,1,1]
	v_pk_fma_f32 v[8:9], v[20:21], v[84:85], v[32:33] op_sel:[0,0,0] op_sel_hi:[0,1,1]
	v_pk_fma_f32 v[10:11], v[20:21], v[86:87], v[32:33] op_sel:[1,0,0] op_sel_hi:[1,1,1]
	v_pk_fma_f32 v[12:13], v[22:23], v[88:89], v[32:33] op_sel:[0,0,0] op_sel_hi:[0,1,1]
	v_pk_fma_f32 v[14:15], v[22:23], v[90:91], v[32:33] op_sel:[1,0,0] op_sel_hi:[1,1,1]
	v_pk_mul_f32 v[92:93], v[24:25], v[0:1] op_sel:[0,0] op_sel_hi:[0,1]
	v_pk_mul_f32 v[94:95], v[24:25], v[2:3] op_sel:[1,0] op_sel_hi:[1,1]
	v_pk_fma_f32 v[92:93], v[26:27], v[4:5], v[92:93] op_sel:[0,0,0] op_sel_hi:[0,1,1]
	v_pk_fma_f32 v[94:95], v[26:27], v[6:7], v[94:95] op_sel:[1,0,0] op_sel_hi:[1,1,1]
	v_pk_fma_f32 v[92:93], v[28:29], v[8:9], v[92:93] op_sel:[0,0,0] op_sel_hi:[0,1,1]
	v_pk_fma_f32 v[94:95], v[28:29], v[10:11], v[94:95] op_sel:[1,0,0] op_sel_hi:[1,1,1]
	v_pk_fma_f32 v[92:93], v[30:31], v[12:13], v[92:93] op_sel:[0,0,0] op_sel_hi:[0,1,1]
	v_pk_fma_f32 v[94:95], v[30:31], v[14:15], v[94:95] op_sel:[1,0,0] op_sel_hi:[1,1,1]
	ds_read_b128 v[16:19], v100 offset:3168
	ds_read_b128 v[20:23], v100 offset:3184
	ds_read_b128 v[24:27], v100 offset:3696
	ds_read_b128 v[28:31], v100 offset:3712
	ds_read_b64 v[32:33], v101 offset:34176
	v_pk_add_f32 v[76:77], v[0:1], v[52:53] neg_lo:[0,1] neg_hi:[0,1]
	v_pk_add_f32 v[78:79], v[2:3], v[52:53] neg_lo:[0,1] neg_hi:[0,1]
	v_pk_add_f32 v[92:93], v[92:93], v[94:95]
	v_pk_add_f32 v[80:81], v[4:5], v[52:53] neg_lo:[0,1] neg_hi:[0,1]
	v_pk_add_f32 v[82:83], v[6:7], v[52:53] neg_lo:[0,1] neg_hi:[0,1]
	v_pk_add_f32 v[84:85], v[8:9], v[52:53] neg_lo:[0,1] neg_hi:[0,1]
	ds_write_b64 v102, v[92:93] offset:0
	v_pk_add_f32 v[86:87], v[10:11], v[52:53] neg_lo:[0,1] neg_hi:[0,1]
	v_pk_add_f32 v[88:89], v[12:13], v[52:53] neg_lo:[0,1] neg_hi:[0,1]
	v_pk_add_f32 v[90:91], v[14:15], v[52:53] neg_lo:[0,1] neg_hi:[0,1]
	v_pk_fma_f32 v[0:1], v[36:37], v[76:77], v[52:53] op_sel:[0,0,0] op_sel_hi:[0,1,1]
	v_pk_fma_f32 v[2:3], v[36:37], v[78:79], v[52:53] op_sel:[1,0,0] op_sel_hi:[1,1,1]
	v_pk_fma_f32 v[4:5], v[38:39], v[80:81], v[52:53] op_sel:[0,0,0] op_sel_hi:[0,1,1]
	v_pk_fma_f32 v[6:7], v[38:39], v[82:83], v[52:53] op_sel:[1,0,0] op_sel_hi:[1,1,1]
	v_pk_fma_f32 v[8:9], v[40:41], v[84:85], v[52:53] op_sel:[0,0,0] op_sel_hi:[0,1,1]
	v_pk_fma_f32 v[10:11], v[40:41], v[86:87], v[52:53] op_sel:[1,0,0] op_sel_hi:[1,1,1]
	v_pk_fma_f32 v[12:13], v[42:43], v[88:89], v[52:53] op_sel:[0,0,0] op_sel_hi:[0,1,1]
	v_pk_fma_f32 v[14:15], v[42:43], v[90:91], v[52:53] op_sel:[1,0,0] op_sel_hi:[1,1,1]
	v_pk_mul_f32 v[96:97], v[44:45], v[0:1] op_sel:[0,0] op_sel_hi:[0,1]
	v_pk_mul_f32 v[98:99], v[44:45], v[2:3] op_sel:[1,0] op_sel_hi:[1,1]
	v_pk_fma_f32 v[96:97], v[46:47], v[4:5], v[96:97] op_sel:[0,0,0] op_sel_hi:[0,1,1]
	v_pk_fma_f32 v[98:99], v[46:47], v[6:7], v[98:99] op_sel:[1,0,0] op_sel_hi:[1,1,1]
	v_pk_fma_f32 v[96:97], v[48:49], v[8:9], v[96:97] op_sel:[0,0,0] op_sel_hi:[0,1,1]
	v_pk_fma_f32 v[98:99], v[48:49], v[10:11], v[98:99] op_sel:[1,0,0] op_sel_hi:[1,1,1]
	v_pk_fma_f32 v[96:97], v[50:51], v[12:13], v[96:97] op_sel:[0,0,0] op_sel_hi:[0,1,1]
	v_pk_fma_f32 v[98:99], v[50:51], v[14:15], v[98:99] op_sel:[1,0,0] op_sel_hi:[1,1,1]
	ds_read_b128 v[36:39], v100 offset:4224
	ds_read_b128 v[40:43], v100 offset:4240
	ds_read_b128 v[44:47], v100 offset:4752
	ds_read_b128 v[48:51], v100 offset:4768
	ds_read_b64 v[52:53], v101 offset:34304
	s_waitcnt lgkmcnt(11)
	v_pk_add_f32 v[76:77], v[0:1], v[72:73] neg_lo:[0,1] neg_hi:[0,1]
	v_pk_add_f32 v[78:79], v[2:3], v[72:73] neg_lo:[0,1] neg_hi:[0,1]
	v_pk_add_f32 v[96:97], v[96:97], v[98:99]
	v_pk_add_f32 v[80:81], v[4:5], v[72:73] neg_lo:[0,1] neg_hi:[0,1]
	v_pk_add_f32 v[82:83], v[6:7], v[72:73] neg_lo:[0,1] neg_hi:[0,1]
	v_pk_add_f32 v[84:85], v[8:9], v[72:73] neg_lo:[0,1] neg_hi:[0,1]
	ds_write_b64 v102, v[96:97] offset:2048
	v_pk_add_f32 v[86:87], v[10:11], v[72:73] neg_lo:[0,1] neg_hi:[0,1]
	v_pk_add_f32 v[88:89], v[12:13], v[72:73] neg_lo:[0,1] neg_hi:[0,1]
	v_pk_add_f32 v[90:91], v[14:15], v[72:73] neg_lo:[0,1] neg_hi:[0,1]
	v_pk_fma_f32 v[0:1], v[56:57], v[76:77], v[72:73] op_sel:[0,0,0] op_sel_hi:[0,1,1]
	v_pk_fma_f32 v[2:3], v[56:57], v[78:79], v[72:73] op_sel:[1,0,0] op_sel_hi:[1,1,1]
	v_pk_fma_f32 v[4:5], v[58:59], v[80:81], v[72:73] op_sel:[0,0,0] op_sel_hi:[0,1,1]
	v_pk_fma_f32 v[6:7], v[58:59], v[82:83], v[72:73] op_sel:[1,0,0] op_sel_hi:[1,1,1]
	v_pk_fma_f32 v[8:9], v[60:61], v[84:85], v[72:73] op_sel:[0,0,0] op_sel_hi:[0,1,1]
	v_pk_fma_f32 v[10:11], v[60:61], v[86:87], v[72:73] op_sel:[1,0,0] op_sel_hi:[1,1,1]
	v_pk_fma_f32 v[12:13], v[62:63], v[88:89], v[72:73] op_sel:[0,0,0] op_sel_hi:[0,1,1]
	v_pk_fma_f32 v[14:15], v[62:63], v[90:91], v[72:73] op_sel:[1,0,0] op_sel_hi:[1,1,1]
	v_pk_mul_f32 v[92:93], v[64:65], v[0:1] op_sel:[0,0] op_sel_hi:[0,1]
	v_pk_mul_f32 v[94:95], v[64:65], v[2:3] op_sel:[1,0] op_sel_hi:[1,1]
	v_pk_fma_f32 v[92:93], v[66:67], v[4:5], v[92:93] op_sel:[0,0,0] op_sel_hi:[0,1,1]
	v_pk_fma_f32 v[94:95], v[66:67], v[6:7], v[94:95] op_sel:[1,0,0] op_sel_hi:[1,1,1]
	v_pk_fma_f32 v[92:93], v[68:69], v[8:9], v[92:93] op_sel:[0,0,0] op_sel_hi:[0,1,1]
	v_pk_fma_f32 v[94:95], v[68:69], v[10:11], v[94:95] op_sel:[1,0,0] op_sel_hi:[1,1,1]
	v_pk_fma_f32 v[92:93], v[70:71], v[12:13], v[92:93] op_sel:[0,0,0] op_sel_hi:[0,1,1]
	v_pk_fma_f32 v[94:95], v[70:71], v[14:15], v[94:95] op_sel:[1,0,0] op_sel_hi:[1,1,1]
	ds_read_b128 v[56:59], v100 offset:5280
	ds_read_b128 v[60:63], v100 offset:5296
	ds_read_b128 v[64:67], v100 offset:5808
	ds_read_b128 v[68:71], v100 offset:5824
	ds_read_b64 v[72:73], v101 offset:34432
	s_waitcnt lgkmcnt(12)
	v_pk_add_f32 v[76:77], v[0:1], v[32:33] neg_lo:[0,1] neg_hi:[0,1]
	v_pk_add_f32 v[78:79], v[2:3], v[32:33] neg_lo:[0,1] neg_hi:[0,1]
	v_pk_add_f32 v[92:93], v[92:93], v[94:95]
	v_pk_add_f32 v[80:81], v[4:5], v[32:33] neg_lo:[0,1] neg_hi:[0,1]
	v_pk_add_f32 v[82:83], v[6:7], v[32:33] neg_lo:[0,1] neg_hi:[0,1]
	v_pk_add_f32 v[84:85], v[8:9], v[32:33] neg_lo:[0,1] neg_hi:[0,1]
	ds_write_b64 v102, v[92:93] offset:4096
	v_pk_add_f32 v[86:87], v[10:11], v[32:33] neg_lo:[0,1] neg_hi:[0,1]
	v_pk_add_f32 v[88:89], v[12:13], v[32:33] neg_lo:[0,1] neg_hi:[0,1]
	v_pk_add_f32 v[90:91], v[14:15], v[32:33] neg_lo:[0,1] neg_hi:[0,1]
	v_pk_fma_f32 v[0:1], v[16:17], v[76:77], v[32:33] op_sel:[0,0,0] op_sel_hi:[0,1,1]
	v_pk_fma_f32 v[2:3], v[16:17], v[78:79], v[32:33] op_sel:[1,0,0] op_sel_hi:[1,1,1]
	v_pk_fma_f32 v[4:5], v[18:19], v[80:81], v[32:33] op_sel:[0,0,0] op_sel_hi:[0,1,1]
	v_pk_fma_f32 v[6:7], v[18:19], v[82:83], v[32:33] op_sel:[1,0,0] op_sel_hi:[1,1,1]
	v_pk_fma_f32 v[8:9], v[20:21], v[84:85], v[32:33] op_sel:[0,0,0] op_sel_hi:[0,1,1]
	v_pk_fma_f32 v[10:11], v[20:21], v[86:87], v[32:33] op_sel:[1,0,0] op_sel_hi:[1,1,1]
	v_pk_fma_f32 v[12:13], v[22:23], v[88:89], v[32:33] op_sel:[0,0,0] op_sel_hi:[0,1,1]
	v_pk_fma_f32 v[14:15], v[22:23], v[90:91], v[32:33] op_sel:[1,0,0] op_sel_hi:[1,1,1]
	v_pk_mul_f32 v[96:97], v[24:25], v[0:1] op_sel:[0,0] op_sel_hi:[0,1]
	v_pk_mul_f32 v[98:99], v[24:25], v[2:3] op_sel:[1,0] op_sel_hi:[1,1]
	v_pk_fma_f32 v[96:97], v[26:27], v[4:5], v[96:97] op_sel:[0,0,0] op_sel_hi:[0,1,1]
	v_pk_fma_f32 v[98:99], v[26:27], v[6:7], v[98:99] op_sel:[1,0,0] op_sel_hi:[1,1,1]
	v_pk_fma_f32 v[96:97], v[28:29], v[8:9], v[96:97] op_sel:[0,0,0] op_sel_hi:[0,1,1]
	v_pk_fma_f32 v[98:99], v[28:29], v[10:11], v[98:99] op_sel:[1,0,0] op_sel_hi:[1,1,1]
	v_pk_fma_f32 v[96:97], v[30:31], v[12:13], v[96:97] op_sel:[0,0,0] op_sel_hi:[0,1,1]
	v_pk_fma_f32 v[98:99], v[30:31], v[14:15], v[98:99] op_sel:[1,0,0] op_sel_hi:[1,1,1]
	ds_read_b128 v[16:19], v100 offset:6336
	ds_read_b128 v[20:23], v100 offset:6352
	ds_read_b128 v[24:27], v100 offset:6864
	ds_read_b128 v[28:31], v100 offset:6880
	ds_read_b64 v[32:33], v101 offset:34560
	s_waitcnt lgkmcnt(12)
	v_pk_add_f32 v[76:77], v[0:1], v[52:53] neg_lo:[0,1] neg_hi:[0,1]
	v_pk_add_f32 v[78:79], v[2:3], v[52:53] neg_lo:[0,1] neg_hi:[0,1]
	v_pk_add_f32 v[96:97], v[96:97], v[98:99]
	v_pk_add_f32 v[80:81], v[4:5], v[52:53] neg_lo:[0,1] neg_hi:[0,1]
	v_pk_add_f32 v[82:83], v[6:7], v[52:53] neg_lo:[0,1] neg_hi:[0,1]
	v_pk_add_f32 v[84:85], v[8:9], v[52:53] neg_lo:[0,1] neg_hi:[0,1]
	ds_write_b64 v102, v[96:97] offset:6144
	v_pk_add_f32 v[86:87], v[10:11], v[52:53] neg_lo:[0,1] neg_hi:[0,1]
	v_pk_add_f32 v[88:89], v[12:13], v[52:53] neg_lo:[0,1] neg_hi:[0,1]
	v_pk_add_f32 v[90:91], v[14:15], v[52:53] neg_lo:[0,1] neg_hi:[0,1]
	v_pk_fma_f32 v[0:1], v[36:37], v[76:77], v[52:53] op_sel:[0,0,0] op_sel_hi:[0,1,1]
	v_pk_fma_f32 v[2:3], v[36:37], v[78:79], v[52:53] op_sel:[1,0,0] op_sel_hi:[1,1,1]
	v_pk_fma_f32 v[4:5], v[38:39], v[80:81], v[52:53] op_sel:[0,0,0] op_sel_hi:[0,1,1]
	v_pk_fma_f32 v[6:7], v[38:39], v[82:83], v[52:53] op_sel:[1,0,0] op_sel_hi:[1,1,1]
	v_pk_fma_f32 v[8:9], v[40:41], v[84:85], v[52:53] op_sel:[0,0,0] op_sel_hi:[0,1,1]
	v_pk_fma_f32 v[10:11], v[40:41], v[86:87], v[52:53] op_sel:[1,0,0] op_sel_hi:[1,1,1]
	v_pk_fma_f32 v[12:13], v[42:43], v[88:89], v[52:53] op_sel:[0,0,0] op_sel_hi:[0,1,1]
	v_pk_fma_f32 v[14:15], v[42:43], v[90:91], v[52:53] op_sel:[1,0,0] op_sel_hi:[1,1,1]
	v_pk_mul_f32 v[92:93], v[44:45], v[0:1] op_sel:[0,0] op_sel_hi:[0,1]
	v_pk_mul_f32 v[94:95], v[44:45], v[2:3] op_sel:[1,0] op_sel_hi:[1,1]
	v_pk_fma_f32 v[92:93], v[46:47], v[4:5], v[92:93] op_sel:[0,0,0] op_sel_hi:[0,1,1]
	v_pk_fma_f32 v[94:95], v[46:47], v[6:7], v[94:95] op_sel:[1,0,0] op_sel_hi:[1,1,1]
	v_pk_fma_f32 v[92:93], v[48:49], v[8:9], v[92:93] op_sel:[0,0,0] op_sel_hi:[0,1,1]
	v_pk_fma_f32 v[94:95], v[48:49], v[10:11], v[94:95] op_sel:[1,0,0] op_sel_hi:[1,1,1]
	v_pk_fma_f32 v[92:93], v[50:51], v[12:13], v[92:93] op_sel:[0,0,0] op_sel_hi:[0,1,1]
	v_pk_fma_f32 v[94:95], v[50:51], v[14:15], v[94:95] op_sel:[1,0,0] op_sel_hi:[1,1,1]
	ds_read_b128 v[36:39], v100 offset:7392
	ds_read_b128 v[40:43], v100 offset:7408
	ds_read_b128 v[44:47], v100 offset:7920
	ds_read_b128 v[48:51], v100 offset:7936
	ds_read_b64 v[52:53], v101 offset:34688
	s_waitcnt lgkmcnt(12)
	v_pk_add_f32 v[76:77], v[0:1], v[72:73] neg_lo:[0,1] neg_hi:[0,1]
	v_pk_add_f32 v[78:79], v[2:3], v[72:73] neg_lo:[0,1] neg_hi:[0,1]
	v_pk_add_f32 v[92:93], v[92:93], v[94:95]
	v_pk_add_f32 v[80:81], v[4:5], v[72:73] neg_lo:[0,1] neg_hi:[0,1]
	v_pk_add_f32 v[82:83], v[6:7], v[72:73] neg_lo:[0,1] neg_hi:[0,1]
	v_pk_add_f32 v[84:85], v[8:9], v[72:73] neg_lo:[0,1] neg_hi:[0,1]
	ds_write_b64 v102, v[92:93] offset:8192
	v_pk_add_f32 v[86:87], v[10:11], v[72:73] neg_lo:[0,1] neg_hi:[0,1]
	v_pk_add_f32 v[88:89], v[12:13], v[72:73] neg_lo:[0,1] neg_hi:[0,1]
	v_pk_add_f32 v[90:91], v[14:15], v[72:73] neg_lo:[0,1] neg_hi:[0,1]
	v_pk_fma_f32 v[0:1], v[56:57], v[76:77], v[72:73] op_sel:[0,0,0] op_sel_hi:[0,1,1]
	v_pk_fma_f32 v[2:3], v[56:57], v[78:79], v[72:73] op_sel:[1,0,0] op_sel_hi:[1,1,1]
	v_pk_fma_f32 v[4:5], v[58:59], v[80:81], v[72:73] op_sel:[0,0,0] op_sel_hi:[0,1,1]
	v_pk_fma_f32 v[6:7], v[58:59], v[82:83], v[72:73] op_sel:[1,0,0] op_sel_hi:[1,1,1]
	v_pk_fma_f32 v[8:9], v[60:61], v[84:85], v[72:73] op_sel:[0,0,0] op_sel_hi:[0,1,1]
	v_pk_fma_f32 v[10:11], v[60:61], v[86:87], v[72:73] op_sel:[1,0,0] op_sel_hi:[1,1,1]
	v_pk_fma_f32 v[12:13], v[62:63], v[88:89], v[72:73] op_sel:[0,0,0] op_sel_hi:[0,1,1]
	v_pk_fma_f32 v[14:15], v[62:63], v[90:91], v[72:73] op_sel:[1,0,0] op_sel_hi:[1,1,1]
	v_pk_mul_f32 v[96:97], v[64:65], v[0:1] op_sel:[0,0] op_sel_hi:[0,1]
	v_pk_mul_f32 v[98:99], v[64:65], v[2:3] op_sel:[1,0] op_sel_hi:[1,1]
	v_pk_fma_f32 v[96:97], v[66:67], v[4:5], v[96:97] op_sel:[0,0,0] op_sel_hi:[0,1,1]
	v_pk_fma_f32 v[98:99], v[66:67], v[6:7], v[98:99] op_sel:[1,0,0] op_sel_hi:[1,1,1]
	v_pk_fma_f32 v[96:97], v[68:69], v[8:9], v[96:97] op_sel:[0,0,0] op_sel_hi:[0,1,1]
	v_pk_fma_f32 v[98:99], v[68:69], v[10:11], v[98:99] op_sel:[1,0,0] op_sel_hi:[1,1,1]
	v_pk_fma_f32 v[96:97], v[70:71], v[12:13], v[96:97] op_sel:[0,0,0] op_sel_hi:[0,1,1]
	v_pk_fma_f32 v[98:99], v[70:71], v[14:15], v[98:99] op_sel:[1,0,0] op_sel_hi:[1,1,1]
	ds_read_b128 v[56:59], v100 offset:8448
	ds_read_b128 v[60:63], v100 offset:8464
	ds_read_b128 v[64:67], v100 offset:8976
	ds_read_b128 v[68:71], v100 offset:8992
	ds_read_b64 v[72:73], v101 offset:34816
	s_waitcnt lgkmcnt(12)
	v_pk_add_f32 v[76:77], v[0:1], v[32:33] neg_lo:[0,1] neg_hi:[0,1]
	v_pk_add_f32 v[78:79], v[2:3], v[32:33] neg_lo:[0,1] neg_hi:[0,1]
	v_pk_add_f32 v[96:97], v[96:97], v[98:99]
	v_pk_add_f32 v[80:81], v[4:5], v[32:33] neg_lo:[0,1] neg_hi:[0,1]
	v_pk_add_f32 v[82:83], v[6:7], v[32:33] neg_lo:[0,1] neg_hi:[0,1]
	v_pk_add_f32 v[84:85], v[8:9], v[32:33] neg_lo:[0,1] neg_hi:[0,1]
	ds_write_b64 v102, v[96:97] offset:10240
	v_pk_add_f32 v[86:87], v[10:11], v[32:33] neg_lo:[0,1] neg_hi:[0,1]
	v_pk_add_f32 v[88:89], v[12:13], v[32:33] neg_lo:[0,1] neg_hi:[0,1]
	v_pk_add_f32 v[90:91], v[14:15], v[32:33] neg_lo:[0,1] neg_hi:[0,1]
	v_pk_fma_f32 v[0:1], v[16:17], v[76:77], v[32:33] op_sel:[0,0,0] op_sel_hi:[0,1,1]
	v_pk_fma_f32 v[2:3], v[16:17], v[78:79], v[32:33] op_sel:[1,0,0] op_sel_hi:[1,1,1]
	v_pk_fma_f32 v[4:5], v[18:19], v[80:81], v[32:33] op_sel:[0,0,0] op_sel_hi:[0,1,1]
	v_pk_fma_f32 v[6:7], v[18:19], v[82:83], v[32:33] op_sel:[1,0,0] op_sel_hi:[1,1,1]
	v_pk_fma_f32 v[8:9], v[20:21], v[84:85], v[32:33] op_sel:[0,0,0] op_sel_hi:[0,1,1]
	v_pk_fma_f32 v[10:11], v[20:21], v[86:87], v[32:33] op_sel:[1,0,0] op_sel_hi:[1,1,1]
	v_pk_fma_f32 v[12:13], v[22:23], v[88:89], v[32:33] op_sel:[0,0,0] op_sel_hi:[0,1,1]
	v_pk_fma_f32 v[14:15], v[22:23], v[90:91], v[32:33] op_sel:[1,0,0] op_sel_hi:[1,1,1]
	v_pk_mul_f32 v[92:93], v[24:25], v[0:1] op_sel:[0,0] op_sel_hi:[0,1]
	v_pk_mul_f32 v[94:95], v[24:25], v[2:3] op_sel:[1,0] op_sel_hi:[1,1]
	v_pk_fma_f32 v[92:93], v[26:27], v[4:5], v[92:93] op_sel:[0,0,0] op_sel_hi:[0,1,1]
	v_pk_fma_f32 v[94:95], v[26:27], v[6:7], v[94:95] op_sel:[1,0,0] op_sel_hi:[1,1,1]
	v_pk_fma_f32 v[92:93], v[28:29], v[8:9], v[92:93] op_sel:[0,0,0] op_sel_hi:[0,1,1]
	v_pk_fma_f32 v[94:95], v[28:29], v[10:11], v[94:95] op_sel:[1,0,0] op_sel_hi:[1,1,1]
	v_pk_fma_f32 v[92:93], v[30:31], v[12:13], v[92:93] op_sel:[0,0,0] op_sel_hi:[0,1,1]
	v_pk_fma_f32 v[94:95], v[30:31], v[14:15], v[94:95] op_sel:[1,0,0] op_sel_hi:[1,1,1]
	ds_read_b128 v[16:19], v100 offset:9504
	ds_read_b128 v[20:23], v100 offset:9520
	ds_read_b128 v[24:27], v100 offset:10032
	ds_read_b128 v[28:31], v100 offset:10048
	ds_read_b64 v[32:33], v101 offset:34944
	s_waitcnt lgkmcnt(12)
	v_pk_add_f32 v[76:77], v[0:1], v[52:53] neg_lo:[0,1] neg_hi:[0,1]
	v_pk_add_f32 v[78:79], v[2:3], v[52:53] neg_lo:[0,1] neg_hi:[0,1]
	v_pk_add_f32 v[92:93], v[92:93], v[94:95]
	v_pk_add_f32 v[80:81], v[4:5], v[52:53] neg_lo:[0,1] neg_hi:[0,1]
	v_pk_add_f32 v[82:83], v[6:7], v[52:53] neg_lo:[0,1] neg_hi:[0,1]
	v_pk_add_f32 v[84:85], v[8:9], v[52:53] neg_lo:[0,1] neg_hi:[0,1]
	ds_write_b64 v102, v[92:93] offset:12288
	v_pk_add_f32 v[86:87], v[10:11], v[52:53] neg_lo:[0,1] neg_hi:[0,1]
	v_pk_add_f32 v[88:89], v[12:13], v[52:53] neg_lo:[0,1] neg_hi:[0,1]
	v_pk_add_f32 v[90:91], v[14:15], v[52:53] neg_lo:[0,1] neg_hi:[0,1]
	v_pk_fma_f32 v[0:1], v[36:37], v[76:77], v[52:53] op_sel:[0,0,0] op_sel_hi:[0,1,1]
	v_pk_fma_f32 v[2:3], v[36:37], v[78:79], v[52:53] op_sel:[1,0,0] op_sel_hi:[1,1,1]
	v_pk_fma_f32 v[4:5], v[38:39], v[80:81], v[52:53] op_sel:[0,0,0] op_sel_hi:[0,1,1]
	v_pk_fma_f32 v[6:7], v[38:39], v[82:83], v[52:53] op_sel:[1,0,0] op_sel_hi:[1,1,1]
	v_pk_fma_f32 v[8:9], v[40:41], v[84:85], v[52:53] op_sel:[0,0,0] op_sel_hi:[0,1,1]
	v_pk_fma_f32 v[10:11], v[40:41], v[86:87], v[52:53] op_sel:[1,0,0] op_sel_hi:[1,1,1]
	v_pk_fma_f32 v[12:13], v[42:43], v[88:89], v[52:53] op_sel:[0,0,0] op_sel_hi:[0,1,1]
	v_pk_fma_f32 v[14:15], v[42:43], v[90:91], v[52:53] op_sel:[1,0,0] op_sel_hi:[1,1,1]
	v_pk_mul_f32 v[96:97], v[44:45], v[0:1] op_sel:[0,0] op_sel_hi:[0,1]
	v_pk_mul_f32 v[98:99], v[44:45], v[2:3] op_sel:[1,0] op_sel_hi:[1,1]
	v_pk_fma_f32 v[96:97], v[46:47], v[4:5], v[96:97] op_sel:[0,0,0] op_sel_hi:[0,1,1]
	v_pk_fma_f32 v[98:99], v[46:47], v[6:7], v[98:99] op_sel:[1,0,0] op_sel_hi:[1,1,1]
	v_pk_fma_f32 v[96:97], v[48:49], v[8:9], v[96:97] op_sel:[0,0,0] op_sel_hi:[0,1,1]
	v_pk_fma_f32 v[98:99], v[48:49], v[10:11], v[98:99] op_sel:[1,0,0] op_sel_hi:[1,1,1]
	v_pk_fma_f32 v[96:97], v[50:51], v[12:13], v[96:97] op_sel:[0,0,0] op_sel_hi:[0,1,1]
	v_pk_fma_f32 v[98:99], v[50:51], v[14:15], v[98:99] op_sel:[1,0,0] op_sel_hi:[1,1,1]
	ds_read_b128 v[36:39], v100 offset:10560
	ds_read_b128 v[40:43], v100 offset:10576
	ds_read_b128 v[44:47], v100 offset:11088
	ds_read_b128 v[48:51], v100 offset:11104
	ds_read_b64 v[52:53], v101 offset:35072
	s_waitcnt lgkmcnt(12)
	v_pk_add_f32 v[76:77], v[0:1], v[72:73] neg_lo:[0,1] neg_hi:[0,1]
	v_pk_add_f32 v[78:79], v[2:3], v[72:73] neg_lo:[0,1] neg_hi:[0,1]
	v_pk_add_f32 v[96:97], v[96:97], v[98:99]
	v_pk_add_f32 v[80:81], v[4:5], v[72:73] neg_lo:[0,1] neg_hi:[0,1]
	v_pk_add_f32 v[82:83], v[6:7], v[72:73] neg_lo:[0,1] neg_hi:[0,1]
	v_pk_add_f32 v[84:85], v[8:9], v[72:73] neg_lo:[0,1] neg_hi:[0,1]
	ds_write_b64 v102, v[96:97] offset:14336
	v_pk_add_f32 v[86:87], v[10:11], v[72:73] neg_lo:[0,1] neg_hi:[0,1]
	v_pk_add_f32 v[88:89], v[12:13], v[72:73] neg_lo:[0,1] neg_hi:[0,1]
	v_pk_add_f32 v[90:91], v[14:15], v[72:73] neg_lo:[0,1] neg_hi:[0,1]
	v_pk_fma_f32 v[0:1], v[56:57], v[76:77], v[72:73] op_sel:[0,0,0] op_sel_hi:[0,1,1]
	v_pk_fma_f32 v[2:3], v[56:57], v[78:79], v[72:73] op_sel:[1,0,0] op_sel_hi:[1,1,1]
	v_pk_fma_f32 v[4:5], v[58:59], v[80:81], v[72:73] op_sel:[0,0,0] op_sel_hi:[0,1,1]
	v_pk_fma_f32 v[6:7], v[58:59], v[82:83], v[72:73] op_sel:[1,0,0] op_sel_hi:[1,1,1]
	v_pk_fma_f32 v[8:9], v[60:61], v[84:85], v[72:73] op_sel:[0,0,0] op_sel_hi:[0,1,1]
	v_pk_fma_f32 v[10:11], v[60:61], v[86:87], v[72:73] op_sel:[1,0,0] op_sel_hi:[1,1,1]
	v_pk_fma_f32 v[12:13], v[62:63], v[88:89], v[72:73] op_sel:[0,0,0] op_sel_hi:[0,1,1]
	v_pk_fma_f32 v[14:15], v[62:63], v[90:91], v[72:73] op_sel:[1,0,0] op_sel_hi:[1,1,1]
	v_pk_mul_f32 v[92:93], v[64:65], v[0:1] op_sel:[0,0] op_sel_hi:[0,1]
	v_pk_mul_f32 v[94:95], v[64:65], v[2:3] op_sel:[1,0] op_sel_hi:[1,1]
	v_pk_fma_f32 v[92:93], v[66:67], v[4:5], v[92:93] op_sel:[0,0,0] op_sel_hi:[0,1,1]
	v_pk_fma_f32 v[94:95], v[66:67], v[6:7], v[94:95] op_sel:[1,0,0] op_sel_hi:[1,1,1]
	v_pk_fma_f32 v[92:93], v[68:69], v[8:9], v[92:93] op_sel:[0,0,0] op_sel_hi:[0,1,1]
	v_pk_fma_f32 v[94:95], v[68:69], v[10:11], v[94:95] op_sel:[1,0,0] op_sel_hi:[1,1,1]
	v_pk_fma_f32 v[92:93], v[70:71], v[12:13], v[92:93] op_sel:[0,0,0] op_sel_hi:[0,1,1]
	v_pk_fma_f32 v[94:95], v[70:71], v[14:15], v[94:95] op_sel:[1,0,0] op_sel_hi:[1,1,1]
	ds_read_b128 v[56:59], v100 offset:11616
	ds_read_b128 v[60:63], v100 offset:11632
	ds_read_b128 v[64:67], v100 offset:12144
	ds_read_b128 v[68:71], v100 offset:12160
	ds_read_b64 v[72:73], v101 offset:35200
	s_waitcnt lgkmcnt(12)
	v_pk_add_f32 v[76:77], v[0:1], v[32:33] neg_lo:[0,1] neg_hi:[0,1]
	v_pk_add_f32 v[78:79], v[2:3], v[32:33] neg_lo:[0,1] neg_hi:[0,1]
	v_pk_add_f32 v[92:93], v[92:93], v[94:95]
	v_pk_add_f32 v[80:81], v[4:5], v[32:33] neg_lo:[0,1] neg_hi:[0,1]
	v_pk_add_f32 v[82:83], v[6:7], v[32:33] neg_lo:[0,1] neg_hi:[0,1]
	v_pk_add_f32 v[84:85], v[8:9], v[32:33] neg_lo:[0,1] neg_hi:[0,1]
	ds_write_b64 v102, v[92:93] offset:16384
	v_pk_add_f32 v[86:87], v[10:11], v[32:33] neg_lo:[0,1] neg_hi:[0,1]
	v_pk_add_f32 v[88:89], v[12:13], v[32:33] neg_lo:[0,1] neg_hi:[0,1]
	v_pk_add_f32 v[90:91], v[14:15], v[32:33] neg_lo:[0,1] neg_hi:[0,1]
	v_pk_fma_f32 v[0:1], v[16:17], v[76:77], v[32:33] op_sel:[0,0,0] op_sel_hi:[0,1,1]
	v_pk_fma_f32 v[2:3], v[16:17], v[78:79], v[32:33] op_sel:[1,0,0] op_sel_hi:[1,1,1]
	v_pk_fma_f32 v[4:5], v[18:19], v[80:81], v[32:33] op_sel:[0,0,0] op_sel_hi:[0,1,1]
	v_pk_fma_f32 v[6:7], v[18:19], v[82:83], v[32:33] op_sel:[1,0,0] op_sel_hi:[1,1,1]
	v_pk_fma_f32 v[8:9], v[20:21], v[84:85], v[32:33] op_sel:[0,0,0] op_sel_hi:[0,1,1]
	v_pk_fma_f32 v[10:11], v[20:21], v[86:87], v[32:33] op_sel:[1,0,0] op_sel_hi:[1,1,1]
	v_pk_fma_f32 v[12:13], v[22:23], v[88:89], v[32:33] op_sel:[0,0,0] op_sel_hi:[0,1,1]
	v_pk_fma_f32 v[14:15], v[22:23], v[90:91], v[32:33] op_sel:[1,0,0] op_sel_hi:[1,1,1]
	v_pk_mul_f32 v[96:97], v[24:25], v[0:1] op_sel:[0,0] op_sel_hi:[0,1]
	v_pk_mul_f32 v[98:99], v[24:25], v[2:3] op_sel:[1,0] op_sel_hi:[1,1]
	v_pk_fma_f32 v[96:97], v[26:27], v[4:5], v[96:97] op_sel:[0,0,0] op_sel_hi:[0,1,1]
	v_pk_fma_f32 v[98:99], v[26:27], v[6:7], v[98:99] op_sel:[1,0,0] op_sel_hi:[1,1,1]
	v_pk_fma_f32 v[96:97], v[28:29], v[8:9], v[96:97] op_sel:[0,0,0] op_sel_hi:[0,1,1]
	v_pk_fma_f32 v[98:99], v[28:29], v[10:11], v[98:99] op_sel:[1,0,0] op_sel_hi:[1,1,1]
	v_pk_fma_f32 v[96:97], v[30:31], v[12:13], v[96:97] op_sel:[0,0,0] op_sel_hi:[0,1,1]
	v_pk_fma_f32 v[98:99], v[30:31], v[14:15], v[98:99] op_sel:[1,0,0] op_sel_hi:[1,1,1]
	ds_read_b128 v[16:19], v100 offset:12672
	ds_read_b128 v[20:23], v100 offset:12688
	ds_read_b128 v[24:27], v100 offset:13200
	ds_read_b128 v[28:31], v100 offset:13216
	ds_read_b64 v[32:33], v101 offset:35328
	s_waitcnt lgkmcnt(12)
	v_pk_add_f32 v[76:77], v[0:1], v[52:53] neg_lo:[0,1] neg_hi:[0,1]
	v_pk_add_f32 v[78:79], v[2:3], v[52:53] neg_lo:[0,1] neg_hi:[0,1]
	v_pk_add_f32 v[96:97], v[96:97], v[98:99]
	v_pk_add_f32 v[80:81], v[4:5], v[52:53] neg_lo:[0,1] neg_hi:[0,1]
	v_pk_add_f32 v[82:83], v[6:7], v[52:53] neg_lo:[0,1] neg_hi:[0,1]
	v_pk_add_f32 v[84:85], v[8:9], v[52:53] neg_lo:[0,1] neg_hi:[0,1]
	ds_write_b64 v102, v[96:97] offset:18432
	v_pk_add_f32 v[86:87], v[10:11], v[52:53] neg_lo:[0,1] neg_hi:[0,1]
	v_pk_add_f32 v[88:89], v[12:13], v[52:53] neg_lo:[0,1] neg_hi:[0,1]
	v_pk_add_f32 v[90:91], v[14:15], v[52:53] neg_lo:[0,1] neg_hi:[0,1]
	v_pk_fma_f32 v[0:1], v[36:37], v[76:77], v[52:53] op_sel:[0,0,0] op_sel_hi:[0,1,1]
	v_pk_fma_f32 v[2:3], v[36:37], v[78:79], v[52:53] op_sel:[1,0,0] op_sel_hi:[1,1,1]
	v_pk_fma_f32 v[4:5], v[38:39], v[80:81], v[52:53] op_sel:[0,0,0] op_sel_hi:[0,1,1]
	v_pk_fma_f32 v[6:7], v[38:39], v[82:83], v[52:53] op_sel:[1,0,0] op_sel_hi:[1,1,1]
	v_pk_fma_f32 v[8:9], v[40:41], v[84:85], v[52:53] op_sel:[0,0,0] op_sel_hi:[0,1,1]
	v_pk_fma_f32 v[10:11], v[40:41], v[86:87], v[52:53] op_sel:[1,0,0] op_sel_hi:[1,1,1]
	v_pk_fma_f32 v[12:13], v[42:43], v[88:89], v[52:53] op_sel:[0,0,0] op_sel_hi:[0,1,1]
	v_pk_fma_f32 v[14:15], v[42:43], v[90:91], v[52:53] op_sel:[1,0,0] op_sel_hi:[1,1,1]
	v_pk_mul_f32 v[92:93], v[44:45], v[0:1] op_sel:[0,0] op_sel_hi:[0,1]
	v_pk_mul_f32 v[94:95], v[44:45], v[2:3] op_sel:[1,0] op_sel_hi:[1,1]
	v_pk_fma_f32 v[92:93], v[46:47], v[4:5], v[92:93] op_sel:[0,0,0] op_sel_hi:[0,1,1]
	v_pk_fma_f32 v[94:95], v[46:47], v[6:7], v[94:95] op_sel:[1,0,0] op_sel_hi:[1,1,1]
	v_pk_fma_f32 v[92:93], v[48:49], v[8:9], v[92:93] op_sel:[0,0,0] op_sel_hi:[0,1,1]
	v_pk_fma_f32 v[94:95], v[48:49], v[10:11], v[94:95] op_sel:[1,0,0] op_sel_hi:[1,1,1]
	v_pk_fma_f32 v[92:93], v[50:51], v[12:13], v[92:93] op_sel:[0,0,0] op_sel_hi:[0,1,1]
	v_pk_fma_f32 v[94:95], v[50:51], v[14:15], v[94:95] op_sel:[1,0,0] op_sel_hi:[1,1,1]
	ds_read_b128 v[36:39], v100 offset:13728
	ds_read_b128 v[40:43], v100 offset:13744
	ds_read_b128 v[44:47], v100 offset:14256
	ds_read_b128 v[48:51], v100 offset:14272
	ds_read_b64 v[52:53], v101 offset:35456
	s_waitcnt lgkmcnt(12)
	v_pk_add_f32 v[76:77], v[0:1], v[72:73] neg_lo:[0,1] neg_hi:[0,1]
	v_pk_add_f32 v[78:79], v[2:3], v[72:73] neg_lo:[0,1] neg_hi:[0,1]
	v_pk_add_f32 v[92:93], v[92:93], v[94:95]
	v_pk_add_f32 v[80:81], v[4:5], v[72:73] neg_lo:[0,1] neg_hi:[0,1]
	v_pk_add_f32 v[82:83], v[6:7], v[72:73] neg_lo:[0,1] neg_hi:[0,1]
	v_pk_add_f32 v[84:85], v[8:9], v[72:73] neg_lo:[0,1] neg_hi:[0,1]
	ds_write_b64 v102, v[92:93] offset:20480
	v_pk_add_f32 v[86:87], v[10:11], v[72:73] neg_lo:[0,1] neg_hi:[0,1]
	v_pk_add_f32 v[88:89], v[12:13], v[72:73] neg_lo:[0,1] neg_hi:[0,1]
	v_pk_add_f32 v[90:91], v[14:15], v[72:73] neg_lo:[0,1] neg_hi:[0,1]
	v_pk_fma_f32 v[0:1], v[56:57], v[76:77], v[72:73] op_sel:[0,0,0] op_sel_hi:[0,1,1]
	v_pk_fma_f32 v[2:3], v[56:57], v[78:79], v[72:73] op_sel:[1,0,0] op_sel_hi:[1,1,1]
	v_pk_fma_f32 v[4:5], v[58:59], v[80:81], v[72:73] op_sel:[0,0,0] op_sel_hi:[0,1,1]
	v_pk_fma_f32 v[6:7], v[58:59], v[82:83], v[72:73] op_sel:[1,0,0] op_sel_hi:[1,1,1]
	v_pk_fma_f32 v[8:9], v[60:61], v[84:85], v[72:73] op_sel:[0,0,0] op_sel_hi:[0,1,1]
	v_pk_fma_f32 v[10:11], v[60:61], v[86:87], v[72:73] op_sel:[1,0,0] op_sel_hi:[1,1,1]
	v_pk_fma_f32 v[12:13], v[62:63], v[88:89], v[72:73] op_sel:[0,0,0] op_sel_hi:[0,1,1]
	v_pk_fma_f32 v[14:15], v[62:63], v[90:91], v[72:73] op_sel:[1,0,0] op_sel_hi:[1,1,1]
	v_pk_mul_f32 v[96:97], v[64:65], v[0:1] op_sel:[0,0] op_sel_hi:[0,1]
	v_pk_mul_f32 v[98:99], v[64:65], v[2:3] op_sel:[1,0] op_sel_hi:[1,1]
	v_pk_fma_f32 v[96:97], v[66:67], v[4:5], v[96:97] op_sel:[0,0,0] op_sel_hi:[0,1,1]
	v_pk_fma_f32 v[98:99], v[66:67], v[6:7], v[98:99] op_sel:[1,0,0] op_sel_hi:[1,1,1]
	v_pk_fma_f32 v[96:97], v[68:69], v[8:9], v[96:97] op_sel:[0,0,0] op_sel_hi:[0,1,1]
	v_pk_fma_f32 v[98:99], v[68:69], v[10:11], v[98:99] op_sel:[1,0,0] op_sel_hi:[1,1,1]
	v_pk_fma_f32 v[96:97], v[70:71], v[12:13], v[96:97] op_sel:[0,0,0] op_sel_hi:[0,1,1]
	v_pk_fma_f32 v[98:99], v[70:71], v[14:15], v[98:99] op_sel:[1,0,0] op_sel_hi:[1,1,1]
	ds_read_b128 v[56:59], v100 offset:14784
	ds_read_b128 v[60:63], v100 offset:14800
	ds_read_b128 v[64:67], v100 offset:15312
	ds_read_b128 v[68:71], v100 offset:15328
	ds_read_b64 v[72:73], v101 offset:35584
	s_waitcnt lgkmcnt(12)
	v_pk_add_f32 v[76:77], v[0:1], v[32:33] neg_lo:[0,1] neg_hi:[0,1]
	v_pk_add_f32 v[78:79], v[2:3], v[32:33] neg_lo:[0,1] neg_hi:[0,1]
	v_pk_add_f32 v[96:97], v[96:97], v[98:99]
	v_pk_add_f32 v[80:81], v[4:5], v[32:33] neg_lo:[0,1] neg_hi:[0,1]
	v_pk_add_f32 v[82:83], v[6:7], v[32:33] neg_lo:[0,1] neg_hi:[0,1]
	v_pk_add_f32 v[84:85], v[8:9], v[32:33] neg_lo:[0,1] neg_hi:[0,1]
	ds_write_b64 v102, v[96:97] offset:22528
	v_pk_add_f32 v[86:87], v[10:11], v[32:33] neg_lo:[0,1] neg_hi:[0,1]
	v_pk_add_f32 v[88:89], v[12:13], v[32:33] neg_lo:[0,1] neg_hi:[0,1]
	v_pk_add_f32 v[90:91], v[14:15], v[32:33] neg_lo:[0,1] neg_hi:[0,1]
	v_pk_fma_f32 v[0:1], v[16:17], v[76:77], v[32:33] op_sel:[0,0,0] op_sel_hi:[0,1,1]
	v_pk_fma_f32 v[2:3], v[16:17], v[78:79], v[32:33] op_sel:[1,0,0] op_sel_hi:[1,1,1]
	v_pk_fma_f32 v[4:5], v[18:19], v[80:81], v[32:33] op_sel:[0,0,0] op_sel_hi:[0,1,1]
	v_pk_fma_f32 v[6:7], v[18:19], v[82:83], v[32:33] op_sel:[1,0,0] op_sel_hi:[1,1,1]
	v_pk_fma_f32 v[8:9], v[20:21], v[84:85], v[32:33] op_sel:[0,0,0] op_sel_hi:[0,1,1]
	v_pk_fma_f32 v[10:11], v[20:21], v[86:87], v[32:33] op_sel:[1,0,0] op_sel_hi:[1,1,1]
	v_pk_fma_f32 v[12:13], v[22:23], v[88:89], v[32:33] op_sel:[0,0,0] op_sel_hi:[0,1,1]
	v_pk_fma_f32 v[14:15], v[22:23], v[90:91], v[32:33] op_sel:[1,0,0] op_sel_hi:[1,1,1]
	v_pk_mul_f32 v[92:93], v[24:25], v[0:1] op_sel:[0,0] op_sel_hi:[0,1]
	v_pk_mul_f32 v[94:95], v[24:25], v[2:3] op_sel:[1,0] op_sel_hi:[1,1]
	v_pk_fma_f32 v[92:93], v[26:27], v[4:5], v[92:93] op_sel:[0,0,0] op_sel_hi:[0,1,1]
	v_pk_fma_f32 v[94:95], v[26:27], v[6:7], v[94:95] op_sel:[1,0,0] op_sel_hi:[1,1,1]
	v_pk_fma_f32 v[92:93], v[28:29], v[8:9], v[92:93] op_sel:[0,0,0] op_sel_hi:[0,1,1]
	v_pk_fma_f32 v[94:95], v[28:29], v[10:11], v[94:95] op_sel:[1,0,0] op_sel_hi:[1,1,1]
	v_pk_fma_f32 v[92:93], v[30:31], v[12:13], v[92:93] op_sel:[0,0,0] op_sel_hi:[0,1,1]
	v_pk_fma_f32 v[94:95], v[30:31], v[14:15], v[94:95] op_sel:[1,0,0] op_sel_hi:[1,1,1]
	ds_read_b128 v[16:19], v100 offset:15840
	ds_read_b128 v[20:23], v100 offset:15856
	ds_read_b128 v[24:27], v100 offset:16368
	ds_read_b128 v[28:31], v100 offset:16384
	ds_read_b64 v[32:33], v101 offset:35712
	s_waitcnt lgkmcnt(12)
	v_pk_add_f32 v[76:77], v[0:1], v[52:53] neg_lo:[0,1] neg_hi:[0,1]
	v_pk_add_f32 v[78:79], v[2:3], v[52:53] neg_lo:[0,1] neg_hi:[0,1]
	v_pk_add_f32 v[92:93], v[92:93], v[94:95]
	v_pk_add_f32 v[80:81], v[4:5], v[52:53] neg_lo:[0,1] neg_hi:[0,1]
	v_pk_add_f32 v[82:83], v[6:7], v[52:53] neg_lo:[0,1] neg_hi:[0,1]
	v_pk_add_f32 v[84:85], v[8:9], v[52:53] neg_lo:[0,1] neg_hi:[0,1]
	ds_write_b64 v102, v[92:93] offset:24576
	v_pk_add_f32 v[86:87], v[10:11], v[52:53] neg_lo:[0,1] neg_hi:[0,1]
	v_pk_add_f32 v[88:89], v[12:13], v[52:53] neg_lo:[0,1] neg_hi:[0,1]
	v_pk_add_f32 v[90:91], v[14:15], v[52:53] neg_lo:[0,1] neg_hi:[0,1]
	v_pk_fma_f32 v[0:1], v[36:37], v[76:77], v[52:53] op_sel:[0,0,0] op_sel_hi:[0,1,1]
	v_pk_fma_f32 v[2:3], v[36:37], v[78:79], v[52:53] op_sel:[1,0,0] op_sel_hi:[1,1,1]
	v_pk_fma_f32 v[4:5], v[38:39], v[80:81], v[52:53] op_sel:[0,0,0] op_sel_hi:[0,1,1]
	v_pk_fma_f32 v[6:7], v[38:39], v[82:83], v[52:53] op_sel:[1,0,0] op_sel_hi:[1,1,1]
	v_pk_fma_f32 v[8:9], v[40:41], v[84:85], v[52:53] op_sel:[0,0,0] op_sel_hi:[0,1,1]
	v_pk_fma_f32 v[10:11], v[40:41], v[86:87], v[52:53] op_sel:[1,0,0] op_sel_hi:[1,1,1]
	v_pk_fma_f32 v[12:13], v[42:43], v[88:89], v[52:53] op_sel:[0,0,0] op_sel_hi:[0,1,1]
	v_pk_fma_f32 v[14:15], v[42:43], v[90:91], v[52:53] op_sel:[1,0,0] op_sel_hi:[1,1,1]
	v_pk_mul_f32 v[96:97], v[44:45], v[0:1] op_sel:[0,0] op_sel_hi:[0,1]
	v_pk_mul_f32 v[98:99], v[44:45], v[2:3] op_sel:[1,0] op_sel_hi:[1,1]
	v_pk_fma_f32 v[96:97], v[46:47], v[4:5], v[96:97] op_sel:[0,0,0] op_sel_hi:[0,1,1]
	v_pk_fma_f32 v[98:99], v[46:47], v[6:7], v[98:99] op_sel:[1,0,0] op_sel_hi:[1,1,1]
	v_pk_fma_f32 v[96:97], v[48:49], v[8:9], v[96:97] op_sel:[0,0,0] op_sel_hi:[0,1,1]
	v_pk_fma_f32 v[98:99], v[48:49], v[10:11], v[98:99] op_sel:[1,0,0] op_sel_hi:[1,1,1]
	v_pk_fma_f32 v[96:97], v[50:51], v[12:13], v[96:97] op_sel:[0,0,0] op_sel_hi:[0,1,1]
	v_pk_fma_f32 v[98:99], v[50:51], v[14:15], v[98:99] op_sel:[1,0,0] op_sel_hi:[1,1,1]
	s_waitcnt lgkmcnt(7)
	v_pk_add_f32 v[76:77], v[0:1], v[72:73] neg_lo:[0,1] neg_hi:[0,1]
	v_pk_add_f32 v[78:79], v[2:3], v[72:73] neg_lo:[0,1] neg_hi:[0,1]
	v_pk_add_f32 v[96:97], v[96:97], v[98:99]
	v_pk_add_f32 v[80:81], v[4:5], v[72:73] neg_lo:[0,1] neg_hi:[0,1]
	v_pk_add_f32 v[82:83], v[6:7], v[72:73] neg_lo:[0,1] neg_hi:[0,1]
	v_pk_add_f32 v[84:85], v[8:9], v[72:73] neg_lo:[0,1] neg_hi:[0,1]
	ds_write_b64 v102, v[96:97] offset:26624
	v_pk_add_f32 v[86:87], v[10:11], v[72:73] neg_lo:[0,1] neg_hi:[0,1]
	v_pk_add_f32 v[88:89], v[12:13], v[72:73] neg_lo:[0,1] neg_hi:[0,1]
	v_pk_add_f32 v[90:91], v[14:15], v[72:73] neg_lo:[0,1] neg_hi:[0,1]
	v_pk_fma_f32 v[0:1], v[56:57], v[76:77], v[72:73] op_sel:[0,0,0] op_sel_hi:[0,1,1]
	v_pk_fma_f32 v[2:3], v[56:57], v[78:79], v[72:73] op_sel:[1,0,0] op_sel_hi:[1,1,1]
	v_pk_fma_f32 v[4:5], v[58:59], v[80:81], v[72:73] op_sel:[0,0,0] op_sel_hi:[0,1,1]
	v_pk_fma_f32 v[6:7], v[58:59], v[82:83], v[72:73] op_sel:[1,0,0] op_sel_hi:[1,1,1]
	v_pk_fma_f32 v[8:9], v[60:61], v[84:85], v[72:73] op_sel:[0,0,0] op_sel_hi:[0,1,1]
	v_pk_fma_f32 v[10:11], v[60:61], v[86:87], v[72:73] op_sel:[1,0,0] op_sel_hi:[1,1,1]
	v_pk_fma_f32 v[12:13], v[62:63], v[88:89], v[72:73] op_sel:[0,0,0] op_sel_hi:[0,1,1]
	v_pk_fma_f32 v[14:15], v[62:63], v[90:91], v[72:73] op_sel:[1,0,0] op_sel_hi:[1,1,1]
	v_pk_mul_f32 v[92:93], v[64:65], v[0:1] op_sel:[0,0] op_sel_hi:[0,1]
	v_pk_mul_f32 v[94:95], v[64:65], v[2:3] op_sel:[1,0] op_sel_hi:[1,1]
	v_pk_fma_f32 v[92:93], v[66:67], v[4:5], v[92:93] op_sel:[0,0,0] op_sel_hi:[0,1,1]
	v_pk_fma_f32 v[94:95], v[66:67], v[6:7], v[94:95] op_sel:[1,0,0] op_sel_hi:[1,1,1]
	v_pk_fma_f32 v[92:93], v[68:69], v[8:9], v[92:93] op_sel:[0,0,0] op_sel_hi:[0,1,1]
	v_pk_fma_f32 v[94:95], v[68:69], v[10:11], v[94:95] op_sel:[1,0,0] op_sel_hi:[1,1,1]
	v_pk_fma_f32 v[92:93], v[70:71], v[12:13], v[92:93] op_sel:[0,0,0] op_sel_hi:[0,1,1]
	v_pk_fma_f32 v[94:95], v[70:71], v[14:15], v[94:95] op_sel:[1,0,0] op_sel_hi:[1,1,1]
	s_waitcnt lgkmcnt(2)
	v_pk_add_f32 v[76:77], v[0:1], v[32:33] neg_lo:[0,1] neg_hi:[0,1]
	v_pk_add_f32 v[78:79], v[2:3], v[32:33] neg_lo:[0,1] neg_hi:[0,1]
	v_pk_add_f32 v[92:93], v[92:93], v[94:95]
	v_pk_add_f32 v[80:81], v[4:5], v[32:33] neg_lo:[0,1] neg_hi:[0,1]
	v_pk_add_f32 v[82:83], v[6:7], v[32:33] neg_lo:[0,1] neg_hi:[0,1]
	v_pk_add_f32 v[84:85], v[8:9], v[32:33] neg_lo:[0,1] neg_hi:[0,1]
	ds_write_b64 v102, v[92:93] offset:28672
	v_pk_add_f32 v[86:87], v[10:11], v[32:33] neg_lo:[0,1] neg_hi:[0,1]
	v_pk_add_f32 v[88:89], v[12:13], v[32:33] neg_lo:[0,1] neg_hi:[0,1]
	v_pk_add_f32 v[90:91], v[14:15], v[32:33] neg_lo:[0,1] neg_hi:[0,1]
	v_pk_fma_f32 v[0:1], v[16:17], v[76:77], v[32:33] op_sel:[0,0,0] op_sel_hi:[0,1,1]
	v_pk_fma_f32 v[2:3], v[16:17], v[78:79], v[32:33] op_sel:[1,0,0] op_sel_hi:[1,1,1]
	v_pk_fma_f32 v[4:5], v[18:19], v[80:81], v[32:33] op_sel:[0,0,0] op_sel_hi:[0,1,1]
	v_pk_fma_f32 v[6:7], v[18:19], v[82:83], v[32:33] op_sel:[1,0,0] op_sel_hi:[1,1,1]
	v_pk_fma_f32 v[8:9], v[20:21], v[84:85], v[32:33] op_sel:[0,0,0] op_sel_hi:[0,1,1]
	v_pk_fma_f32 v[10:11], v[20:21], v[86:87], v[32:33] op_sel:[1,0,0] op_sel_hi:[1,1,1]
	v_pk_fma_f32 v[12:13], v[22:23], v[88:89], v[32:33] op_sel:[0,0,0] op_sel_hi:[0,1,1]
	v_pk_fma_f32 v[14:15], v[22:23], v[90:91], v[32:33] op_sel:[1,0,0] op_sel_hi:[1,1,1]
	v_pk_mul_f32 v[96:97], v[24:25], v[0:1] op_sel:[0,0] op_sel_hi:[0,1]
	v_pk_mul_f32 v[98:99], v[24:25], v[2:3] op_sel:[1,0] op_sel_hi:[1,1]
	v_pk_fma_f32 v[96:97], v[26:27], v[4:5], v[96:97] op_sel:[0,0,0] op_sel_hi:[0,1,1]
	v_pk_fma_f32 v[98:99], v[26:27], v[6:7], v[98:99] op_sel:[1,0,0] op_sel_hi:[1,1,1]
	v_pk_fma_f32 v[96:97], v[28:29], v[8:9], v[96:97] op_sel:[0,0,0] op_sel_hi:[0,1,1]
	v_pk_fma_f32 v[98:99], v[28:29], v[10:11], v[98:99] op_sel:[1,0,0] op_sel_hi:[1,1,1]
	v_pk_fma_f32 v[96:97], v[30:31], v[12:13], v[96:97] op_sel:[0,0,0] op_sel_hi:[0,1,1]
	v_pk_fma_f32 v[98:99], v[30:31], v[14:15], v[98:99] op_sel:[1,0,0] op_sel_hi:[1,1,1]
	s_nop 0
	v_pk_add_f32 v[96:97], v[96:97], v[98:99]
	s_nop 0
	ds_write_b64 v102, v[96:97] offset:30720
	s_waitcnt lgkmcnt(0)
	s_barrier
	ds_read_b128 v[16:19], v100 offset:16896
	ds_read_b128 v[20:23], v100 offset:16912
	ds_read_b128 v[24:27], v100 offset:17424
	ds_read_b128 v[28:31], v100 offset:17440
	ds_read_b64 v[32:33], v101 offset:35840
	ds_read_b128 v[36:39], v100 offset:17952
	ds_read_b128 v[40:43], v100 offset:17968
	ds_read_b128 v[44:47], v100 offset:18480
	ds_read_b128 v[48:51], v100 offset:18496
	ds_read_b64 v[52:53], v101 offset:35968
	ds_read_b128 v[56:59], v103 offset:0
	v_xor_b32_e32 v89, 16, v103
	ds_read_b128 v[60:63], v89 offset:0
	v_xor_b32_e32 v89, 32, v103
	ds_read_b128 v[64:67], v89 offset:0
	v_xor_b32_e32 v89, 48, v103
	ds_read_b128 v[68:71], v89 offset:0
	v_xor_b32_e32 v89, 64, v103
	ds_read_b128 v[72:75], v89 offset:0
	v_xor_b32_e32 v89, 80, v103
	ds_read_b128 v[76:79], v89 offset:0
	v_xor_b32_e32 v89, 96, v103
	ds_read_b128 v[80:83], v89 offset:0
	v_xor_b32_e32 v89, 112, v103
	ds_read_b128 v[84:87], v89 offset:0
	s_waitcnt lgkmcnt(0)
	v_pk_add_f32 v[56:57], v[56:57], v[58:59]
	v_pk_add_f32 v[60:61], v[60:61], v[62:63]
	v_pk_add_f32 v[64:65], v[64:65], v[66:67]
	v_pk_add_f32 v[68:69], v[68:69], v[70:71]
	v_pk_add_f32 v[72:73], v[72:73], v[74:75]
	v_pk_add_f32 v[76:77], v[76:77], v[78:79]
	v_pk_add_f32 v[80:81], v[80:81], v[82:83]
	v_pk_add_f32 v[84:85], v[84:85], v[86:87]
	v_pk_add_f32 v[56:57], v[56:57], v[60:61]
	v_pk_add_f32 v[64:65], v[64:65], v[68:69]
	v_pk_add_f32 v[72:73], v[72:73], v[76:77]
	v_pk_add_f32 v[80:81], v[80:81], v[84:85]
	v_pk_add_f32 v[56:57], v[56:57], v[64:65]
	v_pk_add_f32 v[72:73], v[72:73], v[80:81]
	s_nop 0
	v_pk_add_f32 v[56:57], v[56:57], v[72:73]
	s_nop 0
	v_cvt_pk_bf16_f32 v88, v56, v57
	global_store_dword v[104:105], v88, off
	v_lshl_add_u64 v[104:105], v[104:105], 0, s[14:15]
	ds_read_b128 v[56:59], v100 offset:19008
	ds_read_b128 v[60:63], v100 offset:19024
	ds_read_b128 v[64:67], v100 offset:19536
	ds_read_b128 v[68:71], v100 offset:19552
	ds_read_b64 v[72:73], v101 offset:36096
	v_pk_add_f32 v[76:77], v[0:1], v[32:33] neg_lo:[0,1] neg_hi:[0,1]
	v_pk_add_f32 v[78:79], v[2:3], v[32:33] neg_lo:[0,1] neg_hi:[0,1]
	v_pk_add_f32 v[80:81], v[4:5], v[32:33] neg_lo:[0,1] neg_hi:[0,1]
	v_pk_add_f32 v[82:83], v[6:7], v[32:33] neg_lo:[0,1] neg_hi:[0,1]
	v_pk_add_f32 v[84:85], v[8:9], v[32:33] neg_lo:[0,1] neg_hi:[0,1]
	v_pk_add_f32 v[86:87], v[10:11], v[32:33] neg_lo:[0,1] neg_hi:[0,1]
	v_pk_add_f32 v[88:89], v[12:13], v[32:33] neg_lo:[0,1] neg_hi:[0,1]
	v_pk_add_f32 v[90:91], v[14:15], v[32:33] neg_lo:[0,1] neg_hi:[0,1]
	v_pk_fma_f32 v[0:1], v[16:17], v[76:77], v[32:33] op_sel:[0,0,0] op_sel_hi:[0,1,1]
	v_pk_fma_f32 v[2:3], v[16:17], v[78:79], v[32:33] op_sel:[1,0,0] op_sel_hi:[1,1,1]
	v_pk_fma_f32 v[4:5], v[18:19], v[80:81], v[32:33] op_sel:[0,0,0] op_sel_hi:[0,1,1]
	v_pk_fma_f32 v[6:7], v[18:19], v[82:83], v[32:33] op_sel:[1,0,0] op_sel_hi:[1,1,1]
	v_pk_fma_f32 v[8:9], v[20:21], v[84:85], v[32:33] op_sel:[0,0,0] op_sel_hi:[0,1,1]
	v_pk_fma_f32 v[10:11], v[20:21], v[86:87], v[32:33] op_sel:[1,0,0] op_sel_hi:[1,1,1]
	v_pk_fma_f32 v[12:13], v[22:23], v[88:89], v[32:33] op_sel:[0,0,0] op_sel_hi:[0,1,1]
	v_pk_fma_f32 v[14:15], v[22:23], v[90:91], v[32:33] op_sel:[1,0,0] op_sel_hi:[1,1,1]
	v_pk_mul_f32 v[92:93], v[24:25], v[0:1] op_sel:[0,0] op_sel_hi:[0,1]
	v_pk_mul_f32 v[94:95], v[24:25], v[2:3] op_sel:[1,0] op_sel_hi:[1,1]
	v_pk_fma_f32 v[92:93], v[26:27], v[4:5], v[92:93] op_sel:[0,0,0] op_sel_hi:[0,1,1]
	v_pk_fma_f32 v[94:95], v[26:27], v[6:7], v[94:95] op_sel:[1,0,0] op_sel_hi:[1,1,1]
	v_pk_fma_f32 v[92:93], v[28:29], v[8:9], v[92:93] op_sel:[0,0,0] op_sel_hi:[0,1,1]
	v_pk_fma_f32 v[94:95], v[28:29], v[10:11], v[94:95] op_sel:[1,0,0] op_sel_hi:[1,1,1]
	v_pk_fma_f32 v[92:93], v[30:31], v[12:13], v[92:93] op_sel:[0,0,0] op_sel_hi:[0,1,1]
	v_pk_fma_f32 v[94:95], v[30:31], v[14:15], v[94:95] op_sel:[1,0,0] op_sel_hi:[1,1,1]
	ds_read_b128 v[16:19], v100 offset:20064
	ds_read_b128 v[20:23], v100 offset:20080
	ds_read_b128 v[24:27], v100 offset:20592
	ds_read_b128 v[28:31], v100 offset:20608
	ds_read_b64 v[32:33], v101 offset:36224
	v_pk_add_f32 v[76:77], v[0:1], v[52:53] neg_lo:[0,1] neg_hi:[0,1]
	v_pk_add_f32 v[78:79], v[2:3], v[52:53] neg_lo:[0,1] neg_hi:[0,1]
	v_pk_add_f32 v[92:93], v[92:93], v[94:95]
	v_pk_add_f32 v[80:81], v[4:5], v[52:53] neg_lo:[0,1] neg_hi:[0,1]
	v_pk_add_f32 v[82:83], v[6:7], v[52:53] neg_lo:[0,1] neg_hi:[0,1]
	v_pk_add_f32 v[84:85], v[8:9], v[52:53] neg_lo:[0,1] neg_hi:[0,1]
	ds_write_b64 v102, v[92:93] offset:32768
	v_pk_add_f32 v[86:87], v[10:11], v[52:53] neg_lo:[0,1] neg_hi:[0,1]
	v_pk_add_f32 v[88:89], v[12:13], v[52:53] neg_lo:[0,1] neg_hi:[0,1]
	v_pk_add_f32 v[90:91], v[14:15], v[52:53] neg_lo:[0,1] neg_hi:[0,1]
	v_pk_fma_f32 v[0:1], v[36:37], v[76:77], v[52:53] op_sel:[0,0,0] op_sel_hi:[0,1,1]
	v_pk_fma_f32 v[2:3], v[36:37], v[78:79], v[52:53] op_sel:[1,0,0] op_sel_hi:[1,1,1]
	v_pk_fma_f32 v[4:5], v[38:39], v[80:81], v[52:53] op_sel:[0,0,0] op_sel_hi:[0,1,1]
	v_pk_fma_f32 v[6:7], v[38:39], v[82:83], v[52:53] op_sel:[1,0,0] op_sel_hi:[1,1,1]
	v_pk_fma_f32 v[8:9], v[40:41], v[84:85], v[52:53] op_sel:[0,0,0] op_sel_hi:[0,1,1]
	v_pk_fma_f32 v[10:11], v[40:41], v[86:87], v[52:53] op_sel:[1,0,0] op_sel_hi:[1,1,1]
	v_pk_fma_f32 v[12:13], v[42:43], v[88:89], v[52:53] op_sel:[0,0,0] op_sel_hi:[0,1,1]
	v_pk_fma_f32 v[14:15], v[42:43], v[90:91], v[52:53] op_sel:[1,0,0] op_sel_hi:[1,1,1]
	v_pk_mul_f32 v[96:97], v[44:45], v[0:1] op_sel:[0,0] op_sel_hi:[0,1]
	v_pk_mul_f32 v[98:99], v[44:45], v[2:3] op_sel:[1,0] op_sel_hi:[1,1]
	v_pk_fma_f32 v[96:97], v[46:47], v[4:5], v[96:97] op_sel:[0,0,0] op_sel_hi:[0,1,1]
	v_pk_fma_f32 v[98:99], v[46:47], v[6:7], v[98:99] op_sel:[1,0,0] op_sel_hi:[1,1,1]
	v_pk_fma_f32 v[96:97], v[48:49], v[8:9], v[96:97] op_sel:[0,0,0] op_sel_hi:[0,1,1]
	v_pk_fma_f32 v[98:99], v[48:49], v[10:11], v[98:99] op_sel:[1,0,0] op_sel_hi:[1,1,1]
	v_pk_fma_f32 v[96:97], v[50:51], v[12:13], v[96:97] op_sel:[0,0,0] op_sel_hi:[0,1,1]
	v_pk_fma_f32 v[98:99], v[50:51], v[14:15], v[98:99] op_sel:[1,0,0] op_sel_hi:[1,1,1]
	ds_read_b128 v[36:39], v100 offset:21120
	ds_read_b128 v[40:43], v100 offset:21136
	ds_read_b128 v[44:47], v100 offset:21648
	ds_read_b128 v[48:51], v100 offset:21664
	ds_read_b64 v[52:53], v101 offset:36352
	s_waitcnt lgkmcnt(11)
	v_pk_add_f32 v[76:77], v[0:1], v[72:73] neg_lo:[0,1] neg_hi:[0,1]
	v_pk_add_f32 v[78:79], v[2:3], v[72:73] neg_lo:[0,1] neg_hi:[0,1]
	v_pk_add_f32 v[96:97], v[96:97], v[98:99]
	v_pk_add_f32 v[80:81], v[4:5], v[72:73] neg_lo:[0,1] neg_hi:[0,1]
	v_pk_add_f32 v[82:83], v[6:7], v[72:73] neg_lo:[0,1] neg_hi:[0,1]
	v_pk_add_f32 v[84:85], v[8:9], v[72:73] neg_lo:[0,1] neg_hi:[0,1]
	ds_write_b64 v102, v[96:97] offset:34816
	v_pk_add_f32 v[86:87], v[10:11], v[72:73] neg_lo:[0,1] neg_hi:[0,1]
	v_pk_add_f32 v[88:89], v[12:13], v[72:73] neg_lo:[0,1] neg_hi:[0,1]
	v_pk_add_f32 v[90:91], v[14:15], v[72:73] neg_lo:[0,1] neg_hi:[0,1]
	v_pk_fma_f32 v[0:1], v[56:57], v[76:77], v[72:73] op_sel:[0,0,0] op_sel_hi:[0,1,1]
	v_pk_fma_f32 v[2:3], v[56:57], v[78:79], v[72:73] op_sel:[1,0,0] op_sel_hi:[1,1,1]
	v_pk_fma_f32 v[4:5], v[58:59], v[80:81], v[72:73] op_sel:[0,0,0] op_sel_hi:[0,1,1]
	v_pk_fma_f32 v[6:7], v[58:59], v[82:83], v[72:73] op_sel:[1,0,0] op_sel_hi:[1,1,1]
	v_pk_fma_f32 v[8:9], v[60:61], v[84:85], v[72:73] op_sel:[0,0,0] op_sel_hi:[0,1,1]
	v_pk_fma_f32 v[10:11], v[60:61], v[86:87], v[72:73] op_sel:[1,0,0] op_sel_hi:[1,1,1]
	v_pk_fma_f32 v[12:13], v[62:63], v[88:89], v[72:73] op_sel:[0,0,0] op_sel_hi:[0,1,1]
	v_pk_fma_f32 v[14:15], v[62:63], v[90:91], v[72:73] op_sel:[1,0,0] op_sel_hi:[1,1,1]
	v_pk_mul_f32 v[92:93], v[64:65], v[0:1] op_sel:[0,0] op_sel_hi:[0,1]
	v_pk_mul_f32 v[94:95], v[64:65], v[2:3] op_sel:[1,0] op_sel_hi:[1,1]
	v_pk_fma_f32 v[92:93], v[66:67], v[4:5], v[92:93] op_sel:[0,0,0] op_sel_hi:[0,1,1]
	v_pk_fma_f32 v[94:95], v[66:67], v[6:7], v[94:95] op_sel:[1,0,0] op_sel_hi:[1,1,1]
	v_pk_fma_f32 v[92:93], v[68:69], v[8:9], v[92:93] op_sel:[0,0,0] op_sel_hi:[0,1,1]
	v_pk_fma_f32 v[94:95], v[68:69], v[10:11], v[94:95] op_sel:[1,0,0] op_sel_hi:[1,1,1]
	v_pk_fma_f32 v[92:93], v[70:71], v[12:13], v[92:93] op_sel:[0,0,0] op_sel_hi:[0,1,1]
	v_pk_fma_f32 v[94:95], v[70:71], v[14:15], v[94:95] op_sel:[1,0,0] op_sel_hi:[1,1,1]
	ds_read_b128 v[56:59], v100 offset:22176
	ds_read_b128 v[60:63], v100 offset:22192
	ds_read_b128 v[64:67], v100 offset:22704
	ds_read_b128 v[68:71], v100 offset:22720
	ds_read_b64 v[72:73], v101 offset:36480
	s_waitcnt lgkmcnt(12)
	v_pk_add_f32 v[76:77], v[0:1], v[32:33] neg_lo:[0,1] neg_hi:[0,1]
	v_pk_add_f32 v[78:79], v[2:3], v[32:33] neg_lo:[0,1] neg_hi:[0,1]
	v_pk_add_f32 v[92:93], v[92:93], v[94:95]
	v_pk_add_f32 v[80:81], v[4:5], v[32:33] neg_lo:[0,1] neg_hi:[0,1]
	v_pk_add_f32 v[82:83], v[6:7], v[32:33] neg_lo:[0,1] neg_hi:[0,1]
	v_pk_add_f32 v[84:85], v[8:9], v[32:33] neg_lo:[0,1] neg_hi:[0,1]
	ds_write_b64 v102, v[92:93] offset:36864
	v_pk_add_f32 v[86:87], v[10:11], v[32:33] neg_lo:[0,1] neg_hi:[0,1]
	v_pk_add_f32 v[88:89], v[12:13], v[32:33] neg_lo:[0,1] neg_hi:[0,1]
	v_pk_add_f32 v[90:91], v[14:15], v[32:33] neg_lo:[0,1] neg_hi:[0,1]
	v_pk_fma_f32 v[0:1], v[16:17], v[76:77], v[32:33] op_sel:[0,0,0] op_sel_hi:[0,1,1]
	v_pk_fma_f32 v[2:3], v[16:17], v[78:79], v[32:33] op_sel:[1,0,0] op_sel_hi:[1,1,1]
	v_pk_fma_f32 v[4:5], v[18:19], v[80:81], v[32:33] op_sel:[0,0,0] op_sel_hi:[0,1,1]
	v_pk_fma_f32 v[6:7], v[18:19], v[82:83], v[32:33] op_sel:[1,0,0] op_sel_hi:[1,1,1]
	v_pk_fma_f32 v[8:9], v[20:21], v[84:85], v[32:33] op_sel:[0,0,0] op_sel_hi:[0,1,1]
	v_pk_fma_f32 v[10:11], v[20:21], v[86:87], v[32:33] op_sel:[1,0,0] op_sel_hi:[1,1,1]
	v_pk_fma_f32 v[12:13], v[22:23], v[88:89], v[32:33] op_sel:[0,0,0] op_sel_hi:[0,1,1]
	v_pk_fma_f32 v[14:15], v[22:23], v[90:91], v[32:33] op_sel:[1,0,0] op_sel_hi:[1,1,1]
	v_pk_mul_f32 v[96:97], v[24:25], v[0:1] op_sel:[0,0] op_sel_hi:[0,1]
	v_pk_mul_f32 v[98:99], v[24:25], v[2:3] op_sel:[1,0] op_sel_hi:[1,1]
	v_pk_fma_f32 v[96:97], v[26:27], v[4:5], v[96:97] op_sel:[0,0,0] op_sel_hi:[0,1,1]
	v_pk_fma_f32 v[98:99], v[26:27], v[6:7], v[98:99] op_sel:[1,0,0] op_sel_hi:[1,1,1]
	v_pk_fma_f32 v[96:97], v[28:29], v[8:9], v[96:97] op_sel:[0,0,0] op_sel_hi:[0,1,1]
	v_pk_fma_f32 v[98:99], v[28:29], v[10:11], v[98:99] op_sel:[1,0,0] op_sel_hi:[1,1,1]
	v_pk_fma_f32 v[96:97], v[30:31], v[12:13], v[96:97] op_sel:[0,0,0] op_sel_hi:[0,1,1]
	v_pk_fma_f32 v[98:99], v[30:31], v[14:15], v[98:99] op_sel:[1,0,0] op_sel_hi:[1,1,1]
	ds_read_b128 v[16:19], v100 offset:23232
	ds_read_b128 v[20:23], v100 offset:23248
	ds_read_b128 v[24:27], v100 offset:23760
	ds_read_b128 v[28:31], v100 offset:23776
	ds_read_b64 v[32:33], v101 offset:36608
	s_waitcnt lgkmcnt(12)
	v_pk_add_f32 v[76:77], v[0:1], v[52:53] neg_lo:[0,1] neg_hi:[0,1]
	v_pk_add_f32 v[78:79], v[2:3], v[52:53] neg_lo:[0,1] neg_hi:[0,1]
	v_pk_add_f32 v[96:97], v[96:97], v[98:99]
	v_pk_add_f32 v[80:81], v[4:5], v[52:53] neg_lo:[0,1] neg_hi:[0,1]
	v_pk_add_f32 v[82:83], v[6:7], v[52:53] neg_lo:[0,1] neg_hi:[0,1]
	v_pk_add_f32 v[84:85], v[8:9], v[52:53] neg_lo:[0,1] neg_hi:[0,1]
	ds_write_b64 v102, v[96:97] offset:38912
	v_pk_add_f32 v[86:87], v[10:11], v[52:53] neg_lo:[0,1] neg_hi:[0,1]
	v_pk_add_f32 v[88:89], v[12:13], v[52:53] neg_lo:[0,1] neg_hi:[0,1]
	v_pk_add_f32 v[90:91], v[14:15], v[52:53] neg_lo:[0,1] neg_hi:[0,1]
	v_pk_fma_f32 v[0:1], v[36:37], v[76:77], v[52:53] op_sel:[0,0,0] op_sel_hi:[0,1,1]
	v_pk_fma_f32 v[2:3], v[36:37], v[78:79], v[52:53] op_sel:[1,0,0] op_sel_hi:[1,1,1]
	v_pk_fma_f32 v[4:5], v[38:39], v[80:81], v[52:53] op_sel:[0,0,0] op_sel_hi:[0,1,1]
	v_pk_fma_f32 v[6:7], v[38:39], v[82:83], v[52:53] op_sel:[1,0,0] op_sel_hi:[1,1,1]
	v_pk_fma_f32 v[8:9], v[40:41], v[84:85], v[52:53] op_sel:[0,0,0] op_sel_hi:[0,1,1]
	v_pk_fma_f32 v[10:11], v[40:41], v[86:87], v[52:53] op_sel:[1,0,0] op_sel_hi:[1,1,1]
	v_pk_fma_f32 v[12:13], v[42:43], v[88:89], v[52:53] op_sel:[0,0,0] op_sel_hi:[0,1,1]
	v_pk_fma_f32 v[14:15], v[42:43], v[90:91], v[52:53] op_sel:[1,0,0] op_sel_hi:[1,1,1]
	v_pk_mul_f32 v[92:93], v[44:45], v[0:1] op_sel:[0,0] op_sel_hi:[0,1]
	v_pk_mul_f32 v[94:95], v[44:45], v[2:3] op_sel:[1,0] op_sel_hi:[1,1]
	v_pk_fma_f32 v[92:93], v[46:47], v[4:5], v[92:93] op_sel:[0,0,0] op_sel_hi:[0,1,1]
	v_pk_fma_f32 v[94:95], v[46:47], v[6:7], v[94:95] op_sel:[1,0,0] op_sel_hi:[1,1,1]
	v_pk_fma_f32 v[92:93], v[48:49], v[8:9], v[92:93] op_sel:[0,0,0] op_sel_hi:[0,1,1]
	v_pk_fma_f32 v[94:95], v[48:49], v[10:11], v[94:95] op_sel:[1,0,0] op_sel_hi:[1,1,1]
	v_pk_fma_f32 v[92:93], v[50:51], v[12:13], v[92:93] op_sel:[0,0,0] op_sel_hi:[0,1,1]
	v_pk_fma_f32 v[94:95], v[50:51], v[14:15], v[94:95] op_sel:[1,0,0] op_sel_hi:[1,1,1]
	ds_read_b128 v[36:39], v100 offset:24288
	ds_read_b128 v[40:43], v100 offset:24304
	ds_read_b128 v[44:47], v100 offset:24816
	ds_read_b128 v[48:51], v100 offset:24832
	ds_read_b64 v[52:53], v101 offset:36736
	s_waitcnt lgkmcnt(12)
	v_pk_add_f32 v[76:77], v[0:1], v[72:73] neg_lo:[0,1] neg_hi:[0,1]
	v_pk_add_f32 v[78:79], v[2:3], v[72:73] neg_lo:[0,1] neg_hi:[0,1]
	v_pk_add_f32 v[92:93], v[92:93], v[94:95]
	v_pk_add_f32 v[80:81], v[4:5], v[72:73] neg_lo:[0,1] neg_hi:[0,1]
	v_pk_add_f32 v[82:83], v[6:7], v[72:73] neg_lo:[0,1] neg_hi:[0,1]
	v_pk_add_f32 v[84:85], v[8:9], v[72:73] neg_lo:[0,1] neg_hi:[0,1]
	ds_write_b64 v102, v[92:93] offset:40960
	v_pk_add_f32 v[86:87], v[10:11], v[72:73] neg_lo:[0,1] neg_hi:[0,1]
	v_pk_add_f32 v[88:89], v[12:13], v[72:73] neg_lo:[0,1] neg_hi:[0,1]
	v_pk_add_f32 v[90:91], v[14:15], v[72:73] neg_lo:[0,1] neg_hi:[0,1]
	v_pk_fma_f32 v[0:1], v[56:57], v[76:77], v[72:73] op_sel:[0,0,0] op_sel_hi:[0,1,1]
	v_pk_fma_f32 v[2:3], v[56:57], v[78:79], v[72:73] op_sel:[1,0,0] op_sel_hi:[1,1,1]
	v_pk_fma_f32 v[4:5], v[58:59], v[80:81], v[72:73] op_sel:[0,0,0] op_sel_hi:[0,1,1]
	v_pk_fma_f32 v[6:7], v[58:59], v[82:83], v[72:73] op_sel:[1,0,0] op_sel_hi:[1,1,1]
	v_pk_fma_f32 v[8:9], v[60:61], v[84:85], v[72:73] op_sel:[0,0,0] op_sel_hi:[0,1,1]
	v_pk_fma_f32 v[10:11], v[60:61], v[86:87], v[72:73] op_sel:[1,0,0] op_sel_hi:[1,1,1]
	v_pk_fma_f32 v[12:13], v[62:63], v[88:89], v[72:73] op_sel:[0,0,0] op_sel_hi:[0,1,1]
	v_pk_fma_f32 v[14:15], v[62:63], v[90:91], v[72:73] op_sel:[1,0,0] op_sel_hi:[1,1,1]
	v_pk_mul_f32 v[96:97], v[64:65], v[0:1] op_sel:[0,0] op_sel_hi:[0,1]
	v_pk_mul_f32 v[98:99], v[64:65], v[2:3] op_sel:[1,0] op_sel_hi:[1,1]
	v_pk_fma_f32 v[96:97], v[66:67], v[4:5], v[96:97] op_sel:[0,0,0] op_sel_hi:[0,1,1]
	v_pk_fma_f32 v[98:99], v[66:67], v[6:7], v[98:99] op_sel:[1,0,0] op_sel_hi:[1,1,1]
	v_pk_fma_f32 v[96:97], v[68:69], v[8:9], v[96:97] op_sel:[0,0,0] op_sel_hi:[0,1,1]
	v_pk_fma_f32 v[98:99], v[68:69], v[10:11], v[98:99] op_sel:[1,0,0] op_sel_hi:[1,1,1]
	v_pk_fma_f32 v[96:97], v[70:71], v[12:13], v[96:97] op_sel:[0,0,0] op_sel_hi:[0,1,1]
	v_pk_fma_f32 v[98:99], v[70:71], v[14:15], v[98:99] op_sel:[1,0,0] op_sel_hi:[1,1,1]
	ds_read_b128 v[56:59], v100 offset:25344
	ds_read_b128 v[60:63], v100 offset:25360
	ds_read_b128 v[64:67], v100 offset:25872
	ds_read_b128 v[68:71], v100 offset:25888
	ds_read_b64 v[72:73], v101 offset:36864
	s_waitcnt lgkmcnt(12)
	v_pk_add_f32 v[76:77], v[0:1], v[32:33] neg_lo:[0,1] neg_hi:[0,1]
	v_pk_add_f32 v[78:79], v[2:3], v[32:33] neg_lo:[0,1] neg_hi:[0,1]
	v_pk_add_f32 v[96:97], v[96:97], v[98:99]
	v_pk_add_f32 v[80:81], v[4:5], v[32:33] neg_lo:[0,1] neg_hi:[0,1]
	v_pk_add_f32 v[82:83], v[6:7], v[32:33] neg_lo:[0,1] neg_hi:[0,1]
	v_pk_add_f32 v[84:85], v[8:9], v[32:33] neg_lo:[0,1] neg_hi:[0,1]
	ds_write_b64 v102, v[96:97] offset:43008
	v_pk_add_f32 v[86:87], v[10:11], v[32:33] neg_lo:[0,1] neg_hi:[0,1]
	v_pk_add_f32 v[88:89], v[12:13], v[32:33] neg_lo:[0,1] neg_hi:[0,1]
	v_pk_add_f32 v[90:91], v[14:15], v[32:33] neg_lo:[0,1] neg_hi:[0,1]
	v_pk_fma_f32 v[0:1], v[16:17], v[76:77], v[32:33] op_sel:[0,0,0] op_sel_hi:[0,1,1]
	v_pk_fma_f32 v[2:3], v[16:17], v[78:79], v[32:33] op_sel:[1,0,0] op_sel_hi:[1,1,1]
	v_pk_fma_f32 v[4:5], v[18:19], v[80:81], v[32:33] op_sel:[0,0,0] op_sel_hi:[0,1,1]
	v_pk_fma_f32 v[6:7], v[18:19], v[82:83], v[32:33] op_sel:[1,0,0] op_sel_hi:[1,1,1]
	v_pk_fma_f32 v[8:9], v[20:21], v[84:85], v[32:33] op_sel:[0,0,0] op_sel_hi:[0,1,1]
	v_pk_fma_f32 v[10:11], v[20:21], v[86:87], v[32:33] op_sel:[1,0,0] op_sel_hi:[1,1,1]
	v_pk_fma_f32 v[12:13], v[22:23], v[88:89], v[32:33] op_sel:[0,0,0] op_sel_hi:[0,1,1]
	v_pk_fma_f32 v[14:15], v[22:23], v[90:91], v[32:33] op_sel:[1,0,0] op_sel_hi:[1,1,1]
	v_pk_mul_f32 v[92:93], v[24:25], v[0:1] op_sel:[0,0] op_sel_hi:[0,1]
	v_pk_mul_f32 v[94:95], v[24:25], v[2:3] op_sel:[1,0] op_sel_hi:[1,1]
	v_pk_fma_f32 v[92:93], v[26:27], v[4:5], v[92:93] op_sel:[0,0,0] op_sel_hi:[0,1,1]
	v_pk_fma_f32 v[94:95], v[26:27], v[6:7], v[94:95] op_sel:[1,0,0] op_sel_hi:[1,1,1]
	v_pk_fma_f32 v[92:93], v[28:29], v[8:9], v[92:93] op_sel:[0,0,0] op_sel_hi:[0,1,1]
	v_pk_fma_f32 v[94:95], v[28:29], v[10:11], v[94:95] op_sel:[1,0,0] op_sel_hi:[1,1,1]
	v_pk_fma_f32 v[92:93], v[30:31], v[12:13], v[92:93] op_sel:[0,0,0] op_sel_hi:[0,1,1]
	v_pk_fma_f32 v[94:95], v[30:31], v[14:15], v[94:95] op_sel:[1,0,0] op_sel_hi:[1,1,1]
	ds_read_b128 v[16:19], v100 offset:26400
	ds_read_b128 v[20:23], v100 offset:26416
	ds_read_b128 v[24:27], v100 offset:26928
	ds_read_b128 v[28:31], v100 offset:26944
	ds_read_b64 v[32:33], v101 offset:36992
	s_waitcnt lgkmcnt(12)
	v_pk_add_f32 v[76:77], v[0:1], v[52:53] neg_lo:[0,1] neg_hi:[0,1]
	v_pk_add_f32 v[78:79], v[2:3], v[52:53] neg_lo:[0,1] neg_hi:[0,1]
	v_pk_add_f32 v[92:93], v[92:93], v[94:95]
	v_pk_add_f32 v[80:81], v[4:5], v[52:53] neg_lo:[0,1] neg_hi:[0,1]
	v_pk_add_f32 v[82:83], v[6:7], v[52:53] neg_lo:[0,1] neg_hi:[0,1]
	v_pk_add_f32 v[84:85], v[8:9], v[52:53] neg_lo:[0,1] neg_hi:[0,1]
	ds_write_b64 v102, v[92:93] offset:45056
	v_pk_add_f32 v[86:87], v[10:11], v[52:53] neg_lo:[0,1] neg_hi:[0,1]
	v_pk_add_f32 v[88:89], v[12:13], v[52:53] neg_lo:[0,1] neg_hi:[0,1]
	v_pk_add_f32 v[90:91], v[14:15], v[52:53] neg_lo:[0,1] neg_hi:[0,1]
	v_pk_fma_f32 v[0:1], v[36:37], v[76:77], v[52:53] op_sel:[0,0,0] op_sel_hi:[0,1,1]
	v_pk_fma_f32 v[2:3], v[36:37], v[78:79], v[52:53] op_sel:[1,0,0] op_sel_hi:[1,1,1]
	v_pk_fma_f32 v[4:5], v[38:39], v[80:81], v[52:53] op_sel:[0,0,0] op_sel_hi:[0,1,1]
	v_pk_fma_f32 v[6:7], v[38:39], v[82:83], v[52:53] op_sel:[1,0,0] op_sel_hi:[1,1,1]
	v_pk_fma_f32 v[8:9], v[40:41], v[84:85], v[52:53] op_sel:[0,0,0] op_sel_hi:[0,1,1]
	v_pk_fma_f32 v[10:11], v[40:41], v[86:87], v[52:53] op_sel:[1,0,0] op_sel_hi:[1,1,1]
	v_pk_fma_f32 v[12:13], v[42:43], v[88:89], v[52:53] op_sel:[0,0,0] op_sel_hi:[0,1,1]
	v_pk_fma_f32 v[14:15], v[42:43], v[90:91], v[52:53] op_sel:[1,0,0] op_sel_hi:[1,1,1]
	v_pk_mul_f32 v[96:97], v[44:45], v[0:1] op_sel:[0,0] op_sel_hi:[0,1]
	v_pk_mul_f32 v[98:99], v[44:45], v[2:3] op_sel:[1,0] op_sel_hi:[1,1]
	v_pk_fma_f32 v[96:97], v[46:47], v[4:5], v[96:97] op_sel:[0,0,0] op_sel_hi:[0,1,1]
	v_pk_fma_f32 v[98:99], v[46:47], v[6:7], v[98:99] op_sel:[1,0,0] op_sel_hi:[1,1,1]
	v_pk_fma_f32 v[96:97], v[48:49], v[8:9], v[96:97] op_sel:[0,0,0] op_sel_hi:[0,1,1]
	v_pk_fma_f32 v[98:99], v[48:49], v[10:11], v[98:99] op_sel:[1,0,0] op_sel_hi:[1,1,1]
	v_pk_fma_f32 v[96:97], v[50:51], v[12:13], v[96:97] op_sel:[0,0,0] op_sel_hi:[0,1,1]
	v_pk_fma_f32 v[98:99], v[50:51], v[14:15], v[98:99] op_sel:[1,0,0] op_sel_hi:[1,1,1]
	ds_read_b128 v[36:39], v100 offset:27456
	ds_read_b128 v[40:43], v100 offset:27472
	ds_read_b128 v[44:47], v100 offset:27984
	ds_read_b128 v[48:51], v100 offset:28000
	ds_read_b64 v[52:53], v101 offset:37120
	s_waitcnt lgkmcnt(12)
	v_pk_add_f32 v[76:77], v[0:1], v[72:73] neg_lo:[0,1] neg_hi:[0,1]
	v_pk_add_f32 v[78:79], v[2:3], v[72:73] neg_lo:[0,1] neg_hi:[0,1]
	v_pk_add_f32 v[96:97], v[96:97], v[98:99]
	v_pk_add_f32 v[80:81], v[4:5], v[72:73] neg_lo:[0,1] neg_hi:[0,1]
	v_pk_add_f32 v[82:83], v[6:7], v[72:73] neg_lo:[0,1] neg_hi:[0,1]
	v_pk_add_f32 v[84:85], v[8:9], v[72:73] neg_lo:[0,1] neg_hi:[0,1]
	ds_write_b64 v102, v[96:97] offset:47104
	v_pk_add_f32 v[86:87], v[10:11], v[72:73] neg_lo:[0,1] neg_hi:[0,1]
	v_pk_add_f32 v[88:89], v[12:13], v[72:73] neg_lo:[0,1] neg_hi:[0,1]
	v_pk_add_f32 v[90:91], v[14:15], v[72:73] neg_lo:[0,1] neg_hi:[0,1]
	v_pk_fma_f32 v[0:1], v[56:57], v[76:77], v[72:73] op_sel:[0,0,0] op_sel_hi:[0,1,1]
	v_pk_fma_f32 v[2:3], v[56:57], v[78:79], v[72:73] op_sel:[1,0,0] op_sel_hi:[1,1,1]
	v_pk_fma_f32 v[4:5], v[58:59], v[80:81], v[72:73] op_sel:[0,0,0] op_sel_hi:[0,1,1]
	v_pk_fma_f32 v[6:7], v[58:59], v[82:83], v[72:73] op_sel:[1,0,0] op_sel_hi:[1,1,1]
	v_pk_fma_f32 v[8:9], v[60:61], v[84:85], v[72:73] op_sel:[0,0,0] op_sel_hi:[0,1,1]
	v_pk_fma_f32 v[10:11], v[60:61], v[86:87], v[72:73] op_sel:[1,0,0] op_sel_hi:[1,1,1]
	v_pk_fma_f32 v[12:13], v[62:63], v[88:89], v[72:73] op_sel:[0,0,0] op_sel_hi:[0,1,1]
	v_pk_fma_f32 v[14:15], v[62:63], v[90:91], v[72:73] op_sel:[1,0,0] op_sel_hi:[1,1,1]
	v_pk_mul_f32 v[92:93], v[64:65], v[0:1] op_sel:[0,0] op_sel_hi:[0,1]
	v_pk_mul_f32 v[94:95], v[64:65], v[2:3] op_sel:[1,0] op_sel_hi:[1,1]
	v_pk_fma_f32 v[92:93], v[66:67], v[4:5], v[92:93] op_sel:[0,0,0] op_sel_hi:[0,1,1]
	v_pk_fma_f32 v[94:95], v[66:67], v[6:7], v[94:95] op_sel:[1,0,0] op_sel_hi:[1,1,1]
	v_pk_fma_f32 v[92:93], v[68:69], v[8:9], v[92:93] op_sel:[0,0,0] op_sel_hi:[0,1,1]
	v_pk_fma_f32 v[94:95], v[68:69], v[10:11], v[94:95] op_sel:[1,0,0] op_sel_hi:[1,1,1]
	v_pk_fma_f32 v[92:93], v[70:71], v[12:13], v[92:93] op_sel:[0,0,0] op_sel_hi:[0,1,1]
	v_pk_fma_f32 v[94:95], v[70:71], v[14:15], v[94:95] op_sel:[1,0,0] op_sel_hi:[1,1,1]
	ds_read_b128 v[56:59], v100 offset:28512
	ds_read_b128 v[60:63], v100 offset:28528
	ds_read_b128 v[64:67], v100 offset:29040
	ds_read_b128 v[68:71], v100 offset:29056
	ds_read_b64 v[72:73], v101 offset:37248
	s_waitcnt lgkmcnt(12)
	v_pk_add_f32 v[76:77], v[0:1], v[32:33] neg_lo:[0,1] neg_hi:[0,1]
	v_pk_add_f32 v[78:79], v[2:3], v[32:33] neg_lo:[0,1] neg_hi:[0,1]
	v_pk_add_f32 v[92:93], v[92:93], v[94:95]
	v_pk_add_f32 v[80:81], v[4:5], v[32:33] neg_lo:[0,1] neg_hi:[0,1]
	v_pk_add_f32 v[82:83], v[6:7], v[32:33] neg_lo:[0,1] neg_hi:[0,1]
	v_pk_add_f32 v[84:85], v[8:9], v[32:33] neg_lo:[0,1] neg_hi:[0,1]
	ds_write_b64 v102, v[92:93] offset:49152
	v_pk_add_f32 v[86:87], v[10:11], v[32:33] neg_lo:[0,1] neg_hi:[0,1]
	v_pk_add_f32 v[88:89], v[12:13], v[32:33] neg_lo:[0,1] neg_hi:[0,1]
	v_pk_add_f32 v[90:91], v[14:15], v[32:33] neg_lo:[0,1] neg_hi:[0,1]
	v_pk_fma_f32 v[0:1], v[16:17], v[76:77], v[32:33] op_sel:[0,0,0] op_sel_hi:[0,1,1]
	v_pk_fma_f32 v[2:3], v[16:17], v[78:79], v[32:33] op_sel:[1,0,0] op_sel_hi:[1,1,1]
	v_pk_fma_f32 v[4:5], v[18:19], v[80:81], v[32:33] op_sel:[0,0,0] op_sel_hi:[0,1,1]
	v_pk_fma_f32 v[6:7], v[18:19], v[82:83], v[32:33] op_sel:[1,0,0] op_sel_hi:[1,1,1]
	v_pk_fma_f32 v[8:9], v[20:21], v[84:85], v[32:33] op_sel:[0,0,0] op_sel_hi:[0,1,1]
	v_pk_fma_f32 v[10:11], v[20:21], v[86:87], v[32:33] op_sel:[1,0,0] op_sel_hi:[1,1,1]
	v_pk_fma_f32 v[12:13], v[22:23], v[88:89], v[32:33] op_sel:[0,0,0] op_sel_hi:[0,1,1]
	v_pk_fma_f32 v[14:15], v[22:23], v[90:91], v[32:33] op_sel:[1,0,0] op_sel_hi:[1,1,1]
	v_pk_mul_f32 v[96:97], v[24:25], v[0:1] op_sel:[0,0] op_sel_hi:[0,1]
	v_pk_mul_f32 v[98:99], v[24:25], v[2:3] op_sel:[1,0] op_sel_hi:[1,1]
	v_pk_fma_f32 v[96:97], v[26:27], v[4:5], v[96:97] op_sel:[0,0,0] op_sel_hi:[0,1,1]
	v_pk_fma_f32 v[98:99], v[26:27], v[6:7], v[98:99] op_sel:[1,0,0] op_sel_hi:[1,1,1]
	v_pk_fma_f32 v[96:97], v[28:29], v[8:9], v[96:97] op_sel:[0,0,0] op_sel_hi:[0,1,1]
	v_pk_fma_f32 v[98:99], v[28:29], v[10:11], v[98:99] op_sel:[1,0,0] op_sel_hi:[1,1,1]
	v_pk_fma_f32 v[96:97], v[30:31], v[12:13], v[96:97] op_sel:[0,0,0] op_sel_hi:[0,1,1]
	v_pk_fma_f32 v[98:99], v[30:31], v[14:15], v[98:99] op_sel:[1,0,0] op_sel_hi:[1,1,1]
	ds_read_b128 v[16:19], v100 offset:29568
	ds_read_b128 v[20:23], v100 offset:29584
	ds_read_b128 v[24:27], v100 offset:30096
	ds_read_b128 v[28:31], v100 offset:30112
	ds_read_b64 v[32:33], v101 offset:37376
	s_waitcnt lgkmcnt(12)
	v_pk_add_f32 v[76:77], v[0:1], v[52:53] neg_lo:[0,1] neg_hi:[0,1]
	v_pk_add_f32 v[78:79], v[2:3], v[52:53] neg_lo:[0,1] neg_hi:[0,1]
	v_pk_add_f32 v[96:97], v[96:97], v[98:99]
	v_pk_add_f32 v[80:81], v[4:5], v[52:53] neg_lo:[0,1] neg_hi:[0,1]
	v_pk_add_f32 v[82:83], v[6:7], v[52:53] neg_lo:[0,1] neg_hi:[0,1]
	v_pk_add_f32 v[84:85], v[8:9], v[52:53] neg_lo:[0,1] neg_hi:[0,1]
	ds_write_b64 v102, v[96:97] offset:51200
	v_pk_add_f32 v[86:87], v[10:11], v[52:53] neg_lo:[0,1] neg_hi:[0,1]
	v_pk_add_f32 v[88:89], v[12:13], v[52:53] neg_lo:[0,1] neg_hi:[0,1]
	v_pk_add_f32 v[90:91], v[14:15], v[52:53] neg_lo:[0,1] neg_hi:[0,1]
	v_pk_fma_f32 v[0:1], v[36:37], v[76:77], v[52:53] op_sel:[0,0,0] op_sel_hi:[0,1,1]
	v_pk_fma_f32 v[2:3], v[36:37], v[78:79], v[52:53] op_sel:[1,0,0] op_sel_hi:[1,1,1]
	v_pk_fma_f32 v[4:5], v[38:39], v[80:81], v[52:53] op_sel:[0,0,0] op_sel_hi:[0,1,1]
	v_pk_fma_f32 v[6:7], v[38:39], v[82:83], v[52:53] op_sel:[1,0,0] op_sel_hi:[1,1,1]
	v_pk_fma_f32 v[8:9], v[40:41], v[84:85], v[52:53] op_sel:[0,0,0] op_sel_hi:[0,1,1]
	v_pk_fma_f32 v[10:11], v[40:41], v[86:87], v[52:53] op_sel:[1,0,0] op_sel_hi:[1,1,1]
	v_pk_fma_f32 v[12:13], v[42:43], v[88:89], v[52:53] op_sel:[0,0,0] op_sel_hi:[0,1,1]
	v_pk_fma_f32 v[14:15], v[42:43], v[90:91], v[52:53] op_sel:[1,0,0] op_sel_hi:[1,1,1]
	v_pk_mul_f32 v[92:93], v[44:45], v[0:1] op_sel:[0,0] op_sel_hi:[0,1]
	v_pk_mul_f32 v[94:95], v[44:45], v[2:3] op_sel:[1,0] op_sel_hi:[1,1]
	v_pk_fma_f32 v[92:93], v[46:47], v[4:5], v[92:93] op_sel:[0,0,0] op_sel_hi:[0,1,1]
	v_pk_fma_f32 v[94:95], v[46:47], v[6:7], v[94:95] op_sel:[1,0,0] op_sel_hi:[1,1,1]
	v_pk_fma_f32 v[92:93], v[48:49], v[8:9], v[92:93] op_sel:[0,0,0] op_sel_hi:[0,1,1]
	v_pk_fma_f32 v[94:95], v[48:49], v[10:11], v[94:95] op_sel:[1,0,0] op_sel_hi:[1,1,1]
	v_pk_fma_f32 v[92:93], v[50:51], v[12:13], v[92:93] op_sel:[0,0,0] op_sel_hi:[0,1,1]
	v_pk_fma_f32 v[94:95], v[50:51], v[14:15], v[94:95] op_sel:[1,0,0] op_sel_hi:[1,1,1]
	ds_read_b128 v[36:39], v100 offset:30624
	ds_read_b128 v[40:43], v100 offset:30640
	ds_read_b128 v[44:47], v100 offset:31152
	ds_read_b128 v[48:51], v100 offset:31168
	ds_read_b64 v[52:53], v101 offset:37504
	s_waitcnt lgkmcnt(12)
	v_pk_add_f32 v[76:77], v[0:1], v[72:73] neg_lo:[0,1] neg_hi:[0,1]
	v_pk_add_f32 v[78:79], v[2:3], v[72:73] neg_lo:[0,1] neg_hi:[0,1]
	v_pk_add_f32 v[92:93], v[92:93], v[94:95]
	v_pk_add_f32 v[80:81], v[4:5], v[72:73] neg_lo:[0,1] neg_hi:[0,1]
	v_pk_add_f32 v[82:83], v[6:7], v[72:73] neg_lo:[0,1] neg_hi:[0,1]
	v_pk_add_f32 v[84:85], v[8:9], v[72:73] neg_lo:[0,1] neg_hi:[0,1]
	ds_write_b64 v102, v[92:93] offset:53248
	v_pk_add_f32 v[86:87], v[10:11], v[72:73] neg_lo:[0,1] neg_hi:[0,1]
	v_pk_add_f32 v[88:89], v[12:13], v[72:73] neg_lo:[0,1] neg_hi:[0,1]
	v_pk_add_f32 v[90:91], v[14:15], v[72:73] neg_lo:[0,1] neg_hi:[0,1]
	v_pk_fma_f32 v[0:1], v[56:57], v[76:77], v[72:73] op_sel:[0,0,0] op_sel_hi:[0,1,1]
	v_pk_fma_f32 v[2:3], v[56:57], v[78:79], v[72:73] op_sel:[1,0,0] op_sel_hi:[1,1,1]
	v_pk_fma_f32 v[4:5], v[58:59], v[80:81], v[72:73] op_sel:[0,0,0] op_sel_hi:[0,1,1]
	v_pk_fma_f32 v[6:7], v[58:59], v[82:83], v[72:73] op_sel:[1,0,0] op_sel_hi:[1,1,1]
	v_pk_fma_f32 v[8:9], v[60:61], v[84:85], v[72:73] op_sel:[0,0,0] op_sel_hi:[0,1,1]
	v_pk_fma_f32 v[10:11], v[60:61], v[86:87], v[72:73] op_sel:[1,0,0] op_sel_hi:[1,1,1]
	v_pk_fma_f32 v[12:13], v[62:63], v[88:89], v[72:73] op_sel:[0,0,0] op_sel_hi:[0,1,1]
	v_pk_fma_f32 v[14:15], v[62:63], v[90:91], v[72:73] op_sel:[1,0,0] op_sel_hi:[1,1,1]
	v_pk_mul_f32 v[96:97], v[64:65], v[0:1] op_sel:[0,0] op_sel_hi:[0,1]
	v_pk_mul_f32 v[98:99], v[64:65], v[2:3] op_sel:[1,0] op_sel_hi:[1,1]
	v_pk_fma_f32 v[96:97], v[66:67], v[4:5], v[96:97] op_sel:[0,0,0] op_sel_hi:[0,1,1]
	v_pk_fma_f32 v[98:99], v[66:67], v[6:7], v[98:99] op_sel:[1,0,0] op_sel_hi:[1,1,1]
	v_pk_fma_f32 v[96:97], v[68:69], v[8:9], v[96:97] op_sel:[0,0,0] op_sel_hi:[0,1,1]
	v_pk_fma_f32 v[98:99], v[68:69], v[10:11], v[98:99] op_sel:[1,0,0] op_sel_hi:[1,1,1]
	v_pk_fma_f32 v[96:97], v[70:71], v[12:13], v[96:97] op_sel:[0,0,0] op_sel_hi:[0,1,1]
	v_pk_fma_f32 v[98:99], v[70:71], v[14:15], v[98:99] op_sel:[1,0,0] op_sel_hi:[1,1,1]
	ds_read_b128 v[56:59], v100 offset:31680
	ds_read_b128 v[60:63], v100 offset:31696
	ds_read_b128 v[64:67], v100 offset:32208
	ds_read_b128 v[68:71], v100 offset:32224
	ds_read_b64 v[72:73], v101 offset:37632
	s_waitcnt lgkmcnt(12)
	v_pk_add_f32 v[76:77], v[0:1], v[32:33] neg_lo:[0,1] neg_hi:[0,1]
	v_pk_add_f32 v[78:79], v[2:3], v[32:33] neg_lo:[0,1] neg_hi:[0,1]
	v_pk_add_f32 v[96:97], v[96:97], v[98:99]
	v_pk_add_f32 v[80:81], v[4:5], v[32:33] neg_lo:[0,1] neg_hi:[0,1]
	v_pk_add_f32 v[82:83], v[6:7], v[32:33] neg_lo:[0,1] neg_hi:[0,1]
	v_pk_add_f32 v[84:85], v[8:9], v[32:33] neg_lo:[0,1] neg_hi:[0,1]
	ds_write_b64 v102, v[96:97] offset:55296
	v_pk_add_f32 v[86:87], v[10:11], v[32:33] neg_lo:[0,1] neg_hi:[0,1]
	v_pk_add_f32 v[88:89], v[12:13], v[32:33] neg_lo:[0,1] neg_hi:[0,1]
	v_pk_add_f32 v[90:91], v[14:15], v[32:33] neg_lo:[0,1] neg_hi:[0,1]
	v_pk_fma_f32 v[0:1], v[16:17], v[76:77], v[32:33] op_sel:[0,0,0] op_sel_hi:[0,1,1]
	v_pk_fma_f32 v[2:3], v[16:17], v[78:79], v[32:33] op_sel:[1,0,0] op_sel_hi:[1,1,1]
	v_pk_fma_f32 v[4:5], v[18:19], v[80:81], v[32:33] op_sel:[0,0,0] op_sel_hi:[0,1,1]
	v_pk_fma_f32 v[6:7], v[18:19], v[82:83], v[32:33] op_sel:[1,0,0] op_sel_hi:[1,1,1]
	v_pk_fma_f32 v[8:9], v[20:21], v[84:85], v[32:33] op_sel:[0,0,0] op_sel_hi:[0,1,1]
	v_pk_fma_f32 v[10:11], v[20:21], v[86:87], v[32:33] op_sel:[1,0,0] op_sel_hi:[1,1,1]
	v_pk_fma_f32 v[12:13], v[22:23], v[88:89], v[32:33] op_sel:[0,0,0] op_sel_hi:[0,1,1]
	v_pk_fma_f32 v[14:15], v[22:23], v[90:91], v[32:33] op_sel:[1,0,0] op_sel_hi:[1,1,1]
	v_pk_mul_f32 v[92:93], v[24:25], v[0:1] op_sel:[0,0] op_sel_hi:[0,1]
	v_pk_mul_f32 v[94:95], v[24:25], v[2:3] op_sel:[1,0] op_sel_hi:[1,1]
	v_pk_fma_f32 v[92:93], v[26:27], v[4:5], v[92:93] op_sel:[0,0,0] op_sel_hi:[0,1,1]
	v_pk_fma_f32 v[94:95], v[26:27], v[6:7], v[94:95] op_sel:[1,0,0] op_sel_hi:[1,1,1]
	v_pk_fma_f32 v[92:93], v[28:29], v[8:9], v[92:93] op_sel:[0,0,0] op_sel_hi:[0,1,1]
	v_pk_fma_f32 v[94:95], v[28:29], v[10:11], v[94:95] op_sel:[1,0,0] op_sel_hi:[1,1,1]
	v_pk_fma_f32 v[92:93], v[30:31], v[12:13], v[92:93] op_sel:[0,0,0] op_sel_hi:[0,1,1]
	v_pk_fma_f32 v[94:95], v[30:31], v[14:15], v[94:95] op_sel:[1,0,0] op_sel_hi:[1,1,1]
	ds_read_b128 v[16:19], v100 offset:32736
	ds_read_b128 v[20:23], v100 offset:32752
	ds_read_b128 v[24:27], v100 offset:33264
	ds_read_b128 v[28:31], v100 offset:33280
	ds_read_b64 v[32:33], v101 offset:37760
	s_waitcnt lgkmcnt(12)
	v_pk_add_f32 v[76:77], v[0:1], v[52:53] neg_lo:[0,1] neg_hi:[0,1]
	v_pk_add_f32 v[78:79], v[2:3], v[52:53] neg_lo:[0,1] neg_hi:[0,1]
	v_pk_add_f32 v[92:93], v[92:93], v[94:95]
	v_pk_add_f32 v[80:81], v[4:5], v[52:53] neg_lo:[0,1] neg_hi:[0,1]
	v_pk_add_f32 v[82:83], v[6:7], v[52:53] neg_lo:[0,1] neg_hi:[0,1]
	v_pk_add_f32 v[84:85], v[8:9], v[52:53] neg_lo:[0,1] neg_hi:[0,1]
	ds_write_b64 v102, v[92:93] offset:57344
	v_pk_add_f32 v[86:87], v[10:11], v[52:53] neg_lo:[0,1] neg_hi:[0,1]
	v_pk_add_f32 v[88:89], v[12:13], v[52:53] neg_lo:[0,1] neg_hi:[0,1]
	v_pk_add_f32 v[90:91], v[14:15], v[52:53] neg_lo:[0,1] neg_hi:[0,1]
	v_pk_fma_f32 v[0:1], v[36:37], v[76:77], v[52:53] op_sel:[0,0,0] op_sel_hi:[0,1,1]
	v_pk_fma_f32 v[2:3], v[36:37], v[78:79], v[52:53] op_sel:[1,0,0] op_sel_hi:[1,1,1]
	v_pk_fma_f32 v[4:5], v[38:39], v[80:81], v[52:53] op_sel:[0,0,0] op_sel_hi:[0,1,1]
	v_pk_fma_f32 v[6:7], v[38:39], v[82:83], v[52:53] op_sel:[1,0,0] op_sel_hi:[1,1,1]
	v_pk_fma_f32 v[8:9], v[40:41], v[84:85], v[52:53] op_sel:[0,0,0] op_sel_hi:[0,1,1]
	v_pk_fma_f32 v[10:11], v[40:41], v[86:87], v[52:53] op_sel:[1,0,0] op_sel_hi:[1,1,1]
	v_pk_fma_f32 v[12:13], v[42:43], v[88:89], v[52:53] op_sel:[0,0,0] op_sel_hi:[0,1,1]
	v_pk_fma_f32 v[14:15], v[42:43], v[90:91], v[52:53] op_sel:[1,0,0] op_sel_hi:[1,1,1]
	v_pk_mul_f32 v[96:97], v[44:45], v[0:1] op_sel:[0,0] op_sel_hi:[0,1]
	v_pk_mul_f32 v[98:99], v[44:45], v[2:3] op_sel:[1,0] op_sel_hi:[1,1]
	v_pk_fma_f32 v[96:97], v[46:47], v[4:5], v[96:97] op_sel:[0,0,0] op_sel_hi:[0,1,1]
	v_pk_fma_f32 v[98:99], v[46:47], v[6:7], v[98:99] op_sel:[1,0,0] op_sel_hi:[1,1,1]
	v_pk_fma_f32 v[96:97], v[48:49], v[8:9], v[96:97] op_sel:[0,0,0] op_sel_hi:[0,1,1]
	v_pk_fma_f32 v[98:99], v[48:49], v[10:11], v[98:99] op_sel:[1,0,0] op_sel_hi:[1,1,1]
	v_pk_fma_f32 v[96:97], v[50:51], v[12:13], v[96:97] op_sel:[0,0,0] op_sel_hi:[0,1,1]
	v_pk_fma_f32 v[98:99], v[50:51], v[14:15], v[98:99] op_sel:[1,0,0] op_sel_hi:[1,1,1]
	s_waitcnt lgkmcnt(7)
	v_pk_add_f32 v[76:77], v[0:1], v[72:73] neg_lo:[0,1] neg_hi:[0,1]
	v_pk_add_f32 v[78:79], v[2:3], v[72:73] neg_lo:[0,1] neg_hi:[0,1]
	v_pk_add_f32 v[96:97], v[96:97], v[98:99]
	v_pk_add_f32 v[80:81], v[4:5], v[72:73] neg_lo:[0,1] neg_hi:[0,1]
	v_pk_add_f32 v[82:83], v[6:7], v[72:73] neg_lo:[0,1] neg_hi:[0,1]
	v_pk_add_f32 v[84:85], v[8:9], v[72:73] neg_lo:[0,1] neg_hi:[0,1]
	ds_write_b64 v102, v[96:97] offset:59392
	v_pk_add_f32 v[86:87], v[10:11], v[72:73] neg_lo:[0,1] neg_hi:[0,1]
	v_pk_add_f32 v[88:89], v[12:13], v[72:73] neg_lo:[0,1] neg_hi:[0,1]
	v_pk_add_f32 v[90:91], v[14:15], v[72:73] neg_lo:[0,1] neg_hi:[0,1]
	v_pk_fma_f32 v[0:1], v[56:57], v[76:77], v[72:73] op_sel:[0,0,0] op_sel_hi:[0,1,1]
	v_pk_fma_f32 v[2:3], v[56:57], v[78:79], v[72:73] op_sel:[1,0,0] op_sel_hi:[1,1,1]
	v_pk_fma_f32 v[4:5], v[58:59], v[80:81], v[72:73] op_sel:[0,0,0] op_sel_hi:[0,1,1]
	v_pk_fma_f32 v[6:7], v[58:59], v[82:83], v[72:73] op_sel:[1,0,0] op_sel_hi:[1,1,1]
	v_pk_fma_f32 v[8:9], v[60:61], v[84:85], v[72:73] op_sel:[0,0,0] op_sel_hi:[0,1,1]
	v_pk_fma_f32 v[10:11], v[60:61], v[86:87], v[72:73] op_sel:[1,0,0] op_sel_hi:[1,1,1]
	v_pk_fma_f32 v[12:13], v[62:63], v[88:89], v[72:73] op_sel:[0,0,0] op_sel_hi:[0,1,1]
	v_pk_fma_f32 v[14:15], v[62:63], v[90:91], v[72:73] op_sel:[1,0,0] op_sel_hi:[1,1,1]
	v_pk_mul_f32 v[92:93], v[64:65], v[0:1] op_sel:[0,0] op_sel_hi:[0,1]
	v_pk_mul_f32 v[94:95], v[64:65], v[2:3] op_sel:[1,0] op_sel_hi:[1,1]
	v_pk_fma_f32 v[92:93], v[66:67], v[4:5], v[92:93] op_sel:[0,0,0] op_sel_hi:[0,1,1]
	v_pk_fma_f32 v[94:95], v[66:67], v[6:7], v[94:95] op_sel:[1,0,0] op_sel_hi:[1,1,1]
	v_pk_fma_f32 v[92:93], v[68:69], v[8:9], v[92:93] op_sel:[0,0,0] op_sel_hi:[0,1,1]
	v_pk_fma_f32 v[94:95], v[68:69], v[10:11], v[94:95] op_sel:[1,0,0] op_sel_hi:[1,1,1]
	v_pk_fma_f32 v[92:93], v[70:71], v[12:13], v[92:93] op_sel:[0,0,0] op_sel_hi:[0,1,1]
	v_pk_fma_f32 v[94:95], v[70:71], v[14:15], v[94:95] op_sel:[1,0,0] op_sel_hi:[1,1,1]
	s_waitcnt lgkmcnt(2)
	v_pk_add_f32 v[76:77], v[0:1], v[32:33] neg_lo:[0,1] neg_hi:[0,1]
	v_pk_add_f32 v[78:79], v[2:3], v[32:33] neg_lo:[0,1] neg_hi:[0,1]
	v_pk_add_f32 v[92:93], v[92:93], v[94:95]
	v_pk_add_f32 v[80:81], v[4:5], v[32:33] neg_lo:[0,1] neg_hi:[0,1]
	v_pk_add_f32 v[82:83], v[6:7], v[32:33] neg_lo:[0,1] neg_hi:[0,1]
	v_pk_add_f32 v[84:85], v[8:9], v[32:33] neg_lo:[0,1] neg_hi:[0,1]
	ds_write_b64 v102, v[92:93] offset:61440
	v_pk_add_f32 v[86:87], v[10:11], v[32:33] neg_lo:[0,1] neg_hi:[0,1]
	v_pk_add_f32 v[88:89], v[12:13], v[32:33] neg_lo:[0,1] neg_hi:[0,1]
	v_pk_add_f32 v[90:91], v[14:15], v[32:33] neg_lo:[0,1] neg_hi:[0,1]
	v_pk_fma_f32 v[0:1], v[16:17], v[76:77], v[32:33] op_sel:[0,0,0] op_sel_hi:[0,1,1]
	v_pk_fma_f32 v[2:3], v[16:17], v[78:79], v[32:33] op_sel:[1,0,0] op_sel_hi:[1,1,1]
	v_pk_fma_f32 v[4:5], v[18:19], v[80:81], v[32:33] op_sel:[0,0,0] op_sel_hi:[0,1,1]
	v_pk_fma_f32 v[6:7], v[18:19], v[82:83], v[32:33] op_sel:[1,0,0] op_sel_hi:[1,1,1]
	v_pk_fma_f32 v[8:9], v[20:21], v[84:85], v[32:33] op_sel:[0,0,0] op_sel_hi:[0,1,1]
	v_pk_fma_f32 v[10:11], v[20:21], v[86:87], v[32:33] op_sel:[1,0,0] op_sel_hi:[1,1,1]
	v_pk_fma_f32 v[12:13], v[22:23], v[88:89], v[32:33] op_sel:[0,0,0] op_sel_hi:[0,1,1]
	v_pk_fma_f32 v[14:15], v[22:23], v[90:91], v[32:33] op_sel:[1,0,0] op_sel_hi:[1,1,1]
	v_pk_mul_f32 v[96:97], v[24:25], v[0:1] op_sel:[0,0] op_sel_hi:[0,1]
	v_pk_mul_f32 v[98:99], v[24:25], v[2:3] op_sel:[1,0] op_sel_hi:[1,1]
	v_pk_fma_f32 v[96:97], v[26:27], v[4:5], v[96:97] op_sel:[0,0,0] op_sel_hi:[0,1,1]
	v_pk_fma_f32 v[98:99], v[26:27], v[6:7], v[98:99] op_sel:[1,0,0] op_sel_hi:[1,1,1]
	v_pk_fma_f32 v[96:97], v[28:29], v[8:9], v[96:97] op_sel:[0,0,0] op_sel_hi:[0,1,1]
	v_pk_fma_f32 v[98:99], v[28:29], v[10:11], v[98:99] op_sel:[1,0,0] op_sel_hi:[1,1,1]
	v_pk_fma_f32 v[96:97], v[30:31], v[12:13], v[96:97] op_sel:[0,0,0] op_sel_hi:[0,1,1]
	v_pk_fma_f32 v[98:99], v[30:31], v[14:15], v[98:99] op_sel:[1,0,0] op_sel_hi:[1,1,1]
	s_nop 0
	v_pk_add_f32 v[96:97], v[96:97], v[98:99]
	s_nop 0
	ds_write_b64 v102, v[96:97] offset:63488
	s_waitcnt lgkmcnt(0)
	s_barrier
	s_add_i32 s16, s16, 2
	s_cmp_lt_u32 s16, 0x100
	s_cbranch_scc1 .Lhc_loop
	ds_read_b128 v[56:59], v103 offset:32768
	v_xor_b32_e32 v89, 16, v103
	ds_read_b128 v[60:63], v89 offset:32768
	v_xor_b32_e32 v89, 32, v103
	ds_read_b128 v[64:67], v89 offset:32768
	v_xor_b32_e32 v89, 48, v103
	ds_read_b128 v[68:71], v89 offset:32768
	v_xor_b32_e32 v89, 64, v103
	ds_read_b128 v[72:75], v89 offset:32768
	v_xor_b32_e32 v89, 80, v103
	ds_read_b128 v[76:79], v89 offset:32768
	v_xor_b32_e32 v89, 96, v103
	ds_read_b128 v[80:83], v89 offset:32768
	v_xor_b32_e32 v89, 112, v103
	ds_read_b128 v[84:87], v89 offset:32768
	s_waitcnt lgkmcnt(0)
	v_pk_add_f32 v[56:57], v[56:57], v[58:59]
	v_pk_add_f32 v[60:61], v[60:61], v[62:63]
	v_pk_add_f32 v[64:65], v[64:65], v[66:67]
	v_pk_add_f32 v[68:69], v[68:69], v[70:71]
	v_pk_add_f32 v[72:73], v[72:73], v[74:75]
	v_pk_add_f32 v[76:77], v[76:77], v[78:79]
	v_pk_add_f32 v[80:81], v[80:81], v[82:83]
	v_pk_add_f32 v[84:85], v[84:85], v[86:87]
	v_pk_add_f32 v[56:57], v[56:57], v[60:61]
	v_pk_add_f32 v[64:65], v[64:65], v[68:69]
	v_pk_add_f32 v[72:73], v[72:73], v[76:77]
	v_pk_add_f32 v[80:81], v[80:81], v[84:85]
	v_pk_add_f32 v[56:57], v[56:57], v[64:65]
	v_pk_add_f32 v[72:73], v[72:73], v[80:81]
	s_nop 0
	v_pk_add_f32 v[56:57], v[56:57], v[72:73]
	s_nop 0
	v_cvt_pk_bf16_f32 v88, v56, v57
	global_store_dword v[104:105], v88, off
	v_lshl_add_u64 v[104:105], v[104:105], 0, s[14:15]
	s_waitcnt vmcnt(0) lgkmcnt(0)
	s_setprio 0
